# GEMM K-loops: LDS-DMA loads rebalanced 6/2 -> 4/4 between the first 6-load segment and the following segment (vmcnt(8)->(6) on the shortened one), on top of v044
# speedup vs baseline: 1.0035x; 1.0035x over previous
; #define PG8_STAGE(bufoff, gbase, voff) do { _Pragma("unroll") for (int _i = 0; _i < 2; ++_i) \
;         __builtin_amdgcn_global_load_lds((const unsigned*)((const char*)(gbase) + (voff)[_i]), (PG8_LAS unsigned*)(lds + (bufoff) + ldsw + _i * 8192), 16, 0, 0); } while (0)
; #define PG8_LDA(dst, b, h) do { _Pragma("unroll") for (int m = 0; m < 4; ++m) _Pragma("unroll") for (int k = 0; k < 2; ++k) dst[m][k] = *(const PG8_LAS bf16x8*)(lds + PG8_SA(b, h) + aoff + m * 2048 + k * 1024); } while (0)
; #define PG8_LDB(dst, b, h) do { _Pragma("unroll") for (int n = 0; n < 2; ++n) _Pragma("unroll") for (int k = 0; k < 2; ++k) dst[n][k] = *(const PG8_LAS bf16x8*)(lds + PG8_SB(b, h) + boff + n * 2048 + k * 1024); } while (0)
; #define PG8_MMA(ai, bj, At, Bt) do { __builtin_amdgcn_s_setprio(1); _Pragma("unroll") for (int m = 0; m < 4; ++m) _Pragma("unroll") for (int n = 0; n < 2; ++n) _Pragma("unroll") for (int k = 0; k < 2; ++k) \
;         acc[ai][bj][m][n] = __builtin_amdgcn_mfma_f32_16x16x32_bf16(Bt[n][k], At[m][k], acc[ai][bj][m][n], 0, 0, 0); __builtin_amdgcn_s_setprio(0); } while (0)
; #define PG8_WAIT_V(n) asm volatile("s_waitcnt vmcnt(" #n ")" ::: "memory")
; #define PG8_WAIT_L(n) asm volatile("s_waitcnt lgkmcnt(" #n ")" ::: "memory")
; template <class Epi, class Sched, bool ALIGN_EPI = false, bool SP2 = false>
; __device__ __forceinline__ void gemm_phase(PG8_LAS unsigned char* lds, const Gemm g, const Sched& S, const Epi& E, int tid_in) {
;     ...
;             const bool last = (t == nt - 2);
;             const char* a1 = cA + (size_t)(t + 1) * kstep;
;             const char* a2 = last ? nA : cA + (size_t)(t + 2) * kstep; const char* b2 = last ? nB : cB + (size_t)(t + 2) * kstep;
;             const char* a3 = a2 + kstep; const char* b3 = b2 + kstep;
;             if (last && has_next) S.a_ready(nxt);
;             if constexpr (SP2) {
;             PG8_LDB(B0, 0, 0); PG8_LDB(B1, 0, 1); PG8_SCHED; PG8_LDA(At, 0, 0); PG8_STAGE(PG8_SA(1, 1), a1 + hstepA, voffA);
;             PG8_WAIT_V(8); PG8_WAIT_L(0); PG8_BAR; PG8_MMA(0, 0, At, B0); PG8_MMA(0, 1, At, B1); PG8_BAR; PG8_SCHED;
;             PG8_LDA(At, 0, 1); PG8_STAGE(PG8_SB(0, 0), b2, voffB); PG8_STAGE(PG8_SB(0, 1), b2 + hstep, voffB); PG8_STAGE(PG8_SA(0, 0), a2, voffA);
;             PG8_WAIT_V(8); PG8_WAIT_L(0); PG8_BAR; PG8_MMA(1, 0, At, B0); PG8_MMA(1, 1, At, B1); PG8_BAR; PG8_SCHED;
.LBB0_282:
	s_add_u32 s26, s24, 0xfff80080
	s_addc_u32 s27, s25, -1
	s_add_i32 s45, 0, 0x10000
	s_cmp_eq_u32 s23, 28
	s_cselect_b32 s29, s19, s27
	s_cselect_b32 s28, s18, s26
	s_cselect_b32 s27, s21, s17
	s_cselect_b32 s26, s20, s15
	s_add_i32 s48, 0, 0x14000
	v_add_u32_e32 v158, s45, v152
	v_add_u32_e32 v186, s48, v152
	ds_read_b128 v[142:145], v158
	ds_read_b128 v[146:149], v158 offset:1024
	ds_read_b128 v[154:157], v158 offset:2048
	ds_read_b128 v[158:161], v158 offset:3072
	ds_read_b128 v[162:165], v186
	ds_read_b128 v[166:169], v186 offset:1024
	ds_read_b128 v[182:185], v186 offset:2048
	ds_read_b128 v[186:189], v186 offset:3072
	v_lshl_add_u64 v[222:223], s[24:25], 0, v[138:139]
	s_add_i32 m0, s33, 0xc000
	ds_read_b128 v[190:193], v153
	ds_read_b128 v[194:197], v153 offset:1024
	ds_read_b128 v[198:201], v153 offset:2048
	ds_read_b128 v[202:205], v153 offset:3072
	ds_read_b128 v[206:209], v153 offset:4096
	ds_read_b128 v[210:213], v153 offset:5120
	ds_read_b128 v[214:217], v153 offset:6144
	ds_read_b128 v[218:221], v153 offset:7168
	global_load_lds_dwordx4 v[222:223], off
	v_lshl_add_u64 v[222:223], s[24:25], 0, v[140:141]
	s_add_i32 m0, s33, 0xe000
	s_nop 0
	global_load_lds_dwordx4 v[222:223], off
	s_waitcnt vmcnt(8)
	s_waitcnt lgkmcnt(0)
	s_barrier
	s_setprio 1
	s_waitcnt lgkmcnt(0)
	v_mfma_f32_16x16x32_bf16 v[126:129], v[142:145], v[190:193], v[126:129]
	v_mfma_f32_16x16x32_bf16 v[118:121], v[154:157], v[190:193], v[118:121]
	v_mfma_f32_16x16x32_bf16 v[110:113], v[142:145], v[198:201], v[110:113]
	v_mfma_f32_16x16x32_bf16 v[102:105], v[154:157], v[198:201], v[102:105]
	v_mfma_f32_16x16x32_bf16 v[94:97], v[142:145], v[206:209], v[94:97]
	v_mfma_f32_16x16x32_bf16 v[86:89], v[154:157], v[206:209], v[86:89]
	v_mfma_f32_16x16x32_bf16 v[78:81], v[142:145], v[214:217], v[78:81]
	v_mfma_f32_16x16x32_bf16 v[70:73], v[154:157], v[214:217], v[70:73]
	v_mfma_f32_16x16x32_bf16 v[126:129], v[146:149], v[194:197], v[126:129]
	v_mfma_f32_16x16x32_bf16 v[118:121], v[158:161], v[194:197], v[118:121]
	v_mfma_f32_16x16x32_bf16 v[110:113], v[146:149], v[202:205], v[110:113]
	v_mfma_f32_16x16x32_bf16 v[102:105], v[158:161], v[202:205], v[102:105]
	v_mfma_f32_16x16x32_bf16 v[94:97], v[146:149], v[210:213], v[94:97]
	v_mfma_f32_16x16x32_bf16 v[86:89], v[158:161], v[210:213], v[86:89]
	v_mfma_f32_16x16x32_bf16 v[78:81], v[146:149], v[218:221], v[78:81]
	v_mfma_f32_16x16x32_bf16 v[70:73], v[158:161], v[218:221], v[70:73]
	s_setprio 0
	s_setprio 1
	v_mfma_f32_16x16x32_bf16 v[122:125], v[162:165], v[190:193], v[122:125]
	v_mfma_f32_16x16x32_bf16 v[114:117], v[182:185], v[190:193], v[114:117]
	v_mfma_f32_16x16x32_bf16 v[106:109], v[162:165], v[198:201], v[106:109]
	v_mfma_f32_16x16x32_bf16 v[98:101], v[182:185], v[198:201], v[98:101]
	v_mfma_f32_16x16x32_bf16 v[90:93], v[162:165], v[206:209], v[90:93]
	v_mfma_f32_16x16x32_bf16 v[82:85], v[182:185], v[206:209], v[82:85]
	v_mfma_f32_16x16x32_bf16 v[74:77], v[162:165], v[214:217], v[74:77]
	v_mfma_f32_16x16x32_bf16 v[66:69], v[182:185], v[214:217], v[66:69]
	v_mfma_f32_16x16x32_bf16 v[122:125], v[166:169], v[194:197], v[122:125]
	v_mfma_f32_16x16x32_bf16 v[114:117], v[186:189], v[194:197], v[114:117]
	v_mfma_f32_16x16x32_bf16 v[106:109], v[166:169], v[202:205], v[106:109]
	v_mfma_f32_16x16x32_bf16 v[98:101], v[186:189], v[202:205], v[98:101]
	v_mfma_f32_16x16x32_bf16 v[90:93], v[166:169], v[210:213], v[90:93]
	v_mfma_f32_16x16x32_bf16 v[82:85], v[186:189], v[210:213], v[82:85]
	v_mfma_f32_16x16x32_bf16 v[74:77], v[166:169], v[218:221], v[74:77]
	v_mfma_f32_16x16x32_bf16 v[66:69], v[186:189], v[218:221], v[66:69]
	s_setprio 0
	s_barrier
	s_add_i32 s45, s45, s31
	v_lshl_add_u64 v[222:223], s[26:27], 0, v[0:1]
	s_mov_b32 m0, s45
	ds_read_b128 v[190:193], v153 offset:16384
	ds_read_b128 v[194:197], v153 offset:17408
	ds_read_b128 v[198:201], v153 offset:18432
	ds_read_b128 v[202:205], v153 offset:19456
	ds_read_b128 v[206:209], v153 offset:20480
	ds_read_b128 v[210:213], v153 offset:21504
	ds_read_b128 v[214:217], v153 offset:22528
	ds_read_b128 v[218:221], v153 offset:23552
	global_load_lds_dwordx4 v[222:223], off
	s_add_i32 m0, s45, 0x2000
	s_add_u32 s46, s26, 0x80000
	v_lshl_add_u64 v[224:225], s[26:27], 0, v[130:131]
	s_addc_u32 s47, s27, 0
	s_add_i32 s45, s48, s31
	global_load_lds_dwordx4 v[224:225], off
	v_lshl_add_u64 v[226:227], s[46:47], 0, v[0:1]
	s_mov_b32 m0, s45
	v_lshl_add_u64 v[228:229], s[28:29], 0, v[132:133]
	global_load_lds_dwordx4 v[226:227], off
	v_lshl_add_u64 v[226:227], s[46:47], 0, v[130:131]
	s_add_i32 m0, s45, 0x2000
	s_nop 0
	global_load_lds_dwordx4 v[226:227], off
	s_waitcnt vmcnt(6)
	s_waitcnt lgkmcnt(0)
	s_barrier
; #define PG8_STAGE(bufoff, gbase, voff) do { _Pragma("unroll") for (int _i = 0; _i < 2; ++_i) \
;         __builtin_amdgcn_global_load_lds((const unsigned*)((const char*)(gbase) + (voff)[_i]), (PG8_LAS unsigned*)(lds + (bufoff) + ldsw + _i * 8192), 16, 0, 0); } while (0)
; #define PG8_LDA(dst, b, h) do { _Pragma("unroll") for (int m = 0; m < 4; ++m) _Pragma("unroll") for (int k = 0; k < 2; ++k) dst[m][k] = *(const PG8_LAS bf16x8*)(lds + PG8_SA(b, h) + aoff + m * 2048 + k * 1024); } while (0)
; #define PG8_LDB(dst, b, h) do { _Pragma("unroll") for (int n = 0; n < 2; ++n) _Pragma("unroll") for (int k = 0; k < 2; ++k) dst[n][k] = *(const PG8_LAS bf16x8*)(lds + PG8_SB(b, h) + boff + n * 2048 + k * 1024); } while (0)
; #define PG8_MMA(ai, bj, At, Bt) do { __builtin_amdgcn_s_setprio(1); _Pragma("unroll") for (int m = 0; m < 4; ++m) _Pragma("unroll") for (int n = 0; n < 2; ++n) _Pragma("unroll") for (int k = 0; k < 2; ++k) \
;         acc[ai][bj][m][n] = __builtin_amdgcn_mfma_f32_16x16x32_bf16(Bt[n][k], At[m][k], acc[ai][bj][m][n], 0, 0, 0); __builtin_amdgcn_s_setprio(0); } while (0)
; #define PG8_WAIT_V(n) asm volatile("s_waitcnt vmcnt(" #n ")" ::: "memory")
; #define PG8_WAIT_L(n) asm volatile("s_waitcnt lgkmcnt(" #n ")" ::: "memory")
; #define PG8_BAR __builtin_amdgcn_s_barrier()
; #define PG8_SCHED __builtin_amdgcn_sched_barrier(0)
; template <class Epi, class Sched, bool ALIGN_EPI = false, bool SP2 = false>
; __device__ __forceinline__ void gemm_phase(PG8_LAS unsigned char* lds, const Gemm g, const Sched& S, const Epi& E, int tid_in) {
;     ...
;             PG8_WAIT_V(8); PG8_WAIT_L(0); PG8_BAR; PG8_MMA(1, 0, At, B0); PG8_MMA(1, 1, At, B1); PG8_BAR; PG8_SCHED;
;             PG8_LDB(B0, 1, 0); PG8_LDB(B1, 1, 1); PG8_SCHED; PG8_LDA(At, 1, 0); PG8_STAGE(PG8_SA(0, 1), a2 + hstepA, voffA);
;             PG8_WAIT_V(8); PG8_WAIT_L(0); PG8_BAR; PG8_MMA(0, 0, At, B0); PG8_MMA(0, 1, At, B1); PG8_BAR; PG8_SCHED;
	s_setprio 1
	s_waitcnt lgkmcnt(0)
	v_mfma_f32_16x16x32_bf16 v[62:65], v[142:145], v[190:193], v[62:65]
	v_mfma_f32_16x16x32_bf16 v[54:57], v[154:157], v[190:193], v[54:57]
	v_mfma_f32_16x16x32_bf16 v[46:49], v[142:145], v[198:201], v[46:49]
	v_mfma_f32_16x16x32_bf16 v[38:41], v[154:157], v[198:201], v[38:41]
	v_mfma_f32_16x16x32_bf16 v[30:33], v[142:145], v[206:209], v[30:33]
	v_mfma_f32_16x16x32_bf16 v[22:25], v[154:157], v[206:209], v[22:25]
	v_mfma_f32_16x16x32_bf16 v[14:17], v[142:145], v[214:217], v[14:17]
	v_mfma_f32_16x16x32_bf16 v[6:9], v[154:157], v[214:217], v[6:9]
	v_mfma_f32_16x16x32_bf16 v[62:65], v[146:149], v[194:197], v[62:65]
	v_mfma_f32_16x16x32_bf16 v[54:57], v[158:161], v[194:197], v[54:57]
	v_mfma_f32_16x16x32_bf16 v[46:49], v[146:149], v[202:205], v[46:49]
	v_mfma_f32_16x16x32_bf16 v[38:41], v[158:161], v[202:205], v[38:41]
	v_mfma_f32_16x16x32_bf16 v[30:33], v[146:149], v[210:213], v[30:33]
	v_mfma_f32_16x16x32_bf16 v[22:25], v[158:161], v[210:213], v[22:25]
	v_mfma_f32_16x16x32_bf16 v[14:17], v[146:149], v[218:221], v[14:17]
	v_mfma_f32_16x16x32_bf16 v[6:9], v[158:161], v[218:221], v[6:9]
	s_setprio 0
	s_setprio 1
	v_mfma_f32_16x16x32_bf16 v[58:61], v[162:165], v[190:193], v[58:61]
	v_mfma_f32_16x16x32_bf16 v[50:53], v[182:185], v[190:193], v[50:53]
	v_mfma_f32_16x16x32_bf16 v[42:45], v[162:165], v[198:201], v[42:45]
	v_mfma_f32_16x16x32_bf16 v[34:37], v[182:185], v[198:201], v[34:37]
	v_mfma_f32_16x16x32_bf16 v[26:29], v[162:165], v[206:209], v[26:29]
	v_mfma_f32_16x16x32_bf16 v[18:21], v[182:185], v[206:209], v[18:21]
	v_mfma_f32_16x16x32_bf16 v[10:13], v[162:165], v[214:217], v[10:13]
	v_mfma_f32_16x16x32_bf16 v[2:5], v[182:185], v[214:217], v[2:5]
	v_mfma_f32_16x16x32_bf16 v[58:61], v[166:169], v[194:197], v[58:61]
	v_mfma_f32_16x16x32_bf16 v[50:53], v[186:189], v[194:197], v[50:53]
	v_mfma_f32_16x16x32_bf16 v[42:45], v[166:169], v[202:205], v[42:45]
	v_mfma_f32_16x16x32_bf16 v[34:37], v[186:189], v[202:205], v[34:37]
	v_mfma_f32_16x16x32_bf16 v[26:29], v[166:169], v[210:213], v[26:29]
	v_mfma_f32_16x16x32_bf16 v[18:21], v[186:189], v[210:213], v[18:21]
	v_mfma_f32_16x16x32_bf16 v[10:13], v[166:169], v[218:221], v[10:13]
	v_mfma_f32_16x16x32_bf16 v[2:5], v[186:189], v[218:221], v[2:5]
	s_setprio 0
	s_barrier
	v_lshl_add_u64 v[226:227], s[28:29], 0, v[134:135]
	s_mov_b32 m0, s33
	s_nop 0
	global_load_lds_dwordx4 v[226:227], off
	s_mov_b32 m0, s34
	s_nop 0
	global_load_lds_dwordx4 v[228:229], off
	s_add_i32 s45, 0, 0x18000
	s_add_i32 s46, 0, 0x1c000
	v_add_u32_e32 v158, s45, v152
	v_add_u32_e32 v186, s46, v152
	ds_read_b128 v[142:145], v158
	ds_read_b128 v[146:149], v158 offset:1024
	ds_read_b128 v[154:157], v158 offset:2048
	ds_read_b128 v[158:161], v158 offset:3072
	ds_read_b128 v[162:165], v186
	ds_read_b128 v[166:169], v186 offset:1024
	ds_read_b128 v[182:185], v186 offset:2048
	ds_read_b128 v[186:189], v186 offset:3072
	s_add_u32 s28, s28, 0x80000
	s_addc_u32 s29, s29, 0
	s_mov_b32 m0, s35
	v_lshl_add_u64 v[240:241], s[28:29], 0, v[134:135]
	ds_read_b128 v[190:193], v153 offset:32768
	ds_read_b128 v[194:197], v153 offset:33792
	ds_read_b128 v[198:201], v153 offset:34816
	ds_read_b128 v[202:205], v153 offset:35840
	ds_read_b128 v[206:209], v153 offset:36864
	ds_read_b128 v[210:213], v153 offset:37888
	ds_read_b128 v[214:217], v153 offset:38912
	ds_read_b128 v[218:221], v153 offset:39936
	global_load_lds_dwordx4 v[240:241], off
	v_lshl_add_u64 v[240:241], s[28:29], 0, v[132:133]
	s_mov_b32 m0, s36
	s_nop 0
	global_load_lds_dwordx4 v[240:241], off
	s_waitcnt vmcnt(8)
	s_waitcnt lgkmcnt(0)
	s_barrier
	s_setprio 1
	s_waitcnt lgkmcnt(0)
	v_mfma_f32_16x16x32_bf16 v[126:129], v[142:145], v[190:193], v[126:129]
	v_mfma_f32_16x16x32_bf16 v[118:121], v[154:157], v[190:193], v[118:121]
	v_mfma_f32_16x16x32_bf16 v[110:113], v[142:145], v[198:201], v[110:113]
	v_mfma_f32_16x16x32_bf16 v[102:105], v[154:157], v[198:201], v[102:105]
	v_mfma_f32_16x16x32_bf16 v[94:97], v[142:145], v[206:209], v[94:97]
	v_mfma_f32_16x16x32_bf16 v[86:89], v[154:157], v[206:209], v[86:89]
	v_mfma_f32_16x16x32_bf16 v[78:81], v[142:145], v[214:217], v[78:81]
	v_mfma_f32_16x16x32_bf16 v[70:73], v[154:157], v[214:217], v[70:73]
	v_mfma_f32_16x16x32_bf16 v[126:129], v[146:149], v[194:197], v[126:129]
	v_mfma_f32_16x16x32_bf16 v[118:121], v[158:161], v[194:197], v[118:121]
	v_mfma_f32_16x16x32_bf16 v[110:113], v[146:149], v[202:205], v[110:113]
	v_mfma_f32_16x16x32_bf16 v[102:105], v[158:161], v[202:205], v[102:105]
	v_mfma_f32_16x16x32_bf16 v[94:97], v[146:149], v[210:213], v[94:97]
	v_mfma_f32_16x16x32_bf16 v[86:89], v[158:161], v[210:213], v[86:89]
	v_mfma_f32_16x16x32_bf16 v[78:81], v[146:149], v[218:221], v[78:81]
	v_mfma_f32_16x16x32_bf16 v[70:73], v[158:161], v[218:221], v[70:73]
	s_setprio 0
	s_setprio 1
	v_mfma_f32_16x16x32_bf16 v[122:125], v[162:165], v[190:193], v[122:125]
	v_mfma_f32_16x16x32_bf16 v[114:117], v[182:185], v[190:193], v[114:117]
	v_mfma_f32_16x16x32_bf16 v[106:109], v[162:165], v[198:201], v[106:109]
	v_mfma_f32_16x16x32_bf16 v[98:101], v[182:185], v[198:201], v[98:101]
	v_mfma_f32_16x16x32_bf16 v[90:93], v[162:165], v[206:209], v[90:93]
	v_mfma_f32_16x16x32_bf16 v[82:85], v[182:185], v[206:209], v[82:85]
	v_mfma_f32_16x16x32_bf16 v[74:77], v[162:165], v[214:217], v[74:77]
	v_mfma_f32_16x16x32_bf16 v[66:69], v[182:185], v[214:217], v[66:69]
	v_mfma_f32_16x16x32_bf16 v[122:125], v[166:169], v[194:197], v[122:125]
	v_mfma_f32_16x16x32_bf16 v[114:117], v[186:189], v[194:197], v[114:117]
	v_mfma_f32_16x16x32_bf16 v[106:109], v[166:169], v[202:205], v[106:109]
	v_mfma_f32_16x16x32_bf16 v[98:101], v[186:189], v[202:205], v[98:101]
	v_mfma_f32_16x16x32_bf16 v[90:93], v[166:169], v[210:213], v[90:93]
	v_mfma_f32_16x16x32_bf16 v[82:85], v[186:189], v[210:213], v[82:85]
	v_mfma_f32_16x16x32_bf16 v[74:77], v[166:169], v[218:221], v[74:77]
	v_mfma_f32_16x16x32_bf16 v[66:69], v[186:189], v[218:221], v[66:69]
	s_setprio 0
	s_barrier
; #define PG8_STAGE(bufoff, gbase, voff) do { _Pragma("unroll") for (int _i = 0; _i < 2; ++_i) \
;         __builtin_amdgcn_global_load_lds((const unsigned*)((const char*)(gbase) + (voff)[_i]), (PG8_LAS unsigned*)(lds + (bufoff) + ldsw + _i * 8192), 16, 0, 0); } while (0)
; #define PG8_LDA(dst, b, h) do { _Pragma("unroll") for (int m = 0; m < 4; ++m) _Pragma("unroll") for (int k = 0; k < 2; ++k) dst[m][k] = *(const PG8_LAS bf16x8*)(lds + PG8_SA(b, h) + aoff + m * 2048 + k * 1024); } while (0)
; #define PG8_MMA(ai, bj, At, Bt) do { __builtin_amdgcn_s_setprio(1); _Pragma("unroll") for (int m = 0; m < 4; ++m) _Pragma("unroll") for (int n = 0; n < 2; ++n) _Pragma("unroll") for (int k = 0; k < 2; ++k) \
;         acc[ai][bj][m][n] = __builtin_amdgcn_mfma_f32_16x16x32_bf16(Bt[n][k], At[m][k], acc[ai][bj][m][n], 0, 0, 0); __builtin_amdgcn_s_setprio(0); } while (0)
; #define PG8_WAIT_V(n) asm volatile("s_waitcnt vmcnt(" #n ")" ::: "memory")
; #define PG8_WAIT_L(n) asm volatile("s_waitcnt lgkmcnt(" #n ")" ::: "memory")
; #define PG8_BAR __builtin_amdgcn_s_barrier()
; #define PG8_SCHED __builtin_amdgcn_sched_barrier(0)
; template <class Epi, class Sched, bool ALIGN_EPI = false, bool SP2 = false>
; __device__ __forceinline__ void gemm_phase(PG8_LAS unsigned char* lds, const Gemm g, const Sched& S, const Epi& E, int tid_in) {
;     ...
;         for (int t = 0; t < nt; t += 2) {
;             const bool last = (t == nt - 2);
;     ...
;             PG8_LDA(At, 1, 1); PG8_STAGE(PG8_SB(1, 0), b3, voffB); PG8_STAGE(PG8_SB(1, 1), b3 + hstep, voffB); PG8_STAGE(PG8_SA(1, 0), a3, voffA);
;             PG8_WAIT_V(8); PG8_WAIT_L(0); PG8_BAR; PG8_MMA(1, 0, At, B0); PG8_MMA(1, 1, At, B1); PG8_BAR; PG8_SCHED;
	s_add_i32 s28, s45, s31
	v_lshl_add_u64 v[222:223], v[222:223], 0, s[90:91]
	s_mov_b32 m0, s28
	ds_read_b128 v[190:193], v153 offset:49152
	ds_read_b128 v[194:197], v153 offset:50176
	ds_read_b128 v[198:201], v153 offset:51200
	ds_read_b128 v[202:205], v153 offset:52224
	ds_read_b128 v[206:209], v153 offset:53248
	ds_read_b128 v[210:213], v153 offset:54272
	ds_read_b128 v[214:217], v153 offset:55296
	ds_read_b128 v[218:221], v153 offset:56320
	global_load_lds_dwordx4 v[222:223], off
	s_add_i32 m0, s28, 0x2000
	s_add_u32 s26, s26, 0x80080
	v_lshl_add_u64 v[222:223], v[224:225], 0, s[90:91]
	s_addc_u32 s27, s27, 0
	s_add_i32 s28, s46, s31
	global_load_lds_dwordx4 v[222:223], off
	v_lshl_add_u64 v[222:223], s[26:27], 0, v[0:1]
	s_mov_b32 m0, s28
	s_nop 0
	global_load_lds_dwordx4 v[222:223], off
	v_lshl_add_u64 v[222:223], s[26:27], 0, v[130:131]
	s_add_i32 m0, s28, 0x2000
	s_nop 0
	global_load_lds_dwordx4 v[222:223], off
	v_lshl_add_u64 v[222:223], v[226:227], 0, s[90:91]
	s_mov_b32 m0, s39
	s_nop 0
	global_load_lds_dwordx4 v[222:223], off
	v_lshl_add_u64 v[222:223], v[228:229], 0, s[90:91]
	s_mov_b32 m0, s40
	s_nop 0
	global_load_lds_dwordx4 v[222:223], off
	s_waitcnt vmcnt(8)
	s_waitcnt lgkmcnt(0)
	s_barrier
	s_setprio 1
	s_waitcnt lgkmcnt(0)
	v_mfma_f32_16x16x32_bf16 v[62:65], v[142:145], v[190:193], v[62:65]
	v_mfma_f32_16x16x32_bf16 v[54:57], v[154:157], v[190:193], v[54:57]
	v_mfma_f32_16x16x32_bf16 v[46:49], v[142:145], v[198:201], v[46:49]
	v_mfma_f32_16x16x32_bf16 v[38:41], v[154:157], v[198:201], v[38:41]
	v_mfma_f32_16x16x32_bf16 v[30:33], v[142:145], v[206:209], v[30:33]
	v_mfma_f32_16x16x32_bf16 v[22:25], v[154:157], v[206:209], v[22:25]
	v_mfma_f32_16x16x32_bf16 v[14:17], v[142:145], v[214:217], v[14:17]
	v_mfma_f32_16x16x32_bf16 v[6:9], v[154:157], v[214:217], v[6:9]
	v_mfma_f32_16x16x32_bf16 v[62:65], v[146:149], v[194:197], v[62:65]
	v_mfma_f32_16x16x32_bf16 v[54:57], v[158:161], v[194:197], v[54:57]
	v_mfma_f32_16x16x32_bf16 v[46:49], v[146:149], v[202:205], v[46:49]
	v_mfma_f32_16x16x32_bf16 v[38:41], v[158:161], v[202:205], v[38:41]
	v_mfma_f32_16x16x32_bf16 v[30:33], v[146:149], v[210:213], v[30:33]
	v_mfma_f32_16x16x32_bf16 v[22:25], v[158:161], v[210:213], v[22:25]
	v_mfma_f32_16x16x32_bf16 v[14:17], v[146:149], v[218:221], v[14:17]
	v_mfma_f32_16x16x32_bf16 v[6:9], v[158:161], v[218:221], v[6:9]
	s_setprio 0
	s_setprio 1
	v_mfma_f32_16x16x32_bf16 v[58:61], v[162:165], v[190:193], v[58:61]
	v_mfma_f32_16x16x32_bf16 v[50:53], v[182:185], v[190:193], v[50:53]
	v_mfma_f32_16x16x32_bf16 v[42:45], v[162:165], v[198:201], v[42:45]
	v_mfma_f32_16x16x32_bf16 v[34:37], v[182:185], v[198:201], v[34:37]
	v_mfma_f32_16x16x32_bf16 v[26:29], v[162:165], v[206:209], v[26:29]
	v_mfma_f32_16x16x32_bf16 v[18:21], v[182:185], v[206:209], v[18:21]
	v_mfma_f32_16x16x32_bf16 v[10:13], v[162:165], v[214:217], v[10:13]
	v_mfma_f32_16x16x32_bf16 v[2:5], v[182:185], v[214:217], v[2:5]
	v_mfma_f32_16x16x32_bf16 v[58:61], v[166:169], v[194:197], v[58:61]
	v_mfma_f32_16x16x32_bf16 v[50:53], v[186:189], v[194:197], v[50:53]
	v_mfma_f32_16x16x32_bf16 v[42:45], v[166:169], v[202:205], v[42:45]
	v_mfma_f32_16x16x32_bf16 v[34:37], v[186:189], v[202:205], v[34:37]
	v_mfma_f32_16x16x32_bf16 v[26:29], v[166:169], v[210:213], v[26:29]
	v_mfma_f32_16x16x32_bf16 v[18:21], v[186:189], v[210:213], v[18:21]
	v_mfma_f32_16x16x32_bf16 v[10:13], v[166:169], v[218:221], v[10:13]
	v_mfma_f32_16x16x32_bf16 v[2:5], v[186:189], v[218:221], v[2:5]
	s_setprio 0
	s_barrier
	s_add_i32 s23, s23, 2
	s_add_u32 s24, s24, 0x100
	s_addc_u32 s25, s25, 0
	s_add_u32 s15, s15, 0x100
	s_addc_u32 s17, s17, 0
	s_cmp_gt_u32 s23, 29
	s_cbranch_scc0 .LBB0_282
	s_and_b64 vcc, exec, s[12:13]
	s_cbranch_vccz .LBB0_285
	s_barrier

; #define PG8_STAGE(bufoff, gbase, voff) do { _Pragma("unroll") for (int _i = 0; _i < 2; ++_i) \
;         __builtin_amdgcn_global_load_lds((const unsigned*)((const char*)(gbase) + (voff)[_i]), (PG8_LAS unsigned*)(lds + (bufoff) + ldsw + _i * 8192), 16, 0, 0); } while (0)
; #define PG8_LDA(dst, b, h) do { _Pragma("unroll") for (int m = 0; m < 4; ++m) _Pragma("unroll") for (int k = 0; k < 2; ++k) dst[m][k] = *(const PG8_LAS bf16x8*)(lds + PG8_SA(b, h) + aoff + m * 2048 + k * 1024); } while (0)
; #define PG8_LDB(dst, b, h) do { _Pragma("unroll") for (int n = 0; n < 2; ++n) _Pragma("unroll") for (int k = 0; k < 2; ++k) dst[n][k] = *(const PG8_LAS bf16x8*)(lds + PG8_SB(b, h) + boff + n * 2048 + k * 1024); } while (0)
; #define PG8_MMA(ai, bj, At, Bt) do { __builtin_amdgcn_s_setprio(1); _Pragma("unroll") for (int m = 0; m < 4; ++m) _Pragma("unroll") for (int n = 0; n < 2; ++n) _Pragma("unroll") for (int k = 0; k < 2; ++k) \
;         acc[ai][bj][m][n] = __builtin_amdgcn_mfma_f32_16x16x32_bf16(Bt[n][k], At[m][k], acc[ai][bj][m][n], 0, 0, 0); __builtin_amdgcn_s_setprio(0); } while (0)
; #define PG8_WAIT_V(n) asm volatile("s_waitcnt vmcnt(" #n ")" ::: "memory")
; #define PG8_WAIT_L(n) asm volatile("s_waitcnt lgkmcnt(" #n ")" ::: "memory")
; template <class Epi, class Sched, bool ALIGN_EPI = false, bool SP2 = false>
; __device__ __forceinline__ void gemm_phase(PG8_LAS unsigned char* lds, const Gemm g, const Sched& S, const Epi& E, int tid_in) {
;     ...
;             const bool last = (t == nt - 2);
;             const char* a1 = cA + (size_t)(t + 1) * kstep;
;             const char* a2 = last ? nA : cA + (size_t)(t + 2) * kstep; const char* b2 = last ? nB : cB + (size_t)(t + 2) * kstep;
;             const char* a3 = a2 + kstep; const char* b3 = b2 + kstep;
;             if (last && has_next) S.a_ready(nxt);
;             if constexpr (SP2) {
;             PG8_LDB(B0, 0, 0); PG8_LDB(B1, 0, 1); PG8_SCHED; PG8_LDA(At, 0, 0); PG8_STAGE(PG8_SA(1, 1), a1 + hstepA, voffA);
;             PG8_WAIT_V(8); PG8_WAIT_L(0); PG8_BAR; PG8_MMA(0, 0, At, B0); PG8_MMA(0, 1, At, B1); PG8_BAR; PG8_SCHED;
;             PG8_LDA(At, 0, 1); PG8_STAGE(PG8_SB(0, 0), b2, voffB); PG8_STAGE(PG8_SB(0, 1), b2 + hstep, voffB); PG8_STAGE(PG8_SA(0, 0), a2, voffA);
;             PG8_WAIT_V(8); PG8_WAIT_L(0); PG8_BAR; PG8_MMA(1, 0, At, B0); PG8_MMA(1, 1, At, B1); PG8_BAR; PG8_SCHED;
.LBB0_352:
	s_add_i32 s82, s28, 2
	s_add_u32 s26, s8, 0x100
	s_addc_u32 s27, s9, 0
	s_add_i32 s4, 0, 0x10000
	s_cmp_eq_u32 s70, s28
	s_cselect_b32 s31, s46, s27
	s_cselect_b32 s30, s47, s26
	s_cselect_b32 s29, s67, s79
	s_cselect_b32 s28, s68, s76
	s_add_i32 s5, 0, 0x14000
	v_add_u32_e32 v152, s4, v146
	v_add_u32_e32 v168, s5, v146
	ds_read_b128 v[136:139], v152
	ds_read_b128 v[140:143], v152 offset:1024
	ds_read_b128 v[148:151], v152 offset:2048
	ds_read_b128 v[152:155], v152 offset:3072
	ds_read_b128 v[156:159], v168
	ds_read_b128 v[160:163], v168 offset:1024
	ds_read_b128 v[164:167], v168 offset:2048
	ds_read_b128 v[182:185], v168 offset:3072
	v_lshl_add_u64 v[168:169], s[8:9], 0, v[132:133]
	s_add_i32 m0, s34, 0xc000
	ds_read_b128 v[186:189], v147
	ds_read_b128 v[190:193], v147 offset:1024
	ds_read_b128 v[194:197], v147 offset:2048
	ds_read_b128 v[198:201], v147 offset:3072
	ds_read_b128 v[202:205], v147 offset:4096
	ds_read_b128 v[206:209], v147 offset:5120
	ds_read_b128 v[210:213], v147 offset:6144
	ds_read_b128 v[214:217], v147 offset:7168
	global_load_lds_dwordx4 v[168:169], off
	v_lshl_add_u64 v[168:169], s[8:9], 0, v[134:135]
	s_add_i32 m0, s34, 0xe000
	s_nop 0
	global_load_lds_dwordx4 v[168:169], off
	s_waitcnt vmcnt(8)
	s_waitcnt lgkmcnt(0)
	s_barrier
	s_setprio 1
	s_waitcnt lgkmcnt(0)
	v_mfma_f32_16x16x32_bf16 v[126:129], v[136:139], v[186:189], v[126:129]
	v_mfma_f32_16x16x32_bf16 v[122:125], v[148:151], v[186:189], v[122:125]
	v_mfma_f32_16x16x32_bf16 v[118:121], v[136:139], v[194:197], v[118:121]
	v_mfma_f32_16x16x32_bf16 v[114:117], v[148:151], v[194:197], v[114:117]
	v_mfma_f32_16x16x32_bf16 v[110:113], v[136:139], v[202:205], v[110:113]
	v_mfma_f32_16x16x32_bf16 v[106:109], v[148:151], v[202:205], v[106:109]
	v_mfma_f32_16x16x32_bf16 v[102:105], v[136:139], v[210:213], v[102:105]
	v_mfma_f32_16x16x32_bf16 v[98:101], v[148:151], v[210:213], v[98:101]
	v_mfma_f32_16x16x32_bf16 v[126:129], v[140:143], v[190:193], v[126:129]
	v_mfma_f32_16x16x32_bf16 v[122:125], v[152:155], v[190:193], v[122:125]
	v_mfma_f32_16x16x32_bf16 v[118:121], v[140:143], v[198:201], v[118:121]
	v_mfma_f32_16x16x32_bf16 v[114:117], v[152:155], v[198:201], v[114:117]
	v_mfma_f32_16x16x32_bf16 v[110:113], v[140:143], v[206:209], v[110:113]
	v_mfma_f32_16x16x32_bf16 v[106:109], v[152:155], v[206:209], v[106:109]
	v_mfma_f32_16x16x32_bf16 v[102:105], v[140:143], v[214:217], v[102:105]
	v_mfma_f32_16x16x32_bf16 v[98:101], v[152:155], v[214:217], v[98:101]
	s_setprio 0
	s_setprio 1
	v_mfma_f32_16x16x32_bf16 v[94:97], v[156:159], v[186:189], v[94:97]
	v_mfma_f32_16x16x32_bf16 v[90:93], v[164:167], v[186:189], v[90:93]
	v_mfma_f32_16x16x32_bf16 v[86:89], v[156:159], v[194:197], v[86:89]
	v_mfma_f32_16x16x32_bf16 v[82:85], v[164:167], v[194:197], v[82:85]
	v_mfma_f32_16x16x32_bf16 v[78:81], v[156:159], v[202:205], v[78:81]
	v_mfma_f32_16x16x32_bf16 v[74:77], v[164:167], v[202:205], v[74:77]
	v_mfma_f32_16x16x32_bf16 v[70:73], v[156:159], v[210:213], v[70:73]
	v_mfma_f32_16x16x32_bf16 v[66:69], v[164:167], v[210:213], v[66:69]
	v_mfma_f32_16x16x32_bf16 v[94:97], v[160:163], v[190:193], v[94:97]
	v_mfma_f32_16x16x32_bf16 v[90:93], v[182:185], v[190:193], v[90:93]
	v_mfma_f32_16x16x32_bf16 v[86:89], v[160:163], v[198:201], v[86:89]
	v_mfma_f32_16x16x32_bf16 v[82:85], v[182:185], v[198:201], v[82:85]
	v_mfma_f32_16x16x32_bf16 v[78:81], v[160:163], v[206:209], v[78:81]
	v_mfma_f32_16x16x32_bf16 v[74:77], v[182:185], v[206:209], v[74:77]
	v_mfma_f32_16x16x32_bf16 v[70:73], v[160:163], v[214:217], v[70:73]
	v_mfma_f32_16x16x32_bf16 v[66:69], v[182:185], v[214:217], v[66:69]
	s_setprio 0
	s_barrier
	s_add_i32 s8, s4, s33
	v_lshl_add_u64 v[168:169], s[28:29], 0, v[0:1]
	s_mov_b32 m0, s8
	ds_read_b128 v[186:189], v147 offset:16384
	ds_read_b128 v[190:193], v147 offset:17408
	ds_read_b128 v[194:197], v147 offset:18432
	ds_read_b128 v[198:201], v147 offset:19456
	ds_read_b128 v[202:205], v147 offset:20480
	ds_read_b128 v[206:209], v147 offset:21504
	ds_read_b128 v[210:213], v147 offset:22528
	ds_read_b128 v[214:217], v147 offset:23552
	global_load_lds_dwordx4 v[168:169], off
	s_add_i32 m0, s8, 0x2000
	s_add_u32 s8, s28, 0x160000
	v_lshl_add_u64 v[218:219], s[28:29], 0, v[130:131]
	s_addc_u32 s9, s29, 0
	s_add_i32 s55, s5, s33
	global_load_lds_dwordx4 v[218:219], off
	v_lshl_add_u64 v[220:221], s[8:9], 0, v[0:1]
	s_mov_b32 m0, s55
	v_lshl_add_u64 v[222:223], s[30:31], 0, v[130:131]
	global_load_lds_dwordx4 v[220:221], off
	v_lshl_add_u64 v[220:221], s[8:9], 0, v[130:131]
	s_add_i32 m0, s55, 0x2000
	s_nop 0
	global_load_lds_dwordx4 v[220:221], off
	s_waitcnt vmcnt(6)
	s_waitcnt lgkmcnt(0)
	s_barrier
; #define PG8_STAGE(bufoff, gbase, voff) do { _Pragma("unroll") for (int _i = 0; _i < 2; ++_i) \
;         __builtin_amdgcn_global_load_lds((const unsigned*)((const char*)(gbase) + (voff)[_i]), (PG8_LAS unsigned*)(lds + (bufoff) + ldsw + _i * 8192), 16, 0, 0); } while (0)
; #define PG8_LDA(dst, b, h) do { _Pragma("unroll") for (int m = 0; m < 4; ++m) _Pragma("unroll") for (int k = 0; k < 2; ++k) dst[m][k] = *(const PG8_LAS bf16x8*)(lds + PG8_SA(b, h) + aoff + m * 2048 + k * 1024); } while (0)
; #define PG8_LDB(dst, b, h) do { _Pragma("unroll") for (int n = 0; n < 2; ++n) _Pragma("unroll") for (int k = 0; k < 2; ++k) dst[n][k] = *(const PG8_LAS bf16x8*)(lds + PG8_SB(b, h) + boff + n * 2048 + k * 1024); } while (0)
; #define PG8_MMA(ai, bj, At, Bt) do { __builtin_amdgcn_s_setprio(1); _Pragma("unroll") for (int m = 0; m < 4; ++m) _Pragma("unroll") for (int n = 0; n < 2; ++n) _Pragma("unroll") for (int k = 0; k < 2; ++k) \
;         acc[ai][bj][m][n] = __builtin_amdgcn_mfma_f32_16x16x32_bf16(Bt[n][k], At[m][k], acc[ai][bj][m][n], 0, 0, 0); __builtin_amdgcn_s_setprio(0); } while (0)
; #define PG8_WAIT_V(n) asm volatile("s_waitcnt vmcnt(" #n ")" ::: "memory")
; #define PG8_WAIT_L(n) asm volatile("s_waitcnt lgkmcnt(" #n ")" ::: "memory")
; #define PG8_BAR __builtin_amdgcn_s_barrier()
; #define PG8_SCHED __builtin_amdgcn_sched_barrier(0)
; template <class Epi, class Sched, bool ALIGN_EPI = false, bool SP2 = false>
; __device__ __forceinline__ void gemm_phase(PG8_LAS unsigned char* lds, const Gemm g, const Sched& S, const Epi& E, int tid_in) {
;     ...
;             PG8_WAIT_V(8); PG8_WAIT_L(0); PG8_BAR; PG8_MMA(1, 0, At, B0); PG8_MMA(1, 1, At, B1); PG8_BAR; PG8_SCHED;
;             PG8_LDB(B0, 1, 0); PG8_LDB(B1, 1, 1); PG8_SCHED; PG8_LDA(At, 1, 0); PG8_STAGE(PG8_SA(0, 1), a2 + hstepA, voffA);
;             PG8_WAIT_V(8); PG8_WAIT_L(0); PG8_BAR; PG8_MMA(0, 0, At, B0); PG8_MMA(0, 1, At, B1); PG8_BAR; PG8_SCHED;
	s_setprio 1
	s_waitcnt lgkmcnt(0)
	v_mfma_f32_16x16x32_bf16 v[62:65], v[136:139], v[186:189], v[62:65]
	v_mfma_f32_16x16x32_bf16 v[58:61], v[148:151], v[186:189], v[58:61]
	v_mfma_f32_16x16x32_bf16 v[54:57], v[136:139], v[194:197], v[54:57]
	v_mfma_f32_16x16x32_bf16 v[50:53], v[148:151], v[194:197], v[50:53]
	v_mfma_f32_16x16x32_bf16 v[46:49], v[136:139], v[202:205], v[46:49]
	v_mfma_f32_16x16x32_bf16 v[42:45], v[148:151], v[202:205], v[42:45]
	v_mfma_f32_16x16x32_bf16 v[38:41], v[136:139], v[210:213], v[38:41]
	v_mfma_f32_16x16x32_bf16 v[34:37], v[148:151], v[210:213], v[34:37]
	v_mfma_f32_16x16x32_bf16 v[62:65], v[140:143], v[190:193], v[62:65]
	v_mfma_f32_16x16x32_bf16 v[58:61], v[152:155], v[190:193], v[58:61]
	v_mfma_f32_16x16x32_bf16 v[54:57], v[140:143], v[198:201], v[54:57]
	v_mfma_f32_16x16x32_bf16 v[50:53], v[152:155], v[198:201], v[50:53]
	v_mfma_f32_16x16x32_bf16 v[46:49], v[140:143], v[206:209], v[46:49]
	v_mfma_f32_16x16x32_bf16 v[42:45], v[152:155], v[206:209], v[42:45]
	v_mfma_f32_16x16x32_bf16 v[38:41], v[140:143], v[214:217], v[38:41]
	v_mfma_f32_16x16x32_bf16 v[34:37], v[152:155], v[214:217], v[34:37]
	s_setprio 0
	s_setprio 1
	v_mfma_f32_16x16x32_bf16 v[30:33], v[156:159], v[186:189], v[30:33]
	v_mfma_f32_16x16x32_bf16 v[26:29], v[164:167], v[186:189], v[26:29]
	v_mfma_f32_16x16x32_bf16 v[22:25], v[156:159], v[194:197], v[22:25]
	v_mfma_f32_16x16x32_bf16 v[18:21], v[164:167], v[194:197], v[18:21]
	v_mfma_f32_16x16x32_bf16 v[14:17], v[156:159], v[202:205], v[14:17]
	v_mfma_f32_16x16x32_bf16 v[10:13], v[164:167], v[202:205], v[10:13]
	v_mfma_f32_16x16x32_bf16 v[6:9], v[156:159], v[210:213], v[6:9]
	v_mfma_f32_16x16x32_bf16 v[2:5], v[164:167], v[210:213], v[2:5]
	v_mfma_f32_16x16x32_bf16 v[30:33], v[160:163], v[190:193], v[30:33]
	v_mfma_f32_16x16x32_bf16 v[26:29], v[182:185], v[190:193], v[26:29]
	v_mfma_f32_16x16x32_bf16 v[22:25], v[160:163], v[198:201], v[22:25]
	v_mfma_f32_16x16x32_bf16 v[18:21], v[182:185], v[198:201], v[18:21]
	v_mfma_f32_16x16x32_bf16 v[14:17], v[160:163], v[206:209], v[14:17]
	v_mfma_f32_16x16x32_bf16 v[10:13], v[182:185], v[206:209], v[10:13]
	v_mfma_f32_16x16x32_bf16 v[6:9], v[160:163], v[214:217], v[6:9]
	v_mfma_f32_16x16x32_bf16 v[2:5], v[182:185], v[214:217], v[2:5]
	s_setprio 0
	s_barrier
	v_lshl_add_u64 v[220:221], s[30:31], 0, v[0:1]
	s_mov_b32 m0, s34
	s_nop 0
	global_load_lds_dwordx4 v[220:221], off
	s_mov_b32 m0, s35
	s_nop 0
	global_load_lds_dwordx4 v[222:223], off
	s_add_i32 s63, 0, 0x18000
	s_add_i32 s55, 0, 0x1c000
	v_add_u32_e32 v152, s63, v146
	v_add_u32_e32 v182, s55, v146
	ds_read_b128 v[136:139], v152
	ds_read_b128 v[140:143], v152 offset:1024
	ds_read_b128 v[148:151], v152 offset:2048
	ds_read_b128 v[152:155], v152 offset:3072
	ds_read_b128 v[156:159], v182
	ds_read_b128 v[160:163], v182 offset:1024
	ds_read_b128 v[164:167], v182 offset:2048
	ds_read_b128 v[182:185], v182 offset:3072
	s_add_u32 s8, s30, 0x160000
	s_addc_u32 s9, s31, 0
	s_mov_b32 m0, s36
	v_lshl_add_u64 v[224:225], s[8:9], 0, v[0:1]
	ds_read_b128 v[186:189], v147 offset:32768
	ds_read_b128 v[190:193], v147 offset:33792
	ds_read_b128 v[194:197], v147 offset:34816
	ds_read_b128 v[198:201], v147 offset:35840
	ds_read_b128 v[202:205], v147 offset:36864
	ds_read_b128 v[206:209], v147 offset:37888
	ds_read_b128 v[210:213], v147 offset:38912
	ds_read_b128 v[214:217], v147 offset:39936
	global_load_lds_dwordx4 v[224:225], off
	v_lshl_add_u64 v[224:225], s[8:9], 0, v[130:131]
	s_mov_b32 m0, s37
	s_nop 0
	global_load_lds_dwordx4 v[224:225], off
	s_waitcnt vmcnt(8)
	s_waitcnt lgkmcnt(0)
	s_barrier
	s_setprio 1
	s_waitcnt lgkmcnt(0)
	v_mfma_f32_16x16x32_bf16 v[126:129], v[136:139], v[186:189], v[126:129]
	v_mfma_f32_16x16x32_bf16 v[122:125], v[148:151], v[186:189], v[122:125]
	v_mfma_f32_16x16x32_bf16 v[118:121], v[136:139], v[194:197], v[118:121]
	v_mfma_f32_16x16x32_bf16 v[114:117], v[148:151], v[194:197], v[114:117]
	v_mfma_f32_16x16x32_bf16 v[110:113], v[136:139], v[202:205], v[110:113]
	v_mfma_f32_16x16x32_bf16 v[106:109], v[148:151], v[202:205], v[106:109]
	v_mfma_f32_16x16x32_bf16 v[102:105], v[136:139], v[210:213], v[102:105]
	v_mfma_f32_16x16x32_bf16 v[98:101], v[148:151], v[210:213], v[98:101]
	v_mfma_f32_16x16x32_bf16 v[126:129], v[140:143], v[190:193], v[126:129]
	v_mfma_f32_16x16x32_bf16 v[122:125], v[152:155], v[190:193], v[122:125]
	v_mfma_f32_16x16x32_bf16 v[118:121], v[140:143], v[198:201], v[118:121]
	v_mfma_f32_16x16x32_bf16 v[114:117], v[152:155], v[198:201], v[114:117]
	v_mfma_f32_16x16x32_bf16 v[110:113], v[140:143], v[206:209], v[110:113]
	v_mfma_f32_16x16x32_bf16 v[106:109], v[152:155], v[206:209], v[106:109]
	v_mfma_f32_16x16x32_bf16 v[102:105], v[140:143], v[214:217], v[102:105]
	v_mfma_f32_16x16x32_bf16 v[98:101], v[152:155], v[214:217], v[98:101]
	s_setprio 0
	s_setprio 1
	v_mfma_f32_16x16x32_bf16 v[94:97], v[156:159], v[186:189], v[94:97]
	v_mfma_f32_16x16x32_bf16 v[90:93], v[164:167], v[186:189], v[90:93]
	v_mfma_f32_16x16x32_bf16 v[86:89], v[156:159], v[194:197], v[86:89]
	v_mfma_f32_16x16x32_bf16 v[82:85], v[164:167], v[194:197], v[82:85]
	v_mfma_f32_16x16x32_bf16 v[78:81], v[156:159], v[202:205], v[78:81]
	v_mfma_f32_16x16x32_bf16 v[74:77], v[164:167], v[202:205], v[74:77]
	v_mfma_f32_16x16x32_bf16 v[70:73], v[156:159], v[210:213], v[70:73]
	v_mfma_f32_16x16x32_bf16 v[66:69], v[164:167], v[210:213], v[66:69]
	v_mfma_f32_16x16x32_bf16 v[94:97], v[160:163], v[190:193], v[94:97]
	v_mfma_f32_16x16x32_bf16 v[90:93], v[182:185], v[190:193], v[90:93]
	v_mfma_f32_16x16x32_bf16 v[86:89], v[160:163], v[198:201], v[86:89]
	v_mfma_f32_16x16x32_bf16 v[82:85], v[182:185], v[198:201], v[82:85]
	v_mfma_f32_16x16x32_bf16 v[78:81], v[160:163], v[206:209], v[78:81]
	v_mfma_f32_16x16x32_bf16 v[74:77], v[182:185], v[206:209], v[74:77]
	v_mfma_f32_16x16x32_bf16 v[70:73], v[160:163], v[214:217], v[70:73]
	v_mfma_f32_16x16x32_bf16 v[66:69], v[182:185], v[214:217], v[66:69]
	s_setprio 0
	s_barrier
; #define PG8_STAGE(bufoff, gbase, voff) do { _Pragma("unroll") for (int _i = 0; _i < 2; ++_i) \
;         __builtin_amdgcn_global_load_lds((const unsigned*)((const char*)(gbase) + (voff)[_i]), (PG8_LAS unsigned*)(lds + (bufoff) + ldsw + _i * 8192), 16, 0, 0); } while (0)
; #define PG8_LDA(dst, b, h) do { _Pragma("unroll") for (int m = 0; m < 4; ++m) _Pragma("unroll") for (int k = 0; k < 2; ++k) dst[m][k] = *(const PG8_LAS bf16x8*)(lds + PG8_SA(b, h) + aoff + m * 2048 + k * 1024); } while (0)
; #define PG8_MMA(ai, bj, At, Bt) do { __builtin_amdgcn_s_setprio(1); _Pragma("unroll") for (int m = 0; m < 4; ++m) _Pragma("unroll") for (int n = 0; n < 2; ++n) _Pragma("unroll") for (int k = 0; k < 2; ++k) \
;         acc[ai][bj][m][n] = __builtin_amdgcn_mfma_f32_16x16x32_bf16(Bt[n][k], At[m][k], acc[ai][bj][m][n], 0, 0, 0); __builtin_amdgcn_s_setprio(0); } while (0)
; #define PG8_WAIT_V(n) asm volatile("s_waitcnt vmcnt(" #n ")" ::: "memory")
; #define PG8_WAIT_L(n) asm volatile("s_waitcnt lgkmcnt(" #n ")" ::: "memory")
; #define PG8_BAR __builtin_amdgcn_s_barrier()
; #define PG8_SCHED __builtin_amdgcn_sched_barrier(0)
; template <class Epi, class Sched, bool ALIGN_EPI = false, bool SP2 = false>
; __device__ __forceinline__ void gemm_phase(PG8_LAS unsigned char* lds, const Gemm g, const Sched& S, const Epi& E, int tid_in) {
;     ...
;         for (int t = 0; t < nt; t += 2) {
;             const bool last = (t == nt - 2);
;     ...
;             PG8_LDA(At, 1, 1); PG8_STAGE(PG8_SB(1, 0), b3, voffB); PG8_STAGE(PG8_SB(1, 1), b3 + hstep, voffB); PG8_STAGE(PG8_SA(1, 0), a3, voffA);
;             PG8_WAIT_V(8); PG8_WAIT_L(0); PG8_BAR; PG8_MMA(1, 0, At, B0); PG8_MMA(1, 1, At, B1); PG8_BAR; PG8_SCHED;
	s_add_i32 s8, s63, s33
	v_lshl_add_u64 v[168:169], v[168:169], 0, s[90:91]
	s_mov_b32 m0, s8
	ds_read_b128 v[186:189], v147 offset:49152
	ds_read_b128 v[190:193], v147 offset:50176
	ds_read_b128 v[194:197], v147 offset:51200
	ds_read_b128 v[198:201], v147 offset:52224
	ds_read_b128 v[202:205], v147 offset:53248
	ds_read_b128 v[206:209], v147 offset:54272
	ds_read_b128 v[210:213], v147 offset:55296
	ds_read_b128 v[214:217], v147 offset:56320
	global_load_lds_dwordx4 v[168:169], off
	s_add_i32 m0, s8, 0x2000
	s_add_u32 s8, s28, 0x160080
	v_lshl_add_u64 v[168:169], v[218:219], 0, s[90:91]
	s_addc_u32 s9, s29, 0
	s_add_i32 s28, s55, s33
	global_load_lds_dwordx4 v[168:169], off
	v_lshl_add_u64 v[168:169], s[8:9], 0, v[0:1]
	s_mov_b32 m0, s28
	s_nop 0
	global_load_lds_dwordx4 v[168:169], off
	v_lshl_add_u64 v[168:169], s[8:9], 0, v[130:131]
	s_add_i32 m0, s28, 0x2000
	s_nop 0
	global_load_lds_dwordx4 v[168:169], off
	v_lshl_add_u64 v[168:169], v[220:221], 0, s[90:91]
	s_mov_b32 m0, s43
	s_nop 0
	global_load_lds_dwordx4 v[168:169], off
	v_lshl_add_u64 v[168:169], v[222:223], 0, s[90:91]
	s_mov_b32 m0, s44
	s_nop 0
	global_load_lds_dwordx4 v[168:169], off
	s_waitcnt vmcnt(8)
	s_waitcnt lgkmcnt(0)
	s_barrier
	s_setprio 1
	s_waitcnt lgkmcnt(0)
	v_mfma_f32_16x16x32_bf16 v[62:65], v[136:139], v[186:189], v[62:65]
	v_mfma_f32_16x16x32_bf16 v[58:61], v[148:151], v[186:189], v[58:61]
	v_mfma_f32_16x16x32_bf16 v[54:57], v[136:139], v[194:197], v[54:57]
	v_mfma_f32_16x16x32_bf16 v[50:53], v[148:151], v[194:197], v[50:53]
	v_mfma_f32_16x16x32_bf16 v[46:49], v[136:139], v[202:205], v[46:49]
	v_mfma_f32_16x16x32_bf16 v[42:45], v[148:151], v[202:205], v[42:45]
	v_mfma_f32_16x16x32_bf16 v[38:41], v[136:139], v[210:213], v[38:41]
	v_mfma_f32_16x16x32_bf16 v[34:37], v[148:151], v[210:213], v[34:37]
	v_mfma_f32_16x16x32_bf16 v[62:65], v[140:143], v[190:193], v[62:65]
	v_mfma_f32_16x16x32_bf16 v[58:61], v[152:155], v[190:193], v[58:61]
	v_mfma_f32_16x16x32_bf16 v[54:57], v[140:143], v[198:201], v[54:57]
	v_mfma_f32_16x16x32_bf16 v[50:53], v[152:155], v[198:201], v[50:53]
	v_mfma_f32_16x16x32_bf16 v[46:49], v[140:143], v[206:209], v[46:49]
	v_mfma_f32_16x16x32_bf16 v[42:45], v[152:155], v[206:209], v[42:45]
	v_mfma_f32_16x16x32_bf16 v[38:41], v[140:143], v[214:217], v[38:41]
	v_mfma_f32_16x16x32_bf16 v[34:37], v[152:155], v[214:217], v[34:37]
	s_setprio 0
	s_setprio 1
	v_mfma_f32_16x16x32_bf16 v[30:33], v[156:159], v[186:189], v[30:33]
	v_mfma_f32_16x16x32_bf16 v[26:29], v[164:167], v[186:189], v[26:29]
	v_mfma_f32_16x16x32_bf16 v[22:25], v[156:159], v[194:197], v[22:25]
	v_mfma_f32_16x16x32_bf16 v[18:21], v[164:167], v[194:197], v[18:21]
	v_mfma_f32_16x16x32_bf16 v[14:17], v[156:159], v[202:205], v[14:17]
	v_mfma_f32_16x16x32_bf16 v[10:13], v[164:167], v[202:205], v[10:13]
	v_mfma_f32_16x16x32_bf16 v[6:9], v[156:159], v[210:213], v[6:9]
	v_mfma_f32_16x16x32_bf16 v[2:5], v[164:167], v[210:213], v[2:5]
	v_mfma_f32_16x16x32_bf16 v[30:33], v[160:163], v[190:193], v[30:33]
	v_mfma_f32_16x16x32_bf16 v[26:29], v[182:185], v[190:193], v[26:29]
	v_mfma_f32_16x16x32_bf16 v[22:25], v[160:163], v[198:201], v[22:25]
	v_mfma_f32_16x16x32_bf16 v[18:21], v[182:185], v[198:201], v[18:21]
	v_mfma_f32_16x16x32_bf16 v[14:17], v[160:163], v[206:209], v[14:17]
	v_mfma_f32_16x16x32_bf16 v[10:13], v[182:185], v[206:209], v[10:13]
	v_mfma_f32_16x16x32_bf16 v[6:9], v[160:163], v[214:217], v[6:9]
	v_mfma_f32_16x16x32_bf16 v[2:5], v[182:185], v[214:217], v[2:5]
	s_setprio 0
	s_barrier
	s_add_u32 s76, s76, 0x100
	s_addc_u32 s79, s79, 0
	s_cmp_ge_u32 s82, s66
	s_mov_b64 s[8:9], s[26:27]
	s_mov_b32 s28, s82
	s_cbranch_scc0 .LBB0_352
	s_and_b64 vcc, exec, s[18:19]
	s_cbranch_vccz .LBB0_355
	s_barrier

; #define PG8_STAGE(bufoff, gbase, voff) do { _Pragma("unroll") for (int _i = 0; _i < 2; ++_i) \
;         __builtin_amdgcn_global_load_lds((const unsigned*)((const char*)(gbase) + (voff)[_i]), (PG8_LAS unsigned*)(lds + (bufoff) + ldsw + _i * 8192), 16, 0, 0); } while (0)
; #define PG8_LDA(dst, b, h) do { _Pragma("unroll") for (int m = 0; m < 4; ++m) _Pragma("unroll") for (int k = 0; k < 2; ++k) dst[m][k] = *(const PG8_LAS bf16x8*)(lds + PG8_SA(b, h) + aoff + m * 2048 + k * 1024); } while (0)
; #define PG8_LDB(dst, b, h) do { _Pragma("unroll") for (int n = 0; n < 2; ++n) _Pragma("unroll") for (int k = 0; k < 2; ++k) dst[n][k] = *(const PG8_LAS bf16x8*)(lds + PG8_SB(b, h) + boff + n * 2048 + k * 1024); } while (0)
; #define PG8_MMA(ai, bj, At, Bt) do { __builtin_amdgcn_s_setprio(1); _Pragma("unroll") for (int m = 0; m < 4; ++m) _Pragma("unroll") for (int n = 0; n < 2; ++n) _Pragma("unroll") for (int k = 0; k < 2; ++k) \
;         acc[ai][bj][m][n] = __builtin_amdgcn_mfma_f32_16x16x32_bf16(Bt[n][k], At[m][k], acc[ai][bj][m][n], 0, 0, 0); __builtin_amdgcn_s_setprio(0); } while (0)
; #define PG8_WAIT_V(n) asm volatile("s_waitcnt vmcnt(" #n ")" ::: "memory")
; #define PG8_WAIT_L(n) asm volatile("s_waitcnt lgkmcnt(" #n ")" ::: "memory")
; template <class Epi, class Sched, bool ALIGN_EPI = false, bool SP2 = false>
; __device__ __forceinline__ void gemm_phase(PG8_LAS unsigned char* lds, const Gemm g, const Sched& S, const Epi& E, int tid_in) {
;     ...
;             const bool last = (t == nt - 2);
;             const char* a1 = cA + (size_t)(t + 1) * kstep;
;             const char* a2 = last ? nA : cA + (size_t)(t + 2) * kstep; const char* b2 = last ? nB : cB + (size_t)(t + 2) * kstep;
;             const char* a3 = a2 + kstep; const char* b3 = b2 + kstep;
;             if (last && has_next) S.a_ready(nxt);
;             if constexpr (SP2) {
;             PG8_LDB(B0, 0, 0); PG8_LDB(B1, 0, 1); PG8_SCHED; PG8_LDA(At, 0, 0); PG8_STAGE(PG8_SA(1, 1), a1 + hstepA, voffA);
;             PG8_WAIT_V(8); PG8_WAIT_L(0); PG8_BAR; PG8_MMA(0, 0, At, B0); PG8_MMA(0, 1, At, B1); PG8_BAR; PG8_SCHED;
;             PG8_LDA(At, 0, 1); PG8_STAGE(PG8_SB(0, 0), b2, voffB); PG8_STAGE(PG8_SB(0, 1), b2 + hstep, voffB); PG8_STAGE(PG8_SA(0, 0), a2, voffA);
;             PG8_WAIT_V(8); PG8_WAIT_L(0); PG8_BAR; PG8_MMA(1, 0, At, B0); PG8_MMA(1, 1, At, B1); PG8_BAR; PG8_SCHED;
.LBB0_513:
	v_add_u32_e32 v150, s4, v157
	ds_read_b128 v[142:145], v150
	ds_read_b128 v[146:149], v150 offset:1024
	ds_read_b128 v[152:155], v150 offset:2048
	ds_read_b128 v[160:163], v150 offset:3072
	v_add_u32_e32 v150, s5, v157
	ds_read_b128 v[164:167], v150
	ds_read_b128 v[182:185], v150 offset:1024
	ds_read_b128 v[186:189], v150 offset:2048
	ds_read_b128 v[190:193], v150 offset:3072
	s_add_u32 s28, s14, 0xfff80080
	s_addc_u32 s29, s15, -1
	s_cmp_eq_u32 s23, 28
	s_cselect_b32 s31, s25, s29
	s_cselect_b32 s30, s24, s28
	s_cselect_b32 s29, s27, s21
	s_cselect_b32 s28, s26, s13
	v_lshl_add_u64 v[168:169], s[14:15], 0, v[138:139]
	s_add_i32 m0, s38, 0xc000
	ds_read_b128 v[194:197], v158
	ds_read_b128 v[198:201], v158 offset:1024
	ds_read_b128 v[202:205], v158 offset:2048
	ds_read_b128 v[206:209], v158 offset:3072
	ds_read_b128 v[210:213], v158 offset:4096
	ds_read_b128 v[214:217], v158 offset:5120
	ds_read_b128 v[218:221], v158 offset:6144
	ds_read_b128 v[222:225], v158 offset:7168
	global_load_lds_dwordx4 v[168:169], off
	v_lshl_add_u64 v[168:169], s[14:15], 0, v[140:141]
	s_add_i32 m0, s38, 0xe000
	s_nop 0
	global_load_lds_dwordx4 v[168:169], off
	s_waitcnt vmcnt(8)
	s_waitcnt lgkmcnt(0)
	s_barrier
	s_setprio 1
	s_waitcnt lgkmcnt(0)
	v_mfma_f32_16x16x32_bf16 v[126:129], v[142:145], v[194:197], v[126:129]
	v_mfma_f32_16x16x32_bf16 v[122:125], v[152:155], v[194:197], v[122:125]
	v_mfma_f32_16x16x32_bf16 v[110:113], v[142:145], v[202:205], v[110:113]
	v_mfma_f32_16x16x32_bf16 v[106:109], v[152:155], v[202:205], v[106:109]
	v_mfma_f32_16x16x32_bf16 v[94:97], v[142:145], v[210:213], v[94:97]
	v_mfma_f32_16x16x32_bf16 v[90:93], v[152:155], v[210:213], v[90:93]
	v_mfma_f32_16x16x32_bf16 v[78:81], v[142:145], v[218:221], v[78:81]
	v_mfma_f32_16x16x32_bf16 v[74:77], v[152:155], v[218:221], v[74:77]
	v_mfma_f32_16x16x32_bf16 v[126:129], v[146:149], v[198:201], v[126:129]
	v_mfma_f32_16x16x32_bf16 v[122:125], v[160:163], v[198:201], v[122:125]
	v_mfma_f32_16x16x32_bf16 v[110:113], v[146:149], v[206:209], v[110:113]
	v_mfma_f32_16x16x32_bf16 v[106:109], v[160:163], v[206:209], v[106:109]
	v_mfma_f32_16x16x32_bf16 v[94:97], v[146:149], v[214:217], v[94:97]
	v_mfma_f32_16x16x32_bf16 v[90:93], v[160:163], v[214:217], v[90:93]
	v_mfma_f32_16x16x32_bf16 v[78:81], v[146:149], v[222:225], v[78:81]
	v_mfma_f32_16x16x32_bf16 v[74:77], v[160:163], v[222:225], v[74:77]
	s_setprio 0
	s_setprio 1
	v_mfma_f32_16x16x32_bf16 v[118:121], v[164:167], v[194:197], v[118:121]
	v_mfma_f32_16x16x32_bf16 v[114:117], v[186:189], v[194:197], v[114:117]
	v_mfma_f32_16x16x32_bf16 v[102:105], v[164:167], v[202:205], v[102:105]
	v_mfma_f32_16x16x32_bf16 v[98:101], v[186:189], v[202:205], v[98:101]
	v_mfma_f32_16x16x32_bf16 v[86:89], v[164:167], v[210:213], v[86:89]
	v_mfma_f32_16x16x32_bf16 v[82:85], v[186:189], v[210:213], v[82:85]
	v_mfma_f32_16x16x32_bf16 v[70:73], v[164:167], v[218:221], v[70:73]
	v_mfma_f32_16x16x32_bf16 v[66:69], v[186:189], v[218:221], v[66:69]
	v_mfma_f32_16x16x32_bf16 v[118:121], v[182:185], v[198:201], v[118:121]
	v_mfma_f32_16x16x32_bf16 v[114:117], v[190:193], v[198:201], v[114:117]
	v_mfma_f32_16x16x32_bf16 v[102:105], v[182:185], v[206:209], v[102:105]
	v_mfma_f32_16x16x32_bf16 v[98:101], v[190:193], v[206:209], v[98:101]
	v_mfma_f32_16x16x32_bf16 v[86:89], v[182:185], v[214:217], v[86:89]
	v_mfma_f32_16x16x32_bf16 v[82:85], v[190:193], v[214:217], v[82:85]
	v_mfma_f32_16x16x32_bf16 v[70:73], v[182:185], v[222:225], v[70:73]
	v_mfma_f32_16x16x32_bf16 v[66:69], v[190:193], v[222:225], v[66:69]
	s_setprio 0
	s_barrier
	s_add_i32 s46, s4, s37
	v_lshl_add_u64 v[168:169], s[28:29], 0, v[0:1]
	s_mov_b32 m0, s46
	ds_read_b128 v[194:197], v158 offset:16384
	ds_read_b128 v[198:201], v158 offset:17408
	ds_read_b128 v[202:205], v158 offset:18432
	ds_read_b128 v[206:209], v158 offset:19456
	ds_read_b128 v[210:213], v158 offset:20480
	ds_read_b128 v[214:217], v158 offset:21504
	ds_read_b128 v[218:221], v158 offset:22528
	ds_read_b128 v[222:225], v158 offset:23552
	global_load_lds_dwordx4 v[168:169], off
	s_add_i32 m0, s46, 0x2000
	s_add_u32 s46, s28, 0x80000
	v_lshl_add_u64 v[226:227], s[28:29], 0, v[134:135]
	s_addc_u32 s47, s29, 0
	s_add_i32 s64, s5, s37
	global_load_lds_dwordx4 v[226:227], off
	v_lshl_add_u64 v[228:229], s[46:47], 0, v[0:1]
	s_mov_b32 m0, s64
	v_lshl_add_u64 v[240:241], s[30:31], 0, v[132:133]
	global_load_lds_dwordx4 v[228:229], off
	v_lshl_add_u64 v[228:229], s[46:47], 0, v[134:135]
	s_add_i32 m0, s64, 0x2000
	s_nop 0
	global_load_lds_dwordx4 v[228:229], off
	s_waitcnt vmcnt(6)
	s_waitcnt lgkmcnt(0)
	s_barrier
; #define PG8_STAGE(bufoff, gbase, voff) do { _Pragma("unroll") for (int _i = 0; _i < 2; ++_i) \
;         __builtin_amdgcn_global_load_lds((const unsigned*)((const char*)(gbase) + (voff)[_i]), (PG8_LAS unsigned*)(lds + (bufoff) + ldsw + _i * 8192), 16, 0, 0); } while (0)
; #define PG8_LDA(dst, b, h) do { _Pragma("unroll") for (int m = 0; m < 4; ++m) _Pragma("unroll") for (int k = 0; k < 2; ++k) dst[m][k] = *(const PG8_LAS bf16x8*)(lds + PG8_SA(b, h) + aoff + m * 2048 + k * 1024); } while (0)
; #define PG8_LDB(dst, b, h) do { _Pragma("unroll") for (int n = 0; n < 2; ++n) _Pragma("unroll") for (int k = 0; k < 2; ++k) dst[n][k] = *(const PG8_LAS bf16x8*)(lds + PG8_SB(b, h) + boff + n * 2048 + k * 1024); } while (0)
; #define PG8_MMA(ai, bj, At, Bt) do { __builtin_amdgcn_s_setprio(1); _Pragma("unroll") for (int m = 0; m < 4; ++m) _Pragma("unroll") for (int n = 0; n < 2; ++n) _Pragma("unroll") for (int k = 0; k < 2; ++k) \
;         acc[ai][bj][m][n] = __builtin_amdgcn_mfma_f32_16x16x32_bf16(Bt[n][k], At[m][k], acc[ai][bj][m][n], 0, 0, 0); __builtin_amdgcn_s_setprio(0); } while (0)
; #define PG8_WAIT_V(n) asm volatile("s_waitcnt vmcnt(" #n ")" ::: "memory")
; #define PG8_WAIT_L(n) asm volatile("s_waitcnt lgkmcnt(" #n ")" ::: "memory")
; #define PG8_BAR __builtin_amdgcn_s_barrier()
; #define PG8_SCHED __builtin_amdgcn_sched_barrier(0)
; template <class Epi, class Sched, bool ALIGN_EPI = false, bool SP2 = false>
; __device__ __forceinline__ void gemm_phase(PG8_LAS unsigned char* lds, const Gemm g, const Sched& S, const Epi& E, int tid_in) {
;     ...
;             PG8_LDA(At, 0, 1); PG8_STAGE(PG8_SB(0, 0), b2, voffB); PG8_STAGE(PG8_SB(0, 1), b2 + hstep, voffB); PG8_STAGE(PG8_SA(0, 0), a2, voffA);
;             PG8_WAIT_V(8); PG8_WAIT_L(0); PG8_BAR; PG8_MMA(1, 0, At, B0); PG8_MMA(1, 1, At, B1); PG8_BAR; PG8_SCHED;
;             PG8_LDB(B0, 1, 0); PG8_LDB(B1, 1, 1); PG8_SCHED; PG8_LDA(At, 1, 0); PG8_STAGE(PG8_SA(0, 1), a2 + hstepA, voffA);
;             PG8_WAIT_V(8); PG8_WAIT_L(0); PG8_BAR; PG8_MMA(0, 0, At, B0); PG8_MMA(0, 1, At, B1); PG8_BAR; PG8_SCHED;
	s_setprio 1
	s_waitcnt lgkmcnt(0)
	v_mfma_f32_16x16x32_bf16 v[62:65], v[142:145], v[194:197], v[62:65]
	v_mfma_f32_16x16x32_bf16 v[58:61], v[152:155], v[194:197], v[58:61]
	v_mfma_f32_16x16x32_bf16 v[46:49], v[142:145], v[202:205], v[46:49]
	v_mfma_f32_16x16x32_bf16 v[42:45], v[152:155], v[202:205], v[42:45]
	v_mfma_f32_16x16x32_bf16 v[30:33], v[142:145], v[210:213], v[30:33]
	v_mfma_f32_16x16x32_bf16 v[26:29], v[152:155], v[210:213], v[26:29]
	v_mfma_f32_16x16x32_bf16 v[14:17], v[142:145], v[218:221], v[14:17]
	v_mfma_f32_16x16x32_bf16 v[10:13], v[152:155], v[218:221], v[10:13]
	v_mfma_f32_16x16x32_bf16 v[62:65], v[146:149], v[198:201], v[62:65]
	v_mfma_f32_16x16x32_bf16 v[58:61], v[160:163], v[198:201], v[58:61]
	v_mfma_f32_16x16x32_bf16 v[46:49], v[146:149], v[206:209], v[46:49]
	v_mfma_f32_16x16x32_bf16 v[42:45], v[160:163], v[206:209], v[42:45]
	v_mfma_f32_16x16x32_bf16 v[30:33], v[146:149], v[214:217], v[30:33]
	v_mfma_f32_16x16x32_bf16 v[26:29], v[160:163], v[214:217], v[26:29]
	v_mfma_f32_16x16x32_bf16 v[14:17], v[146:149], v[222:225], v[14:17]
	v_mfma_f32_16x16x32_bf16 v[10:13], v[160:163], v[222:225], v[10:13]
	s_setprio 0
	s_setprio 1
	v_mfma_f32_16x16x32_bf16 v[54:57], v[164:167], v[194:197], v[54:57]
	v_mfma_f32_16x16x32_bf16 v[50:53], v[186:189], v[194:197], v[50:53]
	v_mfma_f32_16x16x32_bf16 v[38:41], v[164:167], v[202:205], v[38:41]
	v_mfma_f32_16x16x32_bf16 v[34:37], v[186:189], v[202:205], v[34:37]
	v_mfma_f32_16x16x32_bf16 v[22:25], v[164:167], v[210:213], v[22:25]
	v_mfma_f32_16x16x32_bf16 v[18:21], v[186:189], v[210:213], v[18:21]
	v_mfma_f32_16x16x32_bf16 v[6:9], v[164:167], v[218:221], v[6:9]
	v_mfma_f32_16x16x32_bf16 v[2:5], v[186:189], v[218:221], v[2:5]
	v_mfma_f32_16x16x32_bf16 v[54:57], v[182:185], v[198:201], v[54:57]
	v_mfma_f32_16x16x32_bf16 v[50:53], v[190:193], v[198:201], v[50:53]
	v_mfma_f32_16x16x32_bf16 v[38:41], v[182:185], v[206:209], v[38:41]
	v_mfma_f32_16x16x32_bf16 v[34:37], v[190:193], v[206:209], v[34:37]
	v_mfma_f32_16x16x32_bf16 v[22:25], v[182:185], v[214:217], v[22:25]
	v_mfma_f32_16x16x32_bf16 v[18:21], v[190:193], v[214:217], v[18:21]
	v_mfma_f32_16x16x32_bf16 v[6:9], v[182:185], v[222:225], v[6:9]
	v_mfma_f32_16x16x32_bf16 v[2:5], v[190:193], v[222:225], v[2:5]
	s_setprio 0
	s_barrier
	v_lshl_add_u64 v[228:229], s[30:31], 0, v[130:131]
	s_mov_b32 m0, s38
	s_nop 0
	global_load_lds_dwordx4 v[228:229], off
	s_mov_b32 m0, s39
	s_nop 0
	global_load_lds_dwordx4 v[240:241], off
	v_add_u32_e32 v150, s63, v157
	ds_read_b128 v[142:145], v150
	ds_read_b128 v[146:149], v150 offset:1024
	ds_read_b128 v[152:155], v150 offset:2048
	ds_read_b128 v[160:163], v150 offset:3072
	v_add_u32_e32 v150, s55, v157
	ds_read_b128 v[164:167], v150
	ds_read_b128 v[182:185], v150 offset:1024
	ds_read_b128 v[186:189], v150 offset:2048
	ds_read_b128 v[190:193], v150 offset:3072
	s_add_u32 s30, s30, 0x80000
	s_addc_u32 s31, s31, 0
	s_mov_b32 m0, s40
	v_lshl_add_u64 v[242:243], s[30:31], 0, v[130:131]
	ds_read_b128 v[194:197], v158 offset:32768
	ds_read_b128 v[198:201], v158 offset:33792
	ds_read_b128 v[202:205], v158 offset:34816
	ds_read_b128 v[206:209], v158 offset:35840
	ds_read_b128 v[210:213], v158 offset:36864
	ds_read_b128 v[214:217], v158 offset:37888
	ds_read_b128 v[218:221], v158 offset:38912
	ds_read_b128 v[222:225], v158 offset:39936
	global_load_lds_dwordx4 v[242:243], off
	v_lshl_add_u64 v[242:243], s[30:31], 0, v[132:133]
	s_mov_b32 m0, s41
	s_nop 0
	global_load_lds_dwordx4 v[242:243], off
	s_waitcnt vmcnt(8)
	s_waitcnt lgkmcnt(0)
	s_barrier
	s_setprio 1
	s_waitcnt lgkmcnt(0)
	v_mfma_f32_16x16x32_bf16 v[126:129], v[142:145], v[194:197], v[126:129]
	v_mfma_f32_16x16x32_bf16 v[122:125], v[152:155], v[194:197], v[122:125]
	v_mfma_f32_16x16x32_bf16 v[110:113], v[142:145], v[202:205], v[110:113]
	v_mfma_f32_16x16x32_bf16 v[106:109], v[152:155], v[202:205], v[106:109]
	v_mfma_f32_16x16x32_bf16 v[94:97], v[142:145], v[210:213], v[94:97]
	v_mfma_f32_16x16x32_bf16 v[90:93], v[152:155], v[210:213], v[90:93]
	v_mfma_f32_16x16x32_bf16 v[78:81], v[142:145], v[218:221], v[78:81]
	v_mfma_f32_16x16x32_bf16 v[74:77], v[152:155], v[218:221], v[74:77]
	v_mfma_f32_16x16x32_bf16 v[126:129], v[146:149], v[198:201], v[126:129]
	v_mfma_f32_16x16x32_bf16 v[122:125], v[160:163], v[198:201], v[122:125]
	v_mfma_f32_16x16x32_bf16 v[110:113], v[146:149], v[206:209], v[110:113]
	v_mfma_f32_16x16x32_bf16 v[106:109], v[160:163], v[206:209], v[106:109]
	v_mfma_f32_16x16x32_bf16 v[94:97], v[146:149], v[214:217], v[94:97]
	v_mfma_f32_16x16x32_bf16 v[90:93], v[160:163], v[214:217], v[90:93]
	v_mfma_f32_16x16x32_bf16 v[78:81], v[146:149], v[222:225], v[78:81]
	v_mfma_f32_16x16x32_bf16 v[74:77], v[160:163], v[222:225], v[74:77]
	s_setprio 0
	s_setprio 1
	v_mfma_f32_16x16x32_bf16 v[118:121], v[164:167], v[194:197], v[118:121]
	v_mfma_f32_16x16x32_bf16 v[114:117], v[186:189], v[194:197], v[114:117]
	v_mfma_f32_16x16x32_bf16 v[102:105], v[164:167], v[202:205], v[102:105]
	v_mfma_f32_16x16x32_bf16 v[98:101], v[186:189], v[202:205], v[98:101]
	v_mfma_f32_16x16x32_bf16 v[86:89], v[164:167], v[210:213], v[86:89]
	v_mfma_f32_16x16x32_bf16 v[82:85], v[186:189], v[210:213], v[82:85]
	v_mfma_f32_16x16x32_bf16 v[70:73], v[164:167], v[218:221], v[70:73]
	v_mfma_f32_16x16x32_bf16 v[66:69], v[186:189], v[218:221], v[66:69]
	v_mfma_f32_16x16x32_bf16 v[118:121], v[182:185], v[198:201], v[118:121]
	v_mfma_f32_16x16x32_bf16 v[114:117], v[190:193], v[198:201], v[114:117]
	v_mfma_f32_16x16x32_bf16 v[102:105], v[182:185], v[206:209], v[102:105]
	v_mfma_f32_16x16x32_bf16 v[98:101], v[190:193], v[206:209], v[98:101]
	v_mfma_f32_16x16x32_bf16 v[86:89], v[182:185], v[214:217], v[86:89]
	v_mfma_f32_16x16x32_bf16 v[82:85], v[190:193], v[214:217], v[82:85]
	v_mfma_f32_16x16x32_bf16 v[70:73], v[182:185], v[222:225], v[70:73]
	v_mfma_f32_16x16x32_bf16 v[66:69], v[190:193], v[222:225], v[66:69]
	s_setprio 0
	s_barrier
; #define PG8_STAGE(bufoff, gbase, voff) do { _Pragma("unroll") for (int _i = 0; _i < 2; ++_i) \
;         __builtin_amdgcn_global_load_lds((const unsigned*)((const char*)(gbase) + (voff)[_i]), (PG8_LAS unsigned*)(lds + (bufoff) + ldsw + _i * 8192), 16, 0, 0); } while (0)
; #define PG8_LDA(dst, b, h) do { _Pragma("unroll") for (int m = 0; m < 4; ++m) _Pragma("unroll") for (int k = 0; k < 2; ++k) dst[m][k] = *(const PG8_LAS bf16x8*)(lds + PG8_SA(b, h) + aoff + m * 2048 + k * 1024); } while (0)
; #define PG8_MMA(ai, bj, At, Bt) do { __builtin_amdgcn_s_setprio(1); _Pragma("unroll") for (int m = 0; m < 4; ++m) _Pragma("unroll") for (int n = 0; n < 2; ++n) _Pragma("unroll") for (int k = 0; k < 2; ++k) \
;         acc[ai][bj][m][n] = __builtin_amdgcn_mfma_f32_16x16x32_bf16(Bt[n][k], At[m][k], acc[ai][bj][m][n], 0, 0, 0); __builtin_amdgcn_s_setprio(0); } while (0)
; #define PG8_WAIT_V(n) asm volatile("s_waitcnt vmcnt(" #n ")" ::: "memory")
; #define PG8_WAIT_L(n) asm volatile("s_waitcnt lgkmcnt(" #n ")" ::: "memory")
; #define PG8_BAR __builtin_amdgcn_s_barrier()
; #define PG8_SCHED __builtin_amdgcn_sched_barrier(0)
; template <class Epi, class Sched, bool ALIGN_EPI = false, bool SP2 = false>
; __device__ __forceinline__ void gemm_phase(PG8_LAS unsigned char* lds, const Gemm g, const Sched& S, const Epi& E, int tid_in) {
;     ...
;         for (int t = 0; t < nt; t += 2) {
;             const bool last = (t == nt - 2);
;             const char* a1 = cA + (size_t)(t + 1) * kstep;
;             const char* a2 = last ? nA : cA + (size_t)(t + 2) * kstep; const char* b2 = last ? nB : cB + (size_t)(t + 2) * kstep;
;     ...
;             PG8_LDA(At, 1, 1); PG8_STAGE(PG8_SB(1, 0), b3, voffB); PG8_STAGE(PG8_SB(1, 1), b3 + hstep, voffB); PG8_STAGE(PG8_SA(1, 0), a3, voffA);
;             PG8_WAIT_V(8); PG8_WAIT_L(0); PG8_BAR; PG8_MMA(1, 0, At, B0); PG8_MMA(1, 1, At, B1); PG8_BAR; PG8_SCHED;
	s_add_i32 s30, s63, s37
	v_lshl_add_u64 v[168:169], v[168:169], 0, s[90:91]
	s_mov_b32 m0, s30
	ds_read_b128 v[194:197], v158 offset:49152
	ds_read_b128 v[198:201], v158 offset:50176
	ds_read_b128 v[202:205], v158 offset:51200
	ds_read_b128 v[206:209], v158 offset:52224
	ds_read_b128 v[210:213], v158 offset:53248
	ds_read_b128 v[214:217], v158 offset:54272
	ds_read_b128 v[218:221], v158 offset:55296
	ds_read_b128 v[222:225], v158 offset:56320
	global_load_lds_dwordx4 v[168:169], off
	s_add_i32 m0, s30, 0x2000
	s_add_u32 s28, s28, 0x80080
	v_lshl_add_u64 v[168:169], v[226:227], 0, s[90:91]
	s_addc_u32 s29, s29, 0
	s_add_i32 s30, s55, s37
	global_load_lds_dwordx4 v[168:169], off
	v_lshl_add_u64 v[168:169], s[28:29], 0, v[0:1]
	s_mov_b32 m0, s30
	s_nop 0
	global_load_lds_dwordx4 v[168:169], off
	v_lshl_add_u64 v[168:169], s[28:29], 0, v[134:135]
	s_add_i32 m0, s30, 0x2000
	s_nop 0
	global_load_lds_dwordx4 v[168:169], off
	v_lshl_add_u64 v[168:169], v[228:229], 0, s[90:91]
	s_mov_b32 m0, s45
	s_nop 0
	global_load_lds_dwordx4 v[168:169], off
	v_lshl_add_u64 v[168:169], v[240:241], 0, s[90:91]
	s_mov_b32 m0, s48
	s_nop 0
	global_load_lds_dwordx4 v[168:169], off
	s_waitcnt vmcnt(8)
	s_waitcnt lgkmcnt(0)
	s_barrier
	s_setprio 1
	s_waitcnt lgkmcnt(0)
	v_mfma_f32_16x16x32_bf16 v[62:65], v[142:145], v[194:197], v[62:65]
	v_mfma_f32_16x16x32_bf16 v[58:61], v[152:155], v[194:197], v[58:61]
	v_mfma_f32_16x16x32_bf16 v[46:49], v[142:145], v[202:205], v[46:49]
	v_mfma_f32_16x16x32_bf16 v[42:45], v[152:155], v[202:205], v[42:45]
	v_mfma_f32_16x16x32_bf16 v[30:33], v[142:145], v[210:213], v[30:33]
	v_mfma_f32_16x16x32_bf16 v[26:29], v[152:155], v[210:213], v[26:29]
	v_mfma_f32_16x16x32_bf16 v[14:17], v[142:145], v[218:221], v[14:17]
	v_mfma_f32_16x16x32_bf16 v[10:13], v[152:155], v[218:221], v[10:13]
	v_mfma_f32_16x16x32_bf16 v[62:65], v[146:149], v[198:201], v[62:65]
	v_mfma_f32_16x16x32_bf16 v[58:61], v[160:163], v[198:201], v[58:61]
	v_mfma_f32_16x16x32_bf16 v[46:49], v[146:149], v[206:209], v[46:49]
	v_mfma_f32_16x16x32_bf16 v[42:45], v[160:163], v[206:209], v[42:45]
	v_mfma_f32_16x16x32_bf16 v[30:33], v[146:149], v[214:217], v[30:33]
	v_mfma_f32_16x16x32_bf16 v[26:29], v[160:163], v[214:217], v[26:29]
	v_mfma_f32_16x16x32_bf16 v[14:17], v[146:149], v[222:225], v[14:17]
	v_mfma_f32_16x16x32_bf16 v[10:13], v[160:163], v[222:225], v[10:13]
	s_setprio 0
	s_setprio 1
	v_mfma_f32_16x16x32_bf16 v[54:57], v[164:167], v[194:197], v[54:57]
	v_mfma_f32_16x16x32_bf16 v[50:53], v[186:189], v[194:197], v[50:53]
	v_mfma_f32_16x16x32_bf16 v[38:41], v[164:167], v[202:205], v[38:41]
	v_mfma_f32_16x16x32_bf16 v[34:37], v[186:189], v[202:205], v[34:37]
	v_mfma_f32_16x16x32_bf16 v[22:25], v[164:167], v[210:213], v[22:25]
	v_mfma_f32_16x16x32_bf16 v[18:21], v[186:189], v[210:213], v[18:21]
	v_mfma_f32_16x16x32_bf16 v[6:9], v[164:167], v[218:221], v[6:9]
	v_mfma_f32_16x16x32_bf16 v[2:5], v[186:189], v[218:221], v[2:5]
	v_mfma_f32_16x16x32_bf16 v[54:57], v[182:185], v[198:201], v[54:57]
	v_mfma_f32_16x16x32_bf16 v[50:53], v[190:193], v[198:201], v[50:53]
	v_mfma_f32_16x16x32_bf16 v[38:41], v[182:185], v[206:209], v[38:41]
	v_mfma_f32_16x16x32_bf16 v[34:37], v[190:193], v[206:209], v[34:37]
	v_mfma_f32_16x16x32_bf16 v[22:25], v[182:185], v[214:217], v[22:25]
	v_mfma_f32_16x16x32_bf16 v[18:21], v[190:193], v[214:217], v[18:21]
	v_mfma_f32_16x16x32_bf16 v[6:9], v[182:185], v[222:225], v[6:9]
	v_mfma_f32_16x16x32_bf16 v[2:5], v[190:193], v[222:225], v[2:5]
	s_setprio 0
	s_barrier
	s_add_i32 s23, s23, 2
	s_add_u32 s14, s14, 0x100
	s_addc_u32 s15, s15, 0
	s_add_u32 s13, s13, 0x100
	s_addc_u32 s21, s21, 0
	s_cmp_gt_u32 s23, 29
	s_cbranch_scc0 .LBB0_513
	s_and_b64 vcc, exec, s[18:19]
	s_cbranch_vccz .LBB0_516
	s_barrier

; #define PG8_STAGE(bufoff, gbase, voff) do { _Pragma("unroll") for (int _i = 0; _i < 2; ++_i) \
;         __builtin_amdgcn_global_load_lds((const unsigned*)((const char*)(gbase) + (voff)[_i]), (PG8_LAS unsigned*)(lds + (bufoff) + ldsw + _i * 8192), 16, 0, 0); } while (0)
; #define PG8_LDA(dst, b, h) do { _Pragma("unroll") for (int m = 0; m < 4; ++m) _Pragma("unroll") for (int k = 0; k < 2; ++k) dst[m][k] = *(const PG8_LAS bf16x8*)(lds + PG8_SA(b, h) + aoff + m * 2048 + k * 1024); } while (0)
; #define PG8_LDB(dst, b, h) do { _Pragma("unroll") for (int n = 0; n < 2; ++n) _Pragma("unroll") for (int k = 0; k < 2; ++k) dst[n][k] = *(const PG8_LAS bf16x8*)(lds + PG8_SB(b, h) + boff + n * 2048 + k * 1024); } while (0)
; #define PG8_MMA(ai, bj, At, Bt) do { __builtin_amdgcn_s_setprio(1); _Pragma("unroll") for (int m = 0; m < 4; ++m) _Pragma("unroll") for (int n = 0; n < 2; ++n) _Pragma("unroll") for (int k = 0; k < 2; ++k) \
;         acc[ai][bj][m][n] = __builtin_amdgcn_mfma_f32_16x16x32_bf16(Bt[n][k], At[m][k], acc[ai][bj][m][n], 0, 0, 0); __builtin_amdgcn_s_setprio(0); } while (0)
; #define PG8_WAIT_V(n) asm volatile("s_waitcnt vmcnt(" #n ")" ::: "memory")
; #define PG8_WAIT_L(n) asm volatile("s_waitcnt lgkmcnt(" #n ")" ::: "memory")
; #define PG8_BAR __builtin_amdgcn_s_barrier()
; #define PG8_SCHED __builtin_amdgcn_sched_barrier(0)
; template <class Epi, class Sched, bool ALIGN_EPI = false, bool SP2 = false>
; __device__ __forceinline__ void gemm_phase(PG8_LAS unsigned char* lds, const Gemm g, const Sched& S, const Epi& E, int tid_in) {
;     ...
;         for (int t = 0; t < nt; t += 2) {
;             const bool last = (t == nt - 2);
;             const char* a1 = cA + (size_t)(t + 1) * kstep;
;             const char* a2 = last ? nA : cA + (size_t)(t + 2) * kstep; const char* b2 = last ? nB : cB + (size_t)(t + 2) * kstep;
;             const char* a3 = a2 + kstep; const char* b3 = b2 + kstep;
;             if (last && has_next) S.a_ready(nxt);
;             if constexpr (SP2) {
;             PG8_LDB(B0, 0, 0); PG8_LDB(B1, 0, 1); PG8_SCHED; PG8_LDA(At, 0, 0); PG8_STAGE(PG8_SA(1, 1), a1 + hstepA, voffA);
;             PG8_WAIT_V(8); PG8_WAIT_L(0); PG8_BAR; PG8_MMA(0, 0, At, B0); PG8_MMA(0, 1, At, B1); PG8_BAR; PG8_SCHED;
;             PG8_LDA(At, 0, 1); PG8_STAGE(PG8_SB(0, 0), b2, voffB); PG8_STAGE(PG8_SB(0, 1), b2 + hstep, voffB); PG8_STAGE(PG8_SA(0, 0), a2, voffA);
.LBB0_627:
	v_add_u32_e32 v140, s4, v145
	ds_read_b128 v[148:151], v140
	ds_read_b128 v[152:155], v140 offset:1024
	ds_read_b128 v[156:159], v140 offset:2048
	ds_read_b128 v[160:163], v140 offset:3072
	v_add_u32_e32 v140, s5, v145
	ds_read_b128 v[164:167], v140
	ds_read_b128 v[182:185], v140 offset:1024
	ds_read_b128 v[186:189], v140 offset:2048
	ds_read_b128 v[190:193], v140 offset:3072
	s_add_u32 s22, s20, 0x100
	s_addc_u32 s23, s21, 0
	s_cmp_eq_u32 s48, 4
	s_cselect_b32 s27, s17, s23
	s_cselect_b32 s26, s16, s22
	s_cselect_b32 s25, s19, s15
	s_cselect_b32 s24, s18, s0
	v_lshl_add_u64 v[168:169], s[20:21], 0, v[136:137]
	s_add_i32 m0, s34, 0xc000
	ds_read_b128 v[194:197], v147
	ds_read_b128 v[198:201], v147 offset:1024
	ds_read_b128 v[202:205], v147 offset:2048
	ds_read_b128 v[206:209], v147 offset:3072
	ds_read_b128 v[210:213], v147 offset:4096
	ds_read_b128 v[214:217], v147 offset:5120
	ds_read_b128 v[218:221], v147 offset:6144
	ds_read_b128 v[222:225], v147 offset:7168
	global_load_lds_dwordx4 v[168:169], off
	v_lshl_add_u64 v[168:169], s[20:21], 0, v[138:139]
	s_add_i32 m0, s34, 0xe000
	s_nop 0
	global_load_lds_dwordx4 v[168:169], off
	s_waitcnt vmcnt(8)
	s_waitcnt lgkmcnt(0)
	s_barrier
	s_setprio 1
	s_waitcnt lgkmcnt(0)
	v_mfma_f32_16x16x32_bf16 v[126:129], v[148:151], v[194:197], v[126:129]
	v_mfma_f32_16x16x32_bf16 v[122:125], v[156:159], v[194:197], v[122:125]
	v_mfma_f32_16x16x32_bf16 v[114:117], v[148:151], v[202:205], v[114:117]
	v_mfma_f32_16x16x32_bf16 v[106:109], v[156:159], v[202:205], v[106:109]
	v_mfma_f32_16x16x32_bf16 v[98:101], v[148:151], v[210:213], v[98:101]
	v_mfma_f32_16x16x32_bf16 v[90:93], v[156:159], v[210:213], v[90:93]
	v_mfma_f32_16x16x32_bf16 v[82:85], v[148:151], v[218:221], v[82:85]
	v_mfma_f32_16x16x32_bf16 v[74:77], v[156:159], v[218:221], v[74:77]
	v_mfma_f32_16x16x32_bf16 v[126:129], v[152:155], v[198:201], v[126:129]
	v_mfma_f32_16x16x32_bf16 v[122:125], v[160:163], v[198:201], v[122:125]
	v_mfma_f32_16x16x32_bf16 v[114:117], v[152:155], v[206:209], v[114:117]
	v_mfma_f32_16x16x32_bf16 v[106:109], v[160:163], v[206:209], v[106:109]
	v_mfma_f32_16x16x32_bf16 v[98:101], v[152:155], v[214:217], v[98:101]
	v_mfma_f32_16x16x32_bf16 v[90:93], v[160:163], v[214:217], v[90:93]
	v_mfma_f32_16x16x32_bf16 v[82:85], v[152:155], v[222:225], v[82:85]
	v_mfma_f32_16x16x32_bf16 v[74:77], v[160:163], v[222:225], v[74:77]
	s_setprio 0
	s_setprio 1
	v_mfma_f32_16x16x32_bf16 v[118:121], v[164:167], v[194:197], v[118:121]
	v_mfma_f32_16x16x32_bf16 v[110:113], v[186:189], v[194:197], v[110:113]
	v_mfma_f32_16x16x32_bf16 v[102:105], v[164:167], v[202:205], v[102:105]
	v_mfma_f32_16x16x32_bf16 v[94:97], v[186:189], v[202:205], v[94:97]
	v_mfma_f32_16x16x32_bf16 v[86:89], v[164:167], v[210:213], v[86:89]
	v_mfma_f32_16x16x32_bf16 v[78:81], v[186:189], v[210:213], v[78:81]
	v_mfma_f32_16x16x32_bf16 v[70:73], v[164:167], v[218:221], v[70:73]
	v_mfma_f32_16x16x32_bf16 v[66:69], v[186:189], v[218:221], v[66:69]
	v_mfma_f32_16x16x32_bf16 v[118:121], v[182:185], v[198:201], v[118:121]
	v_mfma_f32_16x16x32_bf16 v[110:113], v[190:193], v[198:201], v[110:113]
	v_mfma_f32_16x16x32_bf16 v[102:105], v[182:185], v[206:209], v[102:105]
	v_mfma_f32_16x16x32_bf16 v[94:97], v[190:193], v[206:209], v[94:97]
	v_mfma_f32_16x16x32_bf16 v[86:89], v[182:185], v[214:217], v[86:89]
	v_mfma_f32_16x16x32_bf16 v[78:81], v[190:193], v[214:217], v[78:81]
	v_mfma_f32_16x16x32_bf16 v[70:73], v[182:185], v[222:225], v[70:73]
	v_mfma_f32_16x16x32_bf16 v[66:69], v[190:193], v[222:225], v[66:69]
	s_setprio 0
	s_barrier
	s_add_i32 s20, s4, s33
	v_lshl_add_u64 v[168:169], s[24:25], 0, v[0:1]
	s_mov_b32 m0, s20
	ds_read_b128 v[194:197], v147 offset:16384
	ds_read_b128 v[198:201], v147 offset:17408
	ds_read_b128 v[202:205], v147 offset:18432
	ds_read_b128 v[206:209], v147 offset:19456
	ds_read_b128 v[210:213], v147 offset:20480
	ds_read_b128 v[214:217], v147 offset:21504
	ds_read_b128 v[218:221], v147 offset:22528
	ds_read_b128 v[222:225], v147 offset:23552
	global_load_lds_dwordx4 v[168:169], off
	s_add_i32 m0, s20, 0x2000
	s_add_u32 s20, s24, 0x20000
	v_lshl_add_u64 v[226:227], s[24:25], 0, v[134:135]
	s_addc_u32 s21, s25, 0
	s_add_i32 s49, s5, s33
	global_load_lds_dwordx4 v[226:227], off
	v_lshl_add_u64 v[228:229], s[20:21], 0, v[0:1]
	s_mov_b32 m0, s49
	v_lshl_add_u64 v[240:241], s[26:27], 0, v[132:133]
	global_load_lds_dwordx4 v[228:229], off
	v_lshl_add_u64 v[228:229], s[20:21], 0, v[134:135]
	s_add_i32 m0, s49, 0x2000
	s_nop 0
	global_load_lds_dwordx4 v[228:229], off
	s_waitcnt vmcnt(6)
	s_waitcnt lgkmcnt(0)
	s_barrier
; #define PG8_STAGE(bufoff, gbase, voff) do { _Pragma("unroll") for (int _i = 0; _i < 2; ++_i) \
;         __builtin_amdgcn_global_load_lds((const unsigned*)((const char*)(gbase) + (voff)[_i]), (PG8_LAS unsigned*)(lds + (bufoff) + ldsw + _i * 8192), 16, 0, 0); } while (0)
; #define PG8_LDA(dst, b, h) do { _Pragma("unroll") for (int m = 0; m < 4; ++m) _Pragma("unroll") for (int k = 0; k < 2; ++k) dst[m][k] = *(const PG8_LAS bf16x8*)(lds + PG8_SA(b, h) + aoff + m * 2048 + k * 1024); } while (0)
; #define PG8_LDB(dst, b, h) do { _Pragma("unroll") for (int n = 0; n < 2; ++n) _Pragma("unroll") for (int k = 0; k < 2; ++k) dst[n][k] = *(const PG8_LAS bf16x8*)(lds + PG8_SB(b, h) + boff + n * 2048 + k * 1024); } while (0)
; #define PG8_MMA(ai, bj, At, Bt) do { __builtin_amdgcn_s_setprio(1); _Pragma("unroll") for (int m = 0; m < 4; ++m) _Pragma("unroll") for (int n = 0; n < 2; ++n) _Pragma("unroll") for (int k = 0; k < 2; ++k) \
;         acc[ai][bj][m][n] = __builtin_amdgcn_mfma_f32_16x16x32_bf16(Bt[n][k], At[m][k], acc[ai][bj][m][n], 0, 0, 0); __builtin_amdgcn_s_setprio(0); } while (0)
; #define PG8_WAIT_V(n) asm volatile("s_waitcnt vmcnt(" #n ")" ::: "memory")
; #define PG8_WAIT_L(n) asm volatile("s_waitcnt lgkmcnt(" #n ")" ::: "memory")
; #define PG8_BAR __builtin_amdgcn_s_barrier()
; #define PG8_SCHED __builtin_amdgcn_sched_barrier(0)
; template <class Epi, class Sched, bool ALIGN_EPI = false, bool SP2 = false>
; __device__ __forceinline__ void gemm_phase(PG8_LAS unsigned char* lds, const Gemm g, const Sched& S, const Epi& E, int tid_in) {
;     ...
;             PG8_LDA(At, 0, 1); PG8_STAGE(PG8_SB(0, 0), b2, voffB); PG8_STAGE(PG8_SB(0, 1), b2 + hstep, voffB); PG8_STAGE(PG8_SA(0, 0), a2, voffA);
;             PG8_WAIT_V(8); PG8_WAIT_L(0); PG8_BAR; PG8_MMA(1, 0, At, B0); PG8_MMA(1, 1, At, B1); PG8_BAR; PG8_SCHED;
;             PG8_LDB(B0, 1, 0); PG8_LDB(B1, 1, 1); PG8_SCHED; PG8_LDA(At, 1, 0); PG8_STAGE(PG8_SA(0, 1), a2 + hstepA, voffA);
;             PG8_WAIT_V(8); PG8_WAIT_L(0); PG8_BAR; PG8_MMA(0, 0, At, B0); PG8_MMA(0, 1, At, B1); PG8_BAR; PG8_SCHED;
	s_setprio 1
	s_waitcnt lgkmcnt(0)
	v_mfma_f32_16x16x32_bf16 v[62:65], v[148:151], v[194:197], v[62:65]
	v_mfma_f32_16x16x32_bf16 v[58:61], v[156:159], v[194:197], v[58:61]
	v_mfma_f32_16x16x32_bf16 v[50:53], v[148:151], v[202:205], v[50:53]
	v_mfma_f32_16x16x32_bf16 v[42:45], v[156:159], v[202:205], v[42:45]
	v_mfma_f32_16x16x32_bf16 v[34:37], v[148:151], v[210:213], v[34:37]
	v_mfma_f32_16x16x32_bf16 v[26:29], v[156:159], v[210:213], v[26:29]
	v_mfma_f32_16x16x32_bf16 v[18:21], v[148:151], v[218:221], v[18:21]
	v_mfma_f32_16x16x32_bf16 v[10:13], v[156:159], v[218:221], v[10:13]
	v_mfma_f32_16x16x32_bf16 v[62:65], v[152:155], v[198:201], v[62:65]
	v_mfma_f32_16x16x32_bf16 v[58:61], v[160:163], v[198:201], v[58:61]
	v_mfma_f32_16x16x32_bf16 v[50:53], v[152:155], v[206:209], v[50:53]
	v_mfma_f32_16x16x32_bf16 v[42:45], v[160:163], v[206:209], v[42:45]
	v_mfma_f32_16x16x32_bf16 v[34:37], v[152:155], v[214:217], v[34:37]
	v_mfma_f32_16x16x32_bf16 v[26:29], v[160:163], v[214:217], v[26:29]
	v_mfma_f32_16x16x32_bf16 v[18:21], v[152:155], v[222:225], v[18:21]
	v_mfma_f32_16x16x32_bf16 v[10:13], v[160:163], v[222:225], v[10:13]
	s_setprio 0
	s_setprio 1
	v_mfma_f32_16x16x32_bf16 v[54:57], v[164:167], v[194:197], v[54:57]
	v_mfma_f32_16x16x32_bf16 v[46:49], v[186:189], v[194:197], v[46:49]
	v_mfma_f32_16x16x32_bf16 v[38:41], v[164:167], v[202:205], v[38:41]
	v_mfma_f32_16x16x32_bf16 v[30:33], v[186:189], v[202:205], v[30:33]
	v_mfma_f32_16x16x32_bf16 v[22:25], v[164:167], v[210:213], v[22:25]
	v_mfma_f32_16x16x32_bf16 v[14:17], v[186:189], v[210:213], v[14:17]
	v_mfma_f32_16x16x32_bf16 v[6:9], v[164:167], v[218:221], v[6:9]
	v_mfma_f32_16x16x32_bf16 v[2:5], v[186:189], v[218:221], v[2:5]
	v_mfma_f32_16x16x32_bf16 v[54:57], v[182:185], v[198:201], v[54:57]
	v_mfma_f32_16x16x32_bf16 v[46:49], v[190:193], v[198:201], v[46:49]
	v_mfma_f32_16x16x32_bf16 v[38:41], v[182:185], v[206:209], v[38:41]
	v_mfma_f32_16x16x32_bf16 v[30:33], v[190:193], v[206:209], v[30:33]
	v_mfma_f32_16x16x32_bf16 v[22:25], v[182:185], v[214:217], v[22:25]
	v_mfma_f32_16x16x32_bf16 v[14:17], v[190:193], v[214:217], v[14:17]
	v_mfma_f32_16x16x32_bf16 v[6:9], v[182:185], v[222:225], v[6:9]
	v_mfma_f32_16x16x32_bf16 v[2:5], v[190:193], v[222:225], v[2:5]
	s_setprio 0
	s_barrier
	v_lshl_add_u64 v[228:229], s[26:27], 0, v[130:131]
	s_mov_b32 m0, s34
	s_nop 0
	global_load_lds_dwordx4 v[228:229], off
	s_mov_b32 m0, s35
	s_nop 0
	global_load_lds_dwordx4 v[240:241], off
	v_add_u32_e32 v140, s63, v145
	ds_read_b128 v[148:151], v140
	ds_read_b128 v[152:155], v140 offset:1024
	ds_read_b128 v[156:159], v140 offset:2048
	ds_read_b128 v[160:163], v140 offset:3072
	v_add_u32_e32 v140, s55, v145
	ds_read_b128 v[164:167], v140
	ds_read_b128 v[182:185], v140 offset:1024
	ds_read_b128 v[186:189], v140 offset:2048
	ds_read_b128 v[190:193], v140 offset:3072
	s_add_u32 s20, s26, 0x2e0000
	s_addc_u32 s21, s27, 0
	s_mov_b32 m0, s36
	v_lshl_add_u64 v[242:243], s[20:21], 0, v[130:131]
	ds_read_b128 v[194:197], v147 offset:32768
	ds_read_b128 v[198:201], v147 offset:33792
	ds_read_b128 v[202:205], v147 offset:34816
	ds_read_b128 v[206:209], v147 offset:35840
	ds_read_b128 v[210:213], v147 offset:36864
	ds_read_b128 v[214:217], v147 offset:37888
	ds_read_b128 v[218:221], v147 offset:38912
	ds_read_b128 v[222:225], v147 offset:39936
	global_load_lds_dwordx4 v[242:243], off
	v_lshl_add_u64 v[242:243], s[20:21], 0, v[132:133]
	s_mov_b32 m0, s37
	s_nop 0
	global_load_lds_dwordx4 v[242:243], off
	s_waitcnt vmcnt(8)
	s_waitcnt lgkmcnt(0)
	s_barrier
	s_setprio 1
	s_waitcnt lgkmcnt(0)
	v_mfma_f32_16x16x32_bf16 v[126:129], v[148:151], v[194:197], v[126:129]
	v_mfma_f32_16x16x32_bf16 v[122:125], v[156:159], v[194:197], v[122:125]
	v_mfma_f32_16x16x32_bf16 v[114:117], v[148:151], v[202:205], v[114:117]
	v_mfma_f32_16x16x32_bf16 v[106:109], v[156:159], v[202:205], v[106:109]
	v_mfma_f32_16x16x32_bf16 v[98:101], v[148:151], v[210:213], v[98:101]
	v_mfma_f32_16x16x32_bf16 v[90:93], v[156:159], v[210:213], v[90:93]
	v_mfma_f32_16x16x32_bf16 v[82:85], v[148:151], v[218:221], v[82:85]
	v_mfma_f32_16x16x32_bf16 v[74:77], v[156:159], v[218:221], v[74:77]
	v_mfma_f32_16x16x32_bf16 v[126:129], v[152:155], v[198:201], v[126:129]
	v_mfma_f32_16x16x32_bf16 v[122:125], v[160:163], v[198:201], v[122:125]
	v_mfma_f32_16x16x32_bf16 v[114:117], v[152:155], v[206:209], v[114:117]
	v_mfma_f32_16x16x32_bf16 v[106:109], v[160:163], v[206:209], v[106:109]
	v_mfma_f32_16x16x32_bf16 v[98:101], v[152:155], v[214:217], v[98:101]
	v_mfma_f32_16x16x32_bf16 v[90:93], v[160:163], v[214:217], v[90:93]
	v_mfma_f32_16x16x32_bf16 v[82:85], v[152:155], v[222:225], v[82:85]
	v_mfma_f32_16x16x32_bf16 v[74:77], v[160:163], v[222:225], v[74:77]
	s_setprio 0
	s_setprio 1
	v_mfma_f32_16x16x32_bf16 v[118:121], v[164:167], v[194:197], v[118:121]
	v_mfma_f32_16x16x32_bf16 v[110:113], v[186:189], v[194:197], v[110:113]
	v_mfma_f32_16x16x32_bf16 v[102:105], v[164:167], v[202:205], v[102:105]
	v_mfma_f32_16x16x32_bf16 v[94:97], v[186:189], v[202:205], v[94:97]
	v_mfma_f32_16x16x32_bf16 v[86:89], v[164:167], v[210:213], v[86:89]
	v_mfma_f32_16x16x32_bf16 v[78:81], v[186:189], v[210:213], v[78:81]
	v_mfma_f32_16x16x32_bf16 v[70:73], v[164:167], v[218:221], v[70:73]
	v_mfma_f32_16x16x32_bf16 v[66:69], v[186:189], v[218:221], v[66:69]
	v_mfma_f32_16x16x32_bf16 v[118:121], v[182:185], v[198:201], v[118:121]
	v_mfma_f32_16x16x32_bf16 v[110:113], v[190:193], v[198:201], v[110:113]
	v_mfma_f32_16x16x32_bf16 v[102:105], v[182:185], v[206:209], v[102:105]
	v_mfma_f32_16x16x32_bf16 v[94:97], v[190:193], v[206:209], v[94:97]
	v_mfma_f32_16x16x32_bf16 v[86:89], v[182:185], v[214:217], v[86:89]
	v_mfma_f32_16x16x32_bf16 v[78:81], v[190:193], v[214:217], v[78:81]
	v_mfma_f32_16x16x32_bf16 v[70:73], v[182:185], v[222:225], v[70:73]
	v_mfma_f32_16x16x32_bf16 v[66:69], v[190:193], v[222:225], v[66:69]
	s_setprio 0
	s_barrier
; #define PG8_STAGE(bufoff, gbase, voff) do { _Pragma("unroll") for (int _i = 0; _i < 2; ++_i) \
;         __builtin_amdgcn_global_load_lds((const unsigned*)((const char*)(gbase) + (voff)[_i]), (PG8_LAS unsigned*)(lds + (bufoff) + ldsw + _i * 8192), 16, 0, 0); } while (0)
; #define PG8_LDA(dst, b, h) do { _Pragma("unroll") for (int m = 0; m < 4; ++m) _Pragma("unroll") for (int k = 0; k < 2; ++k) dst[m][k] = *(const PG8_LAS bf16x8*)(lds + PG8_SA(b, h) + aoff + m * 2048 + k * 1024); } while (0)
; #define PG8_MMA(ai, bj, At, Bt) do { __builtin_amdgcn_s_setprio(1); _Pragma("unroll") for (int m = 0; m < 4; ++m) _Pragma("unroll") for (int n = 0; n < 2; ++n) _Pragma("unroll") for (int k = 0; k < 2; ++k) \
;         acc[ai][bj][m][n] = __builtin_amdgcn_mfma_f32_16x16x32_bf16(Bt[n][k], At[m][k], acc[ai][bj][m][n], 0, 0, 0); __builtin_amdgcn_s_setprio(0); } while (0)
; #define PG8_WAIT_V(n) asm volatile("s_waitcnt vmcnt(" #n ")" ::: "memory")
; #define PG8_WAIT_L(n) asm volatile("s_waitcnt lgkmcnt(" #n ")" ::: "memory")
; #define PG8_BAR __builtin_amdgcn_s_barrier()
; #define PG8_SCHED __builtin_amdgcn_sched_barrier(0)
; template <class Epi, class Sched, bool ALIGN_EPI = false, bool SP2 = false>
; __device__ __forceinline__ void gemm_phase(PG8_LAS unsigned char* lds, const Gemm g, const Sched& S, const Epi& E, int tid_in) {
;     ...
;         for (int t = 0; t < nt; t += 2) {
;             const bool last = (t == nt - 2);
;             const char* a1 = cA + (size_t)(t + 1) * kstep;
;             const char* a2 = last ? nA : cA + (size_t)(t + 2) * kstep; const char* b2 = last ? nB : cB + (size_t)(t + 2) * kstep;
;     ...
;             PG8_LDA(At, 1, 1); PG8_STAGE(PG8_SB(1, 0), b3, voffB); PG8_STAGE(PG8_SB(1, 1), b3 + hstep, voffB); PG8_STAGE(PG8_SA(1, 0), a3, voffA);
;             PG8_WAIT_V(8); PG8_WAIT_L(0); PG8_BAR; PG8_MMA(1, 0, At, B0); PG8_MMA(1, 1, At, B1); PG8_BAR; PG8_SCHED;
	s_add_i32 s20, s63, s33
	v_lshl_add_u64 v[168:169], v[168:169], 0, s[90:91]
	s_mov_b32 m0, s20
	ds_read_b128 v[194:197], v147 offset:49152
	ds_read_b128 v[198:201], v147 offset:50176
	ds_read_b128 v[202:205], v147 offset:51200
	ds_read_b128 v[206:209], v147 offset:52224
	ds_read_b128 v[210:213], v147 offset:53248
	ds_read_b128 v[214:217], v147 offset:54272
	ds_read_b128 v[218:221], v147 offset:55296
	ds_read_b128 v[222:225], v147 offset:56320
	global_load_lds_dwordx4 v[168:169], off
	s_add_i32 m0, s20, 0x2000
	s_add_u32 s20, s24, 0x20080
	v_lshl_add_u64 v[168:169], v[226:227], 0, s[90:91]
	s_addc_u32 s21, s25, 0
	s_add_i32 s24, s55, s33
	global_load_lds_dwordx4 v[168:169], off
	v_lshl_add_u64 v[168:169], s[20:21], 0, v[0:1]
	s_mov_b32 m0, s24
	s_nop 0
	global_load_lds_dwordx4 v[168:169], off
	v_lshl_add_u64 v[168:169], s[20:21], 0, v[134:135]
	s_add_i32 m0, s24, 0x2000
	s_nop 0
	global_load_lds_dwordx4 v[168:169], off
	v_lshl_add_u64 v[168:169], v[228:229], 0, s[90:91]
	s_mov_b32 m0, s42
	s_nop 0
	global_load_lds_dwordx4 v[168:169], off
	v_lshl_add_u64 v[168:169], v[240:241], 0, s[90:91]
	s_mov_b32 m0, s43
	s_nop 0
	global_load_lds_dwordx4 v[168:169], off
	s_waitcnt vmcnt(8)
	s_waitcnt lgkmcnt(0)
	s_barrier
	s_setprio 1
	s_waitcnt lgkmcnt(0)
	v_mfma_f32_16x16x32_bf16 v[62:65], v[148:151], v[194:197], v[62:65]
	v_mfma_f32_16x16x32_bf16 v[58:61], v[156:159], v[194:197], v[58:61]
	v_mfma_f32_16x16x32_bf16 v[50:53], v[148:151], v[202:205], v[50:53]
	v_mfma_f32_16x16x32_bf16 v[42:45], v[156:159], v[202:205], v[42:45]
	v_mfma_f32_16x16x32_bf16 v[34:37], v[148:151], v[210:213], v[34:37]
	v_mfma_f32_16x16x32_bf16 v[26:29], v[156:159], v[210:213], v[26:29]
	v_mfma_f32_16x16x32_bf16 v[18:21], v[148:151], v[218:221], v[18:21]
	v_mfma_f32_16x16x32_bf16 v[10:13], v[156:159], v[218:221], v[10:13]
	v_mfma_f32_16x16x32_bf16 v[62:65], v[152:155], v[198:201], v[62:65]
	v_mfma_f32_16x16x32_bf16 v[58:61], v[160:163], v[198:201], v[58:61]
	v_mfma_f32_16x16x32_bf16 v[50:53], v[152:155], v[206:209], v[50:53]
	v_mfma_f32_16x16x32_bf16 v[42:45], v[160:163], v[206:209], v[42:45]
	v_mfma_f32_16x16x32_bf16 v[34:37], v[152:155], v[214:217], v[34:37]
	v_mfma_f32_16x16x32_bf16 v[26:29], v[160:163], v[214:217], v[26:29]
	v_mfma_f32_16x16x32_bf16 v[18:21], v[152:155], v[222:225], v[18:21]
	v_mfma_f32_16x16x32_bf16 v[10:13], v[160:163], v[222:225], v[10:13]
	s_setprio 0
	s_setprio 1
	v_mfma_f32_16x16x32_bf16 v[54:57], v[164:167], v[194:197], v[54:57]
	v_mfma_f32_16x16x32_bf16 v[46:49], v[186:189], v[194:197], v[46:49]
	v_mfma_f32_16x16x32_bf16 v[38:41], v[164:167], v[202:205], v[38:41]
	v_mfma_f32_16x16x32_bf16 v[30:33], v[186:189], v[202:205], v[30:33]
	v_mfma_f32_16x16x32_bf16 v[22:25], v[164:167], v[210:213], v[22:25]
	v_mfma_f32_16x16x32_bf16 v[14:17], v[186:189], v[210:213], v[14:17]
	v_mfma_f32_16x16x32_bf16 v[6:9], v[164:167], v[218:221], v[6:9]
	v_mfma_f32_16x16x32_bf16 v[2:5], v[186:189], v[218:221], v[2:5]
	v_mfma_f32_16x16x32_bf16 v[54:57], v[182:185], v[198:201], v[54:57]
	v_mfma_f32_16x16x32_bf16 v[46:49], v[190:193], v[198:201], v[46:49]
	v_mfma_f32_16x16x32_bf16 v[38:41], v[182:185], v[206:209], v[38:41]
	v_mfma_f32_16x16x32_bf16 v[30:33], v[190:193], v[206:209], v[30:33]
	v_mfma_f32_16x16x32_bf16 v[22:25], v[182:185], v[214:217], v[22:25]
	v_mfma_f32_16x16x32_bf16 v[14:17], v[190:193], v[214:217], v[14:17]
	v_mfma_f32_16x16x32_bf16 v[6:9], v[182:185], v[222:225], v[6:9]
	v_mfma_f32_16x16x32_bf16 v[2:5], v[190:193], v[222:225], v[2:5]
	s_setprio 0
	s_barrier
	s_add_i32 s48, s48, 2
	s_add_u32 s0, s0, 0x100
	s_addc_u32 s15, s15, 0
	s_cmp_gt_u32 s48, 5
	s_mov_b64 s[20:21], s[22:23]
	s_cbranch_scc0 .LBB0_627
	s_and_b64 vcc, exec, s[12:13]
	s_cbranch_vccz .LBB0_630
	s_barrier

; #define PG8_STAGE(bufoff, gbase, voff) do { _Pragma("unroll") for (int _i = 0; _i < 2; ++_i) \
;         __builtin_amdgcn_global_load_lds((const unsigned*)((const char*)(gbase) + (voff)[_i]), (PG8_LAS unsigned*)(lds + (bufoff) + ldsw + _i * 8192), 16, 0, 0); } while (0)
; #define PG8_LDA(dst, b, h) do { _Pragma("unroll") for (int m = 0; m < 4; ++m) _Pragma("unroll") for (int k = 0; k < 2; ++k) dst[m][k] = *(const PG8_LAS bf16x8*)(lds + PG8_SA(b, h) + aoff + m * 2048 + k * 1024); } while (0)
; #define PG8_LDB(dst, b, h) do { _Pragma("unroll") for (int n = 0; n < 2; ++n) _Pragma("unroll") for (int k = 0; k < 2; ++k) dst[n][k] = *(const PG8_LAS bf16x8*)(lds + PG8_SB(b, h) + boff + n * 2048 + k * 1024); } while (0)
; #define PG8_MMA(ai, bj, At, Bt) do { __builtin_amdgcn_s_setprio(1); _Pragma("unroll") for (int m = 0; m < 4; ++m) _Pragma("unroll") for (int n = 0; n < 2; ++n) _Pragma("unroll") for (int k = 0; k < 2; ++k) \
;         acc[ai][bj][m][n] = __builtin_amdgcn_mfma_f32_16x16x32_bf16(Bt[n][k], At[m][k], acc[ai][bj][m][n], 0, 0, 0); __builtin_amdgcn_s_setprio(0); } while (0)
; #define PG8_WAIT_V(n) asm volatile("s_waitcnt vmcnt(" #n ")" ::: "memory")
; #define PG8_WAIT_L(n) asm volatile("s_waitcnt lgkmcnt(" #n ")" ::: "memory")
; #define PG8_BAR __builtin_amdgcn_s_barrier()
; #define PG8_SCHED __builtin_amdgcn_sched_barrier(0)
; template <class Epi, class Sched, bool ALIGN_EPI = false, bool SP2 = false>
; __device__ __forceinline__ void gemm_phase(PG8_LAS unsigned char* lds, const Gemm g, const Sched& S, const Epi& E, int tid_in) {
;     ...
;         for (int t = 0; t < nt; t += 2) {
;             const bool last = (t == nt - 2);
;             const char* a1 = cA + (size_t)(t + 1) * kstep;
;             const char* a2 = last ? nA : cA + (size_t)(t + 2) * kstep; const char* b2 = last ? nB : cB + (size_t)(t + 2) * kstep;
;             const char* a3 = a2 + kstep; const char* b3 = b2 + kstep;
;             if (last && has_next) S.a_ready(nxt);
;             if constexpr (SP2) {
;             PG8_LDB(B0, 0, 0); PG8_LDB(B1, 0, 1); PG8_SCHED; PG8_LDA(At, 0, 0); PG8_STAGE(PG8_SA(1, 1), a1 + hstepA, voffA);
;             PG8_WAIT_V(8); PG8_WAIT_L(0); PG8_BAR; PG8_MMA(0, 0, At, B0); PG8_MMA(0, 1, At, B1); PG8_BAR; PG8_SCHED;
;             PG8_LDA(At, 0, 1); PG8_STAGE(PG8_SB(0, 0), b2, voffB); PG8_STAGE(PG8_SB(0, 1), b2 + hstep, voffB); PG8_STAGE(PG8_SA(0, 0), a2, voffA);
.LBB0_900:
	v_add_u32_e32 v0, s4, v242
	ds_read_b128 v[132:135], v0
	ds_read_b128 v[144:147], v0 offset:1024
	ds_read_b128 v[148:151], v0 offset:2048
	ds_read_b128 v[152:155], v0 offset:3072
	v_add_u32_e32 v0, s5, v242
	ds_read_b128 v[156:159], v0
	ds_read_b128 v[160:163], v0 offset:1024
	ds_read_b128 v[164:167], v0 offset:2048
	ds_read_b128 v[182:185], v0 offset:3072
	s_add_i32 vcc_hi, s10, 2
	s_add_u32 s11, s8, 0xfffc0080
	s_addc_u32 s12, s9, -1
	s_cmp_eq_u32 s68, s10
	s_cselect_b32 s10, s47, s76
	s_cselect_b32 s13, s30, s12
	s_cselect_b32 s12, s31, s11
	s_cselect_b32 s11, s46, vcc_lo
	v_lshl_add_u64 v[2:3], s[8:9], 0, v[140:141]
	s_add_i32 m0, s37, 0xc000
	ds_read_b128 v[186:189], v243
	ds_read_b128 v[190:193], v243 offset:1024
	ds_read_b128 v[194:197], v243 offset:2048
	ds_read_b128 v[198:201], v243 offset:3072
	ds_read_b128 v[202:205], v243 offset:4096
	ds_read_b128 v[206:209], v243 offset:5120
	ds_read_b128 v[210:213], v243 offset:6144
	ds_read_b128 v[214:217], v243 offset:7168
	global_load_lds_dwordx4 v[2:3], off
	v_lshl_add_u64 v[2:3], s[8:9], 0, v[142:143]
	s_add_i32 m0, s37, 0xe000
	s_nop 0
	global_load_lds_dwordx4 v[2:3], off
	s_waitcnt vmcnt(8)
	s_waitcnt lgkmcnt(0)
	s_barrier
	s_setprio 1
	s_waitcnt lgkmcnt(0)
	v_mfma_f32_16x16x32_bf16 v[128:131], v[132:135], v[186:189], v[128:131]
	v_mfma_f32_16x16x32_bf16 v[124:127], v[148:151], v[186:189], v[124:127]
	v_mfma_f32_16x16x32_bf16 v[120:123], v[132:135], v[194:197], v[120:123]
	v_mfma_f32_16x16x32_bf16 v[116:119], v[148:151], v[194:197], v[116:119]
	v_mfma_f32_16x16x32_bf16 v[112:115], v[132:135], v[202:205], v[112:115]
	v_mfma_f32_16x16x32_bf16 v[108:111], v[148:151], v[202:205], v[108:111]
	v_mfma_f32_16x16x32_bf16 v[104:107], v[132:135], v[210:213], v[104:107]
	v_mfma_f32_16x16x32_bf16 v[100:103], v[148:151], v[210:213], v[100:103]
	v_mfma_f32_16x16x32_bf16 v[128:131], v[144:147], v[190:193], v[128:131]
	v_mfma_f32_16x16x32_bf16 v[124:127], v[152:155], v[190:193], v[124:127]
	v_mfma_f32_16x16x32_bf16 v[120:123], v[144:147], v[198:201], v[120:123]
	v_mfma_f32_16x16x32_bf16 v[116:119], v[152:155], v[198:201], v[116:119]
	v_mfma_f32_16x16x32_bf16 v[112:115], v[144:147], v[206:209], v[112:115]
	v_mfma_f32_16x16x32_bf16 v[108:111], v[152:155], v[206:209], v[108:111]
	v_mfma_f32_16x16x32_bf16 v[104:107], v[144:147], v[214:217], v[104:107]
	v_mfma_f32_16x16x32_bf16 v[100:103], v[152:155], v[214:217], v[100:103]
	s_setprio 0
	s_setprio 1
	v_mfma_f32_16x16x32_bf16 v[96:99], v[156:159], v[186:189], v[96:99]
	v_mfma_f32_16x16x32_bf16 v[92:95], v[164:167], v[186:189], v[92:95]
	v_mfma_f32_16x16x32_bf16 v[88:91], v[156:159], v[194:197], v[88:91]
	v_mfma_f32_16x16x32_bf16 v[84:87], v[164:167], v[194:197], v[84:87]
	v_mfma_f32_16x16x32_bf16 v[80:83], v[156:159], v[202:205], v[80:83]
	v_mfma_f32_16x16x32_bf16 v[76:79], v[164:167], v[202:205], v[76:79]
	v_mfma_f32_16x16x32_bf16 v[72:75], v[156:159], v[210:213], v[72:75]
	v_mfma_f32_16x16x32_bf16 v[68:71], v[164:167], v[210:213], v[68:71]
	v_mfma_f32_16x16x32_bf16 v[96:99], v[160:163], v[190:193], v[96:99]
	v_mfma_f32_16x16x32_bf16 v[92:95], v[182:185], v[190:193], v[92:95]
	v_mfma_f32_16x16x32_bf16 v[88:91], v[160:163], v[198:201], v[88:91]
	v_mfma_f32_16x16x32_bf16 v[84:87], v[182:185], v[198:201], v[84:87]
	v_mfma_f32_16x16x32_bf16 v[80:83], v[160:163], v[206:209], v[80:83]
	v_mfma_f32_16x16x32_bf16 v[76:79], v[182:185], v[206:209], v[76:79]
	v_mfma_f32_16x16x32_bf16 v[72:75], v[160:163], v[214:217], v[72:75]
	v_mfma_f32_16x16x32_bf16 v[68:71], v[182:185], v[214:217], v[68:71]
	s_setprio 0
	s_barrier
	s_add_i32 s64, s4, s36
	v_lshl_add_u64 v[168:169], s[10:11], 0, v[136:137]
	s_mov_b32 m0, s64
	ds_read_b128 v[186:189], v243 offset:16384
	ds_read_b128 v[190:193], v243 offset:17408
	ds_read_b128 v[194:197], v243 offset:18432
	ds_read_b128 v[198:201], v243 offset:19456
	ds_read_b128 v[202:205], v243 offset:20480
	ds_read_b128 v[206:209], v243 offset:21504
	ds_read_b128 v[210:213], v243 offset:22528
	ds_read_b128 v[214:217], v243 offset:23552
	global_load_lds_dwordx4 v[168:169], off
	s_add_i32 m0, s64, 0x2000
	s_add_u32 s64, s10, 0x40000
	v_lshl_add_u64 v[218:219], s[10:11], 0, v[138:139]
	s_addc_u32 s65, s11, 0
	s_add_i32 s95, s5, s36
	global_load_lds_dwordx4 v[218:219], off
	v_lshl_add_u64 v[2:3], s[64:65], 0, v[136:137]
	s_mov_b32 m0, s95
	v_lshl_add_u64 v[220:221], s[12:13], 0, v[136:137]
	global_load_lds_dwordx4 v[2:3], off
	v_lshl_add_u64 v[2:3], s[64:65], 0, v[138:139]
	s_add_i32 m0, s95, 0x2000
	v_lshl_add_u64 v[222:223], s[12:13], 0, v[138:139]
	global_load_lds_dwordx4 v[2:3], off
	s_waitcnt vmcnt(6)
	s_waitcnt lgkmcnt(0)
	s_barrier
; #define PG8_STAGE(bufoff, gbase, voff) do { _Pragma("unroll") for (int _i = 0; _i < 2; ++_i) \
;         __builtin_amdgcn_global_load_lds((const unsigned*)((const char*)(gbase) + (voff)[_i]), (PG8_LAS unsigned*)(lds + (bufoff) + ldsw + _i * 8192), 16, 0, 0); } while (0)
; #define PG8_LDA(dst, b, h) do { _Pragma("unroll") for (int m = 0; m < 4; ++m) _Pragma("unroll") for (int k = 0; k < 2; ++k) dst[m][k] = *(const PG8_LAS bf16x8*)(lds + PG8_SA(b, h) + aoff + m * 2048 + k * 1024); } while (0)
; #define PG8_LDB(dst, b, h) do { _Pragma("unroll") for (int n = 0; n < 2; ++n) _Pragma("unroll") for (int k = 0; k < 2; ++k) dst[n][k] = *(const PG8_LAS bf16x8*)(lds + PG8_SB(b, h) + boff + n * 2048 + k * 1024); } while (0)
; #define PG8_MMA(ai, bj, At, Bt) do { __builtin_amdgcn_s_setprio(1); _Pragma("unroll") for (int m = 0; m < 4; ++m) _Pragma("unroll") for (int n = 0; n < 2; ++n) _Pragma("unroll") for (int k = 0; k < 2; ++k) \
;         acc[ai][bj][m][n] = __builtin_amdgcn_mfma_f32_16x16x32_bf16(Bt[n][k], At[m][k], acc[ai][bj][m][n], 0, 0, 0); __builtin_amdgcn_s_setprio(0); } while (0)
; #define PG8_WAIT_V(n) asm volatile("s_waitcnt vmcnt(" #n ")" ::: "memory")
; #define PG8_WAIT_L(n) asm volatile("s_waitcnt lgkmcnt(" #n ")" ::: "memory")
; #define PG8_BAR __builtin_amdgcn_s_barrier()
; #define PG8_SCHED __builtin_amdgcn_sched_barrier(0)
; template <class Epi, class Sched, bool ALIGN_EPI = false, bool SP2 = false>
; __device__ __forceinline__ void gemm_phase(PG8_LAS unsigned char* lds, const Gemm g, const Sched& S, const Epi& E, int tid_in) {
;     ...
;             PG8_LDA(At, 0, 1); PG8_STAGE(PG8_SB(0, 0), b2, voffB); PG8_STAGE(PG8_SB(0, 1), b2 + hstep, voffB); PG8_STAGE(PG8_SA(0, 0), a2, voffA);
;             PG8_WAIT_V(8); PG8_WAIT_L(0); PG8_BAR; PG8_MMA(1, 0, At, B0); PG8_MMA(1, 1, At, B1); PG8_BAR; PG8_SCHED;
;             PG8_LDB(B0, 1, 0); PG8_LDB(B1, 1, 1); PG8_SCHED; PG8_LDA(At, 1, 0); PG8_STAGE(PG8_SA(0, 1), a2 + hstepA, voffA);
;             PG8_WAIT_V(8); PG8_WAIT_L(0); PG8_BAR; PG8_MMA(0, 0, At, B0); PG8_MMA(0, 1, At, B1); PG8_BAR; PG8_SCHED;
	s_setprio 1
	s_waitcnt lgkmcnt(0)
	v_mfma_f32_16x16x32_bf16 v[64:67], v[132:135], v[186:189], v[64:67]
	v_mfma_f32_16x16x32_bf16 v[60:63], v[148:151], v[186:189], v[60:63]
	v_mfma_f32_16x16x32_bf16 v[56:59], v[132:135], v[194:197], v[56:59]
	v_mfma_f32_16x16x32_bf16 v[52:55], v[148:151], v[194:197], v[52:55]
	v_mfma_f32_16x16x32_bf16 v[48:51], v[132:135], v[202:205], v[48:51]
	v_mfma_f32_16x16x32_bf16 v[44:47], v[148:151], v[202:205], v[44:47]
	v_mfma_f32_16x16x32_bf16 v[40:43], v[132:135], v[210:213], v[40:43]
	v_mfma_f32_16x16x32_bf16 v[36:39], v[148:151], v[210:213], v[36:39]
	v_mfma_f32_16x16x32_bf16 v[64:67], v[144:147], v[190:193], v[64:67]
	v_mfma_f32_16x16x32_bf16 v[60:63], v[152:155], v[190:193], v[60:63]
	v_mfma_f32_16x16x32_bf16 v[56:59], v[144:147], v[198:201], v[56:59]
	v_mfma_f32_16x16x32_bf16 v[52:55], v[152:155], v[198:201], v[52:55]
	v_mfma_f32_16x16x32_bf16 v[48:51], v[144:147], v[206:209], v[48:51]
	v_mfma_f32_16x16x32_bf16 v[44:47], v[152:155], v[206:209], v[44:47]
	v_mfma_f32_16x16x32_bf16 v[40:43], v[144:147], v[214:217], v[40:43]
	v_mfma_f32_16x16x32_bf16 v[36:39], v[152:155], v[214:217], v[36:39]
	s_setprio 0
	s_setprio 1
	v_mfma_f32_16x16x32_bf16 v[32:35], v[156:159], v[186:189], v[32:35]
	v_mfma_f32_16x16x32_bf16 v[28:31], v[164:167], v[186:189], v[28:31]
	v_mfma_f32_16x16x32_bf16 v[24:27], v[156:159], v[194:197], v[24:27]
	v_mfma_f32_16x16x32_bf16 v[20:23], v[164:167], v[194:197], v[20:23]
	v_mfma_f32_16x16x32_bf16 v[16:19], v[156:159], v[202:205], v[16:19]
	v_mfma_f32_16x16x32_bf16 v[12:15], v[164:167], v[202:205], v[12:15]
	v_mfma_f32_16x16x32_bf16 v[8:11], v[156:159], v[210:213], v[8:11]
	v_mfma_f32_16x16x32_bf16 v[2:5], v[164:167], v[210:213], v[4:7]
	v_mfma_f32_16x16x32_bf16 v[32:35], v[160:163], v[190:193], v[32:35]
	v_mfma_f32_16x16x32_bf16 v[28:31], v[182:185], v[190:193], v[28:31]
	v_mfma_f32_16x16x32_bf16 v[24:27], v[160:163], v[198:201], v[24:27]
	v_mfma_f32_16x16x32_bf16 v[20:23], v[182:185], v[198:201], v[20:23]
	v_mfma_f32_16x16x32_bf16 v[16:19], v[160:163], v[206:209], v[16:19]
	v_mfma_f32_16x16x32_bf16 v[12:15], v[182:185], v[206:209], v[12:15]
	v_mfma_f32_16x16x32_bf16 v[8:11], v[160:163], v[214:217], v[8:11]
	v_mfma_f32_16x16x32_bf16 v[2:5], v[182:185], v[214:217], v[2:5]
	s_setprio 0
	s_barrier
	s_mov_b32 m0, s37
	s_nop 0
	global_load_lds_dwordx4 v[220:221], off
	s_mov_b32 m0, s38
	s_nop 0
	global_load_lds_dwordx4 v[222:223], off
	v_add_u32_e32 v0, s63, v242
	ds_read_b128 v[132:135], v0
	ds_read_b128 v[144:147], v0 offset:1024
	ds_read_b128 v[148:151], v0 offset:2048
	ds_read_b128 v[152:155], v0 offset:3072
	v_add_u32_e32 v0, s55, v242
	ds_read_b128 v[156:159], v0
	ds_read_b128 v[160:163], v0 offset:1024
	ds_read_b128 v[164:167], v0 offset:2048
	ds_read_b128 v[182:185], v0 offset:3072
	s_add_u32 s12, s12, 0x40000
	s_addc_u32 s13, s13, 0
	s_mov_b32 m0, s39
	v_lshl_add_u64 v[6:7], s[12:13], 0, v[136:137]
	ds_read_b128 v[186:189], v243 offset:32768
	ds_read_b128 v[190:193], v243 offset:33792
	ds_read_b128 v[194:197], v243 offset:34816
	ds_read_b128 v[198:201], v243 offset:35840
	ds_read_b128 v[202:205], v243 offset:36864
	ds_read_b128 v[206:209], v243 offset:37888
	ds_read_b128 v[210:213], v243 offset:38912
	ds_read_b128 v[214:217], v243 offset:39936
	global_load_lds_dwordx4 v[6:7], off
	v_lshl_add_u64 v[6:7], s[12:13], 0, v[138:139]
	s_mov_b32 m0, s40
	s_nop 0
	global_load_lds_dwordx4 v[6:7], off
	s_waitcnt vmcnt(8)
	s_waitcnt lgkmcnt(0)
	s_barrier
	s_setprio 1
	s_waitcnt lgkmcnt(0)
	v_mfma_f32_16x16x32_bf16 v[128:131], v[132:135], v[186:189], v[128:131]
	v_mfma_f32_16x16x32_bf16 v[124:127], v[148:151], v[186:189], v[124:127]
	v_mfma_f32_16x16x32_bf16 v[120:123], v[132:135], v[194:197], v[120:123]
	v_mfma_f32_16x16x32_bf16 v[116:119], v[148:151], v[194:197], v[116:119]
	v_mfma_f32_16x16x32_bf16 v[112:115], v[132:135], v[202:205], v[112:115]
	v_mfma_f32_16x16x32_bf16 v[108:111], v[148:151], v[202:205], v[108:111]
	v_mfma_f32_16x16x32_bf16 v[104:107], v[132:135], v[210:213], v[104:107]
	v_mfma_f32_16x16x32_bf16 v[100:103], v[148:151], v[210:213], v[100:103]
	v_mfma_f32_16x16x32_bf16 v[128:131], v[144:147], v[190:193], v[128:131]
	v_mfma_f32_16x16x32_bf16 v[124:127], v[152:155], v[190:193], v[124:127]
	v_mfma_f32_16x16x32_bf16 v[120:123], v[144:147], v[198:201], v[120:123]
	v_mfma_f32_16x16x32_bf16 v[116:119], v[152:155], v[198:201], v[116:119]
	v_mfma_f32_16x16x32_bf16 v[112:115], v[144:147], v[206:209], v[112:115]
	v_mfma_f32_16x16x32_bf16 v[108:111], v[152:155], v[206:209], v[108:111]
	v_mfma_f32_16x16x32_bf16 v[104:107], v[144:147], v[214:217], v[104:107]
	v_mfma_f32_16x16x32_bf16 v[100:103], v[152:155], v[214:217], v[100:103]
	s_setprio 0
	s_setprio 1
	v_mfma_f32_16x16x32_bf16 v[96:99], v[156:159], v[186:189], v[96:99]
	v_mfma_f32_16x16x32_bf16 v[92:95], v[164:167], v[186:189], v[92:95]
	v_mfma_f32_16x16x32_bf16 v[88:91], v[156:159], v[194:197], v[88:91]
	v_mfma_f32_16x16x32_bf16 v[84:87], v[164:167], v[194:197], v[84:87]
	v_mfma_f32_16x16x32_bf16 v[80:83], v[156:159], v[202:205], v[80:83]
	v_mfma_f32_16x16x32_bf16 v[76:79], v[164:167], v[202:205], v[76:79]
	v_mfma_f32_16x16x32_bf16 v[72:75], v[156:159], v[210:213], v[72:75]
	v_mfma_f32_16x16x32_bf16 v[68:71], v[164:167], v[210:213], v[68:71]
	v_mfma_f32_16x16x32_bf16 v[96:99], v[160:163], v[190:193], v[96:99]
	v_mfma_f32_16x16x32_bf16 v[92:95], v[182:185], v[190:193], v[92:95]
	v_mfma_f32_16x16x32_bf16 v[88:91], v[160:163], v[198:201], v[88:91]
	v_mfma_f32_16x16x32_bf16 v[84:87], v[182:185], v[198:201], v[84:87]
	v_mfma_f32_16x16x32_bf16 v[80:83], v[160:163], v[206:209], v[80:83]
	v_mfma_f32_16x16x32_bf16 v[76:79], v[182:185], v[206:209], v[76:79]
	v_mfma_f32_16x16x32_bf16 v[72:75], v[160:163], v[214:217], v[72:75]
	v_mfma_f32_16x16x32_bf16 v[68:71], v[182:185], v[214:217], v[68:71]
	s_setprio 0
	s_barrier
; #define PG8_STAGE(bufoff, gbase, voff) do { _Pragma("unroll") for (int _i = 0; _i < 2; ++_i) \
;         __builtin_amdgcn_global_load_lds((const unsigned*)((const char*)(gbase) + (voff)[_i]), (PG8_LAS unsigned*)(lds + (bufoff) + ldsw + _i * 8192), 16, 0, 0); } while (0)
; #define PG8_LDA(dst, b, h) do { _Pragma("unroll") for (int m = 0; m < 4; ++m) _Pragma("unroll") for (int k = 0; k < 2; ++k) dst[m][k] = *(const PG8_LAS bf16x8*)(lds + PG8_SA(b, h) + aoff + m * 2048 + k * 1024); } while (0)
; #define PG8_MMA(ai, bj, At, Bt) do { __builtin_amdgcn_s_setprio(1); _Pragma("unroll") for (int m = 0; m < 4; ++m) _Pragma("unroll") for (int n = 0; n < 2; ++n) _Pragma("unroll") for (int k = 0; k < 2; ++k) \
;         acc[ai][bj][m][n] = __builtin_amdgcn_mfma_f32_16x16x32_bf16(Bt[n][k], At[m][k], acc[ai][bj][m][n], 0, 0, 0); __builtin_amdgcn_s_setprio(0); } while (0)
; #define PG8_WAIT_V(n) asm volatile("s_waitcnt vmcnt(" #n ")" ::: "memory")
; #define PG8_WAIT_L(n) asm volatile("s_waitcnt lgkmcnt(" #n ")" ::: "memory")
; #define PG8_BAR __builtin_amdgcn_s_barrier()
; #define PG8_SCHED __builtin_amdgcn_sched_barrier(0)
; template <class Epi, class Sched, bool ALIGN_EPI = false, bool SP2 = false>
; __device__ __forceinline__ void gemm_phase(PG8_LAS unsigned char* lds, const Gemm g, const Sched& S, const Epi& E, int tid_in) {
;     ...
;         for (int t = 0; t < nt; t += 2) {
;             const bool last = (t == nt - 2);
;             const char* a1 = cA + (size_t)(t + 1) * kstep;
;             const char* a2 = last ? nA : cA + (size_t)(t + 2) * kstep; const char* b2 = last ? nB : cB + (size_t)(t + 2) * kstep;
;     ...
;             PG8_LDA(At, 1, 1); PG8_STAGE(PG8_SB(1, 0), b3, voffB); PG8_STAGE(PG8_SB(1, 1), b3 + hstep, voffB); PG8_STAGE(PG8_SA(1, 0), a3, voffA);
;             PG8_WAIT_V(8); PG8_WAIT_L(0); PG8_BAR; PG8_MMA(1, 0, At, B0); PG8_MMA(1, 1, At, B1); PG8_BAR; PG8_SCHED;
	s_add_i32 s12, s63, s36
	v_lshl_add_u64 v[6:7], v[168:169], 0, s[90:91]
	s_mov_b32 m0, s12
	ds_read_b128 v[186:189], v243 offset:49152
	ds_read_b128 v[190:193], v243 offset:50176
	ds_read_b128 v[194:197], v243 offset:51200
	ds_read_b128 v[198:201], v243 offset:52224
	ds_read_b128 v[202:205], v243 offset:53248
	ds_read_b128 v[206:209], v243 offset:54272
	ds_read_b128 v[210:213], v243 offset:55296
	ds_read_b128 v[214:217], v243 offset:56320
	global_load_lds_dwordx4 v[6:7], off
	s_add_i32 m0, s12, 0x2000
	s_add_u32 s10, s10, 0x40080
	v_lshl_add_u64 v[6:7], v[218:219], 0, s[90:91]
	s_addc_u32 s11, s11, 0
	s_add_i32 s12, s55, s36
	global_load_lds_dwordx4 v[6:7], off
	v_lshl_add_u64 v[6:7], s[10:11], 0, v[136:137]
	s_mov_b32 m0, s12
	s_nop 0
	global_load_lds_dwordx4 v[6:7], off
	v_lshl_add_u64 v[6:7], s[10:11], 0, v[138:139]
	s_add_i32 m0, s12, 0x2000
	s_nop 0
	global_load_lds_dwordx4 v[6:7], off
	v_lshl_add_u64 v[6:7], v[220:221], 0, s[90:91]
	s_mov_b32 m0, s49
	s_nop 0
	global_load_lds_dwordx4 v[6:7], off
	v_lshl_add_u64 v[6:7], v[222:223], 0, s[90:91]
	s_mov_b32 m0, s79
	s_nop 0
	global_load_lds_dwordx4 v[6:7], off
	s_waitcnt vmcnt(8)
	s_waitcnt lgkmcnt(0)
	s_barrier
	s_setprio 1
	s_waitcnt lgkmcnt(0)
	v_mfma_f32_16x16x32_bf16 v[64:67], v[132:135], v[186:189], v[64:67]
	v_mfma_f32_16x16x32_bf16 v[60:63], v[148:151], v[186:189], v[60:63]
	v_mfma_f32_16x16x32_bf16 v[56:59], v[132:135], v[194:197], v[56:59]
	v_mfma_f32_16x16x32_bf16 v[52:55], v[148:151], v[194:197], v[52:55]
	v_mfma_f32_16x16x32_bf16 v[48:51], v[132:135], v[202:205], v[48:51]
	v_mfma_f32_16x16x32_bf16 v[44:47], v[148:151], v[202:205], v[44:47]
	v_mfma_f32_16x16x32_bf16 v[40:43], v[132:135], v[210:213], v[40:43]
	v_mfma_f32_16x16x32_bf16 v[36:39], v[148:151], v[210:213], v[36:39]
	v_mfma_f32_16x16x32_bf16 v[64:67], v[144:147], v[190:193], v[64:67]
	v_mfma_f32_16x16x32_bf16 v[60:63], v[152:155], v[190:193], v[60:63]
	v_mfma_f32_16x16x32_bf16 v[56:59], v[144:147], v[198:201], v[56:59]
	v_mfma_f32_16x16x32_bf16 v[52:55], v[152:155], v[198:201], v[52:55]
	v_mfma_f32_16x16x32_bf16 v[48:51], v[144:147], v[206:209], v[48:51]
	v_mfma_f32_16x16x32_bf16 v[44:47], v[152:155], v[206:209], v[44:47]
	v_mfma_f32_16x16x32_bf16 v[40:43], v[144:147], v[214:217], v[40:43]
	v_mfma_f32_16x16x32_bf16 v[36:39], v[152:155], v[214:217], v[36:39]
	s_setprio 0
	s_setprio 1
	v_mfma_f32_16x16x32_bf16 v[32:35], v[156:159], v[186:189], v[32:35]
	v_mfma_f32_16x16x32_bf16 v[28:31], v[164:167], v[186:189], v[28:31]
	v_mfma_f32_16x16x32_bf16 v[24:27], v[156:159], v[194:197], v[24:27]
	v_mfma_f32_16x16x32_bf16 v[20:23], v[164:167], v[194:197], v[20:23]
	v_mfma_f32_16x16x32_bf16 v[16:19], v[156:159], v[202:205], v[16:19]
	v_mfma_f32_16x16x32_bf16 v[12:15], v[164:167], v[202:205], v[12:15]
	v_mfma_f32_16x16x32_bf16 v[6:9], v[156:159], v[210:213], v[8:11]
	v_mfma_f32_16x16x32_bf16 v[2:5], v[164:167], v[210:213], v[2:5]
	v_mfma_f32_16x16x32_bf16 v[32:35], v[160:163], v[190:193], v[32:35]
	v_mfma_f32_16x16x32_bf16 v[28:31], v[182:185], v[190:193], v[28:31]
	v_mfma_f32_16x16x32_bf16 v[24:27], v[160:163], v[198:201], v[24:27]
	v_mfma_f32_16x16x32_bf16 v[20:23], v[182:185], v[198:201], v[20:23]
	v_mfma_f32_16x16x32_bf16 v[16:19], v[160:163], v[206:209], v[16:19]
	v_mfma_f32_16x16x32_bf16 v[12:15], v[182:185], v[206:209], v[12:15]
	v_mfma_f32_16x16x32_bf16 v[8:11], v[160:163], v[214:217], v[6:9]
	v_mfma_f32_16x16x32_bf16 v[4:7], v[182:185], v[214:217], v[2:5]
	s_setprio 0
	s_barrier
	s_add_u32 s8, s8, 0x100
	s_addc_u32 s9, s9, 0
	s_add_u32 s76, s76, 0x100
	s_addc_u32 vcc_lo, vcc_lo, 0
	s_cmp_ge_i32 vcc_hi, s14
	s_mov_b32 s10, vcc_hi
	s_cbranch_scc0 .LBB0_900
	s_and_b64 vcc, exec, s[18:19]
	s_cbranch_vccz .LBB0_903
	s_barrier

; #define PG8_STAGE(bufoff, gbase, voff) do { _Pragma("unroll") for (int _i = 0; _i < 2; ++_i) \
;         __builtin_amdgcn_global_load_lds((const unsigned*)((const char*)(gbase) + (voff)[_i]), (PG8_LAS unsigned*)(lds + (bufoff) + ldsw + _i * 8192), 16, 0, 0); } while (0)
; #define PG8_LDA(dst, b, h) do { _Pragma("unroll") for (int m = 0; m < 4; ++m) _Pragma("unroll") for (int k = 0; k < 2; ++k) dst[m][k] = *(const PG8_LAS bf16x8*)(lds + PG8_SA(b, h) + aoff + m * 2048 + k * 1024); } while (0)
; #define PG8_LDB(dst, b, h) do { _Pragma("unroll") for (int n = 0; n < 2; ++n) _Pragma("unroll") for (int k = 0; k < 2; ++k) dst[n][k] = *(const PG8_LAS bf16x8*)(lds + PG8_SB(b, h) + boff + n * 2048 + k * 1024); } while (0)
; #define PG8_MMA(ai, bj, At, Bt) do { __builtin_amdgcn_s_setprio(1); _Pragma("unroll") for (int m = 0; m < 4; ++m) _Pragma("unroll") for (int n = 0; n < 2; ++n) _Pragma("unroll") for (int k = 0; k < 2; ++k) \
;         acc[ai][bj][m][n] = __builtin_amdgcn_mfma_f32_16x16x32_bf16(Bt[n][k], At[m][k], acc[ai][bj][m][n], 0, 0, 0); __builtin_amdgcn_s_setprio(0); } while (0)
; #define PG8_WAIT_V(n) asm volatile("s_waitcnt vmcnt(" #n ")" ::: "memory")
; #define PG8_WAIT_L(n) asm volatile("s_waitcnt lgkmcnt(" #n ")" ::: "memory")
; #define PG8_BAR __builtin_amdgcn_s_barrier()
; #define PG8_SCHED __builtin_amdgcn_sched_barrier(0)
; template <class Epi, class Sched, bool ALIGN_EPI = false, bool SP2 = false>
; __device__ __forceinline__ void gemm_phase(PG8_LAS unsigned char* lds, const Gemm g, const Sched& S, const Epi& E, int tid_in) {
;     ...
;         for (int t = 0; t < nt; t += 2) {
;             const bool last = (t == nt - 2);
;             const char* a1 = cA + (size_t)(t + 1) * kstep;
;             const char* a2 = last ? nA : cA + (size_t)(t + 2) * kstep; const char* b2 = last ? nB : cB + (size_t)(t + 2) * kstep;
;             const char* a3 = a2 + kstep; const char* b3 = b2 + kstep;
;             if (last && has_next) S.a_ready(nxt);
;             if constexpr (SP2) {
;             PG8_LDB(B0, 0, 0); PG8_LDB(B1, 0, 1); PG8_SCHED; PG8_LDA(At, 0, 0); PG8_STAGE(PG8_SA(1, 1), a1 + hstepA, voffA);
;             PG8_WAIT_V(8); PG8_WAIT_L(0); PG8_BAR; PG8_MMA(0, 0, At, B0); PG8_MMA(0, 1, At, B1); PG8_BAR; PG8_SCHED;
;             PG8_LDA(At, 0, 1); PG8_STAGE(PG8_SB(0, 0), b2, voffB); PG8_STAGE(PG8_SB(0, 1), b2 + hstep, voffB); PG8_STAGE(PG8_SA(0, 0), a2, voffA);
.LBB0_1348:
	v_add_u32_e32 v152, s4, v146
	v_add_u32_e32 v168, s5, v146
	ds_read_b128 v[136:139], v152
	ds_read_b128 v[140:143], v152 offset:1024
	ds_read_b128 v[148:151], v152 offset:2048
	ds_read_b128 v[152:155], v152 offset:3072
	ds_read_b128 v[156:159], v168
	ds_read_b128 v[160:163], v168 offset:1024
	ds_read_b128 v[164:167], v168 offset:2048
	ds_read_b128 v[182:185], v168 offset:3072
	s_add_i32 s76, s26, 2
	s_add_u32 s27, s24, 0xfff80080
	s_addc_u32 s28, s25, -1
	s_cmp_eq_u32 s67, s26
	s_cselect_b32 s26, s66, s68
	s_cselect_b32 s29, s46, s28
	s_cselect_b32 s28, s47, s27
	s_cselect_b32 s27, s49, s70
	v_lshl_add_u64 v[168:169], s[24:25], 0, v[132:133]
	s_add_i32 m0, s31, 0xc000
	ds_read_b128 v[186:189], v147
	ds_read_b128 v[190:193], v147 offset:1024
	ds_read_b128 v[194:197], v147 offset:2048
	ds_read_b128 v[198:201], v147 offset:3072
	ds_read_b128 v[202:205], v147 offset:4096
	ds_read_b128 v[206:209], v147 offset:5120
	ds_read_b128 v[210:213], v147 offset:6144
	ds_read_b128 v[214:217], v147 offset:7168
	global_load_lds_dwordx4 v[168:169], off
	v_lshl_add_u64 v[168:169], s[24:25], 0, v[134:135]
	s_add_i32 m0, s31, 0xe000
	s_nop 0
	global_load_lds_dwordx4 v[168:169], off
	s_waitcnt vmcnt(8)
	s_waitcnt lgkmcnt(0)
	s_barrier
	s_setprio 1
	s_waitcnt lgkmcnt(0)
	v_mfma_f32_16x16x32_bf16 v[126:129], v[136:139], v[186:189], v[126:129]
	v_mfma_f32_16x16x32_bf16 v[122:125], v[148:151], v[186:189], v[122:125]
	v_mfma_f32_16x16x32_bf16 v[118:121], v[136:139], v[194:197], v[118:121]
	v_mfma_f32_16x16x32_bf16 v[114:117], v[148:151], v[194:197], v[114:117]
	v_mfma_f32_16x16x32_bf16 v[110:113], v[136:139], v[202:205], v[110:113]
	v_mfma_f32_16x16x32_bf16 v[106:109], v[148:151], v[202:205], v[106:109]
	v_mfma_f32_16x16x32_bf16 v[102:105], v[136:139], v[210:213], v[102:105]
	v_mfma_f32_16x16x32_bf16 v[98:101], v[148:151], v[210:213], v[98:101]
	v_mfma_f32_16x16x32_bf16 v[126:129], v[140:143], v[190:193], v[126:129]
	v_mfma_f32_16x16x32_bf16 v[122:125], v[152:155], v[190:193], v[122:125]
	v_mfma_f32_16x16x32_bf16 v[118:121], v[140:143], v[198:201], v[118:121]
	v_mfma_f32_16x16x32_bf16 v[114:117], v[152:155], v[198:201], v[114:117]
	v_mfma_f32_16x16x32_bf16 v[110:113], v[140:143], v[206:209], v[110:113]
	v_mfma_f32_16x16x32_bf16 v[106:109], v[152:155], v[206:209], v[106:109]
	v_mfma_f32_16x16x32_bf16 v[102:105], v[140:143], v[214:217], v[102:105]
	v_mfma_f32_16x16x32_bf16 v[98:101], v[152:155], v[214:217], v[98:101]
	s_setprio 0
	s_setprio 1
	v_mfma_f32_16x16x32_bf16 v[94:97], v[156:159], v[186:189], v[94:97]
	v_mfma_f32_16x16x32_bf16 v[90:93], v[164:167], v[186:189], v[90:93]
	v_mfma_f32_16x16x32_bf16 v[86:89], v[156:159], v[194:197], v[86:89]
	v_mfma_f32_16x16x32_bf16 v[82:85], v[164:167], v[194:197], v[82:85]
	v_mfma_f32_16x16x32_bf16 v[78:81], v[156:159], v[202:205], v[78:81]
	v_mfma_f32_16x16x32_bf16 v[74:77], v[164:167], v[202:205], v[74:77]
	v_mfma_f32_16x16x32_bf16 v[70:73], v[156:159], v[210:213], v[70:73]
	v_mfma_f32_16x16x32_bf16 v[66:69], v[164:167], v[210:213], v[66:69]
	v_mfma_f32_16x16x32_bf16 v[94:97], v[160:163], v[190:193], v[94:97]
	v_mfma_f32_16x16x32_bf16 v[90:93], v[182:185], v[190:193], v[90:93]
	v_mfma_f32_16x16x32_bf16 v[86:89], v[160:163], v[198:201], v[86:89]
	v_mfma_f32_16x16x32_bf16 v[82:85], v[182:185], v[198:201], v[82:85]
	v_mfma_f32_16x16x32_bf16 v[78:81], v[160:163], v[206:209], v[78:81]
	v_mfma_f32_16x16x32_bf16 v[74:77], v[182:185], v[206:209], v[74:77]
	v_mfma_f32_16x16x32_bf16 v[70:73], v[160:163], v[214:217], v[70:73]
	v_mfma_f32_16x16x32_bf16 v[66:69], v[182:185], v[214:217], v[66:69]
	s_setprio 0
	s_barrier
	s_add_i32 s64, s4, s30
	v_lshl_add_u64 v[168:169], s[26:27], 0, v[0:1]
	s_mov_b32 m0, s64
	ds_read_b128 v[186:189], v147 offset:16384
	ds_read_b128 v[190:193], v147 offset:17408
	ds_read_b128 v[194:197], v147 offset:18432
	ds_read_b128 v[198:201], v147 offset:19456
	ds_read_b128 v[202:205], v147 offset:20480
	ds_read_b128 v[206:209], v147 offset:21504
	ds_read_b128 v[210:213], v147 offset:22528
	ds_read_b128 v[214:217], v147 offset:23552
	global_load_lds_dwordx4 v[168:169], off
	s_add_i32 m0, s64, 0x2000
	s_add_u32 s64, s26, 0x80000
	v_lshl_add_u64 v[218:219], s[26:27], 0, v[130:131]
	s_addc_u32 s65, s27, 0
	s_add_i32 s79, s5, s30
	global_load_lds_dwordx4 v[218:219], off
	v_lshl_add_u64 v[220:221], s[64:65], 0, v[0:1]
	s_mov_b32 m0, s79
	v_lshl_add_u64 v[222:223], s[28:29], 0, v[130:131]
	global_load_lds_dwordx4 v[220:221], off
	v_lshl_add_u64 v[220:221], s[64:65], 0, v[130:131]
	s_add_i32 m0, s79, 0x2000
	s_nop 0
	global_load_lds_dwordx4 v[220:221], off
	s_waitcnt vmcnt(6)
	s_waitcnt lgkmcnt(0)
	s_barrier
; #define PG8_STAGE(bufoff, gbase, voff) do { _Pragma("unroll") for (int _i = 0; _i < 2; ++_i) \
;         __builtin_amdgcn_global_load_lds((const unsigned*)((const char*)(gbase) + (voff)[_i]), (PG8_LAS unsigned*)(lds + (bufoff) + ldsw + _i * 8192), 16, 0, 0); } while (0)
; #define PG8_LDA(dst, b, h) do { _Pragma("unroll") for (int m = 0; m < 4; ++m) _Pragma("unroll") for (int k = 0; k < 2; ++k) dst[m][k] = *(const PG8_LAS bf16x8*)(lds + PG8_SA(b, h) + aoff + m * 2048 + k * 1024); } while (0)
; #define PG8_LDB(dst, b, h) do { _Pragma("unroll") for (int n = 0; n < 2; ++n) _Pragma("unroll") for (int k = 0; k < 2; ++k) dst[n][k] = *(const PG8_LAS bf16x8*)(lds + PG8_SB(b, h) + boff + n * 2048 + k * 1024); } while (0)
; #define PG8_MMA(ai, bj, At, Bt) do { __builtin_amdgcn_s_setprio(1); _Pragma("unroll") for (int m = 0; m < 4; ++m) _Pragma("unroll") for (int n = 0; n < 2; ++n) _Pragma("unroll") for (int k = 0; k < 2; ++k) \
;         acc[ai][bj][m][n] = __builtin_amdgcn_mfma_f32_16x16x32_bf16(Bt[n][k], At[m][k], acc[ai][bj][m][n], 0, 0, 0); __builtin_amdgcn_s_setprio(0); } while (0)
; #define PG8_WAIT_V(n) asm volatile("s_waitcnt vmcnt(" #n ")" ::: "memory")
; #define PG8_WAIT_L(n) asm volatile("s_waitcnt lgkmcnt(" #n ")" ::: "memory")
; #define PG8_BAR __builtin_amdgcn_s_barrier()
; #define PG8_SCHED __builtin_amdgcn_sched_barrier(0)
; template <class Epi, class Sched, bool ALIGN_EPI = false, bool SP2 = false>
; __device__ __forceinline__ void gemm_phase(PG8_LAS unsigned char* lds, const Gemm g, const Sched& S, const Epi& E, int tid_in) {
;     ...
;             PG8_LDA(At, 0, 1); PG8_STAGE(PG8_SB(0, 0), b2, voffB); PG8_STAGE(PG8_SB(0, 1), b2 + hstep, voffB); PG8_STAGE(PG8_SA(0, 0), a2, voffA);
;             PG8_WAIT_V(8); PG8_WAIT_L(0); PG8_BAR; PG8_MMA(1, 0, At, B0); PG8_MMA(1, 1, At, B1); PG8_BAR; PG8_SCHED;
;             PG8_LDB(B0, 1, 0); PG8_LDB(B1, 1, 1); PG8_SCHED; PG8_LDA(At, 1, 0); PG8_STAGE(PG8_SA(0, 1), a2 + hstepA, voffA);
;             PG8_WAIT_V(8); PG8_WAIT_L(0); PG8_BAR; PG8_MMA(0, 0, At, B0); PG8_MMA(0, 1, At, B1); PG8_BAR; PG8_SCHED;
	s_setprio 1
	s_waitcnt lgkmcnt(0)
	v_mfma_f32_16x16x32_bf16 v[62:65], v[136:139], v[186:189], v[62:65]
	v_mfma_f32_16x16x32_bf16 v[58:61], v[148:151], v[186:189], v[58:61]
	v_mfma_f32_16x16x32_bf16 v[54:57], v[136:139], v[194:197], v[54:57]
	v_mfma_f32_16x16x32_bf16 v[50:53], v[148:151], v[194:197], v[50:53]
	v_mfma_f32_16x16x32_bf16 v[46:49], v[136:139], v[202:205], v[46:49]
	v_mfma_f32_16x16x32_bf16 v[42:45], v[148:151], v[202:205], v[42:45]
	v_mfma_f32_16x16x32_bf16 v[38:41], v[136:139], v[210:213], v[38:41]
	v_mfma_f32_16x16x32_bf16 v[34:37], v[148:151], v[210:213], v[34:37]
	v_mfma_f32_16x16x32_bf16 v[62:65], v[140:143], v[190:193], v[62:65]
	v_mfma_f32_16x16x32_bf16 v[58:61], v[152:155], v[190:193], v[58:61]
	v_mfma_f32_16x16x32_bf16 v[54:57], v[140:143], v[198:201], v[54:57]
	v_mfma_f32_16x16x32_bf16 v[50:53], v[152:155], v[198:201], v[50:53]
	v_mfma_f32_16x16x32_bf16 v[46:49], v[140:143], v[206:209], v[46:49]
	v_mfma_f32_16x16x32_bf16 v[42:45], v[152:155], v[206:209], v[42:45]
	v_mfma_f32_16x16x32_bf16 v[38:41], v[140:143], v[214:217], v[38:41]
	v_mfma_f32_16x16x32_bf16 v[34:37], v[152:155], v[214:217], v[34:37]
	s_setprio 0
	s_setprio 1
	v_mfma_f32_16x16x32_bf16 v[30:33], v[156:159], v[186:189], v[30:33]
	v_mfma_f32_16x16x32_bf16 v[26:29], v[164:167], v[186:189], v[26:29]
	v_mfma_f32_16x16x32_bf16 v[22:25], v[156:159], v[194:197], v[22:25]
	v_mfma_f32_16x16x32_bf16 v[18:21], v[164:167], v[194:197], v[18:21]
	v_mfma_f32_16x16x32_bf16 v[14:17], v[156:159], v[202:205], v[14:17]
	v_mfma_f32_16x16x32_bf16 v[10:13], v[164:167], v[202:205], v[10:13]
	v_mfma_f32_16x16x32_bf16 v[6:9], v[156:159], v[210:213], v[6:9]
	v_mfma_f32_16x16x32_bf16 v[2:5], v[164:167], v[210:213], v[2:5]
	v_mfma_f32_16x16x32_bf16 v[30:33], v[160:163], v[190:193], v[30:33]
	v_mfma_f32_16x16x32_bf16 v[26:29], v[182:185], v[190:193], v[26:29]
	v_mfma_f32_16x16x32_bf16 v[22:25], v[160:163], v[198:201], v[22:25]
	v_mfma_f32_16x16x32_bf16 v[18:21], v[182:185], v[198:201], v[18:21]
	v_mfma_f32_16x16x32_bf16 v[14:17], v[160:163], v[206:209], v[14:17]
	v_mfma_f32_16x16x32_bf16 v[10:13], v[182:185], v[206:209], v[10:13]
	v_mfma_f32_16x16x32_bf16 v[6:9], v[160:163], v[214:217], v[6:9]
	v_mfma_f32_16x16x32_bf16 v[2:5], v[182:185], v[214:217], v[2:5]
	s_setprio 0
	s_barrier
	v_lshl_add_u64 v[220:221], s[28:29], 0, v[0:1]
	s_mov_b32 m0, s31
	s_nop 0
	global_load_lds_dwordx4 v[220:221], off
	s_mov_b32 m0, s33
	s_nop 0
	global_load_lds_dwordx4 v[222:223], off
	v_add_u32_e32 v152, s63, v146
	v_add_u32_e32 v182, s55, v146
	ds_read_b128 v[136:139], v152
	ds_read_b128 v[140:143], v152 offset:1024
	ds_read_b128 v[148:151], v152 offset:2048
	ds_read_b128 v[152:155], v152 offset:3072
	ds_read_b128 v[156:159], v182
	ds_read_b128 v[160:163], v182 offset:1024
	ds_read_b128 v[164:167], v182 offset:2048
	ds_read_b128 v[182:185], v182 offset:3072
	s_add_u32 s28, s28, 0x80000
	s_addc_u32 s29, s29, 0
	s_mov_b32 m0, s34
	v_lshl_add_u64 v[224:225], s[28:29], 0, v[0:1]
	ds_read_b128 v[186:189], v147 offset:32768
	ds_read_b128 v[190:193], v147 offset:33792
	ds_read_b128 v[194:197], v147 offset:34816
	ds_read_b128 v[198:201], v147 offset:35840
	ds_read_b128 v[202:205], v147 offset:36864
	ds_read_b128 v[206:209], v147 offset:37888
	ds_read_b128 v[210:213], v147 offset:38912
	ds_read_b128 v[214:217], v147 offset:39936
	global_load_lds_dwordx4 v[224:225], off
	v_lshl_add_u64 v[224:225], s[28:29], 0, v[130:131]
	s_mov_b32 m0, s35
	s_nop 0
	global_load_lds_dwordx4 v[224:225], off
	s_waitcnt vmcnt(8)
	s_waitcnt lgkmcnt(0)
	s_barrier
	s_setprio 1
	s_waitcnt lgkmcnt(0)
	v_mfma_f32_16x16x32_bf16 v[126:129], v[136:139], v[186:189], v[126:129]
	v_mfma_f32_16x16x32_bf16 v[122:125], v[148:151], v[186:189], v[122:125]
	v_mfma_f32_16x16x32_bf16 v[118:121], v[136:139], v[194:197], v[118:121]
	v_mfma_f32_16x16x32_bf16 v[114:117], v[148:151], v[194:197], v[114:117]
	v_mfma_f32_16x16x32_bf16 v[110:113], v[136:139], v[202:205], v[110:113]
	v_mfma_f32_16x16x32_bf16 v[106:109], v[148:151], v[202:205], v[106:109]
	v_mfma_f32_16x16x32_bf16 v[102:105], v[136:139], v[210:213], v[102:105]
	v_mfma_f32_16x16x32_bf16 v[98:101], v[148:151], v[210:213], v[98:101]
	v_mfma_f32_16x16x32_bf16 v[126:129], v[140:143], v[190:193], v[126:129]
	v_mfma_f32_16x16x32_bf16 v[122:125], v[152:155], v[190:193], v[122:125]
	v_mfma_f32_16x16x32_bf16 v[118:121], v[140:143], v[198:201], v[118:121]
	v_mfma_f32_16x16x32_bf16 v[114:117], v[152:155], v[198:201], v[114:117]
	v_mfma_f32_16x16x32_bf16 v[110:113], v[140:143], v[206:209], v[110:113]
	v_mfma_f32_16x16x32_bf16 v[106:109], v[152:155], v[206:209], v[106:109]
	v_mfma_f32_16x16x32_bf16 v[102:105], v[140:143], v[214:217], v[102:105]
	v_mfma_f32_16x16x32_bf16 v[98:101], v[152:155], v[214:217], v[98:101]
	s_setprio 0
	s_setprio 1
	v_mfma_f32_16x16x32_bf16 v[94:97], v[156:159], v[186:189], v[94:97]
	v_mfma_f32_16x16x32_bf16 v[90:93], v[164:167], v[186:189], v[90:93]
	v_mfma_f32_16x16x32_bf16 v[86:89], v[156:159], v[194:197], v[86:89]
	v_mfma_f32_16x16x32_bf16 v[82:85], v[164:167], v[194:197], v[82:85]
	v_mfma_f32_16x16x32_bf16 v[78:81], v[156:159], v[202:205], v[78:81]
	v_mfma_f32_16x16x32_bf16 v[74:77], v[164:167], v[202:205], v[74:77]
	v_mfma_f32_16x16x32_bf16 v[70:73], v[156:159], v[210:213], v[70:73]
	v_mfma_f32_16x16x32_bf16 v[66:69], v[164:167], v[210:213], v[66:69]
	v_mfma_f32_16x16x32_bf16 v[94:97], v[160:163], v[190:193], v[94:97]
	v_mfma_f32_16x16x32_bf16 v[90:93], v[182:185], v[190:193], v[90:93]
	v_mfma_f32_16x16x32_bf16 v[86:89], v[160:163], v[198:201], v[86:89]
	v_mfma_f32_16x16x32_bf16 v[82:85], v[182:185], v[198:201], v[82:85]
	v_mfma_f32_16x16x32_bf16 v[78:81], v[160:163], v[206:209], v[78:81]
	v_mfma_f32_16x16x32_bf16 v[74:77], v[182:185], v[206:209], v[74:77]
	v_mfma_f32_16x16x32_bf16 v[70:73], v[160:163], v[214:217], v[70:73]
	v_mfma_f32_16x16x32_bf16 v[66:69], v[182:185], v[214:217], v[66:69]
	s_setprio 0
	s_barrier
; #define PG8_STAGE(bufoff, gbase, voff) do { _Pragma("unroll") for (int _i = 0; _i < 2; ++_i) \
;         __builtin_amdgcn_global_load_lds((const unsigned*)((const char*)(gbase) + (voff)[_i]), (PG8_LAS unsigned*)(lds + (bufoff) + ldsw + _i * 8192), 16, 0, 0); } while (0)
; #define PG8_LDA(dst, b, h) do { _Pragma("unroll") for (int m = 0; m < 4; ++m) _Pragma("unroll") for (int k = 0; k < 2; ++k) dst[m][k] = *(const PG8_LAS bf16x8*)(lds + PG8_SA(b, h) + aoff + m * 2048 + k * 1024); } while (0)
; #define PG8_MMA(ai, bj, At, Bt) do { __builtin_amdgcn_s_setprio(1); _Pragma("unroll") for (int m = 0; m < 4; ++m) _Pragma("unroll") for (int n = 0; n < 2; ++n) _Pragma("unroll") for (int k = 0; k < 2; ++k) \
;         acc[ai][bj][m][n] = __builtin_amdgcn_mfma_f32_16x16x32_bf16(Bt[n][k], At[m][k], acc[ai][bj][m][n], 0, 0, 0); __builtin_amdgcn_s_setprio(0); } while (0)
; #define PG8_WAIT_V(n) asm volatile("s_waitcnt vmcnt(" #n ")" ::: "memory")
; #define PG8_WAIT_L(n) asm volatile("s_waitcnt lgkmcnt(" #n ")" ::: "memory")
; #define PG8_BAR __builtin_amdgcn_s_barrier()
; #define PG8_SCHED __builtin_amdgcn_sched_barrier(0)
; template <class Epi, class Sched, bool ALIGN_EPI = false, bool SP2 = false>
; __device__ __forceinline__ void gemm_phase(PG8_LAS unsigned char* lds, const Gemm g, const Sched& S, const Epi& E, int tid_in) {
;     ...
;         for (int t = 0; t < nt; t += 2) {
;             const bool last = (t == nt - 2);
;             const char* a1 = cA + (size_t)(t + 1) * kstep;
;             const char* a2 = last ? nA : cA + (size_t)(t + 2) * kstep; const char* b2 = last ? nB : cB + (size_t)(t + 2) * kstep;
;     ...
;             PG8_LDA(At, 1, 1); PG8_STAGE(PG8_SB(1, 0), b3, voffB); PG8_STAGE(PG8_SB(1, 1), b3 + hstep, voffB); PG8_STAGE(PG8_SA(1, 0), a3, voffA);
;             PG8_WAIT_V(8); PG8_WAIT_L(0); PG8_BAR; PG8_MMA(1, 0, At, B0); PG8_MMA(1, 1, At, B1); PG8_BAR; PG8_SCHED;
	s_add_i32 s28, s63, s30
	v_lshl_add_u64 v[168:169], v[168:169], 0, s[90:91]
	s_mov_b32 m0, s28
	ds_read_b128 v[186:189], v147 offset:49152
	ds_read_b128 v[190:193], v147 offset:50176
	ds_read_b128 v[194:197], v147 offset:51200
	ds_read_b128 v[198:201], v147 offset:52224
	ds_read_b128 v[202:205], v147 offset:53248
	ds_read_b128 v[206:209], v147 offset:54272
	ds_read_b128 v[210:213], v147 offset:55296
	ds_read_b128 v[214:217], v147 offset:56320
	global_load_lds_dwordx4 v[168:169], off
	s_add_i32 m0, s28, 0x2000
	s_add_u32 s26, s26, 0x80080
	v_lshl_add_u64 v[168:169], v[218:219], 0, s[90:91]
	s_addc_u32 s27, s27, 0
	s_add_i32 s28, s55, s30
	global_load_lds_dwordx4 v[168:169], off
	v_lshl_add_u64 v[168:169], s[26:27], 0, v[0:1]
	s_mov_b32 m0, s28
	s_nop 0
	global_load_lds_dwordx4 v[168:169], off
	v_lshl_add_u64 v[168:169], s[26:27], 0, v[130:131]
	s_add_i32 m0, s28, 0x2000
	s_nop 0
	global_load_lds_dwordx4 v[168:169], off
	v_lshl_add_u64 v[168:169], v[220:221], 0, s[90:91]
	s_mov_b32 m0, s41
	s_nop 0
	global_load_lds_dwordx4 v[168:169], off
	v_lshl_add_u64 v[168:169], v[222:223], 0, s[90:91]
	s_mov_b32 m0, s42
	s_nop 0
	global_load_lds_dwordx4 v[168:169], off
	s_waitcnt vmcnt(8)
	s_waitcnt lgkmcnt(0)
	s_barrier
	s_setprio 1
	s_waitcnt lgkmcnt(0)
	v_mfma_f32_16x16x32_bf16 v[62:65], v[136:139], v[186:189], v[62:65]
	v_mfma_f32_16x16x32_bf16 v[58:61], v[148:151], v[186:189], v[58:61]
	v_mfma_f32_16x16x32_bf16 v[54:57], v[136:139], v[194:197], v[54:57]
	v_mfma_f32_16x16x32_bf16 v[50:53], v[148:151], v[194:197], v[50:53]
	v_mfma_f32_16x16x32_bf16 v[46:49], v[136:139], v[202:205], v[46:49]
	v_mfma_f32_16x16x32_bf16 v[42:45], v[148:151], v[202:205], v[42:45]
	v_mfma_f32_16x16x32_bf16 v[38:41], v[136:139], v[210:213], v[38:41]
	v_mfma_f32_16x16x32_bf16 v[34:37], v[148:151], v[210:213], v[34:37]
	v_mfma_f32_16x16x32_bf16 v[62:65], v[140:143], v[190:193], v[62:65]
	v_mfma_f32_16x16x32_bf16 v[58:61], v[152:155], v[190:193], v[58:61]
	v_mfma_f32_16x16x32_bf16 v[54:57], v[140:143], v[198:201], v[54:57]
	v_mfma_f32_16x16x32_bf16 v[50:53], v[152:155], v[198:201], v[50:53]
	v_mfma_f32_16x16x32_bf16 v[46:49], v[140:143], v[206:209], v[46:49]
	v_mfma_f32_16x16x32_bf16 v[42:45], v[152:155], v[206:209], v[42:45]
	v_mfma_f32_16x16x32_bf16 v[38:41], v[140:143], v[214:217], v[38:41]
	v_mfma_f32_16x16x32_bf16 v[34:37], v[152:155], v[214:217], v[34:37]
	s_setprio 0
	s_setprio 1
	v_mfma_f32_16x16x32_bf16 v[30:33], v[156:159], v[186:189], v[30:33]
	v_mfma_f32_16x16x32_bf16 v[26:29], v[164:167], v[186:189], v[26:29]
	v_mfma_f32_16x16x32_bf16 v[22:25], v[156:159], v[194:197], v[22:25]
	v_mfma_f32_16x16x32_bf16 v[18:21], v[164:167], v[194:197], v[18:21]
	v_mfma_f32_16x16x32_bf16 v[14:17], v[156:159], v[202:205], v[14:17]
	v_mfma_f32_16x16x32_bf16 v[10:13], v[164:167], v[202:205], v[10:13]
	v_mfma_f32_16x16x32_bf16 v[6:9], v[156:159], v[210:213], v[6:9]
	v_mfma_f32_16x16x32_bf16 v[2:5], v[164:167], v[210:213], v[2:5]
	v_mfma_f32_16x16x32_bf16 v[30:33], v[160:163], v[190:193], v[30:33]
	v_mfma_f32_16x16x32_bf16 v[26:29], v[182:185], v[190:193], v[26:29]
	v_mfma_f32_16x16x32_bf16 v[22:25], v[160:163], v[198:201], v[22:25]
	v_mfma_f32_16x16x32_bf16 v[18:21], v[182:185], v[198:201], v[18:21]
	v_mfma_f32_16x16x32_bf16 v[14:17], v[160:163], v[206:209], v[14:17]
	v_mfma_f32_16x16x32_bf16 v[10:13], v[182:185], v[206:209], v[10:13]
	v_mfma_f32_16x16x32_bf16 v[6:9], v[160:163], v[214:217], v[6:9]
	v_mfma_f32_16x16x32_bf16 v[2:5], v[182:185], v[214:217], v[2:5]
	s_setprio 0
	s_barrier
	s_add_u32 s24, s24, 0x100
	s_addc_u32 s25, s25, 0
	s_add_u32 s68, s68, 0x100
	s_addc_u32 s70, s70, 0
	s_cmp_ge_u32 s76, s45
	s_mov_b32 s26, s76
	s_cbranch_scc0 .LBB0_1348
	s_and_b64 vcc, exec, s[16:17]
	s_cbranch_vccz .LBB0_1351
	s_barrier

; #define PG8_STAGE(bufoff, gbase, voff) do { _Pragma("unroll") for (int _i = 0; _i < 2; ++_i) \
;         __builtin_amdgcn_global_load_lds((const unsigned*)((const char*)(gbase) + (voff)[_i]), (PG8_LAS unsigned*)(lds + (bufoff) + ldsw + _i * 8192), 16, 0, 0); } while (0)
; #define PG8_LDA(dst, b, h) do { _Pragma("unroll") for (int m = 0; m < 4; ++m) _Pragma("unroll") for (int k = 0; k < 2; ++k) dst[m][k] = *(const PG8_LAS bf16x8*)(lds + PG8_SA(b, h) + aoff + m * 2048 + k * 1024); } while (0)
; #define PG8_LDB(dst, b, h) do { _Pragma("unroll") for (int n = 0; n < 2; ++n) _Pragma("unroll") for (int k = 0; k < 2; ++k) dst[n][k] = *(const PG8_LAS bf16x8*)(lds + PG8_SB(b, h) + boff + n * 2048 + k * 1024); } while (0)
; #define PG8_MMA(ai, bj, At, Bt) do { __builtin_amdgcn_s_setprio(1); _Pragma("unroll") for (int m = 0; m < 4; ++m) _Pragma("unroll") for (int n = 0; n < 2; ++n) _Pragma("unroll") for (int k = 0; k < 2; ++k) \
;         acc[ai][bj][m][n] = __builtin_amdgcn_mfma_f32_16x16x32_bf16(Bt[n][k], At[m][k], acc[ai][bj][m][n], 0, 0, 0); __builtin_amdgcn_s_setprio(0); } while (0)
; #define PG8_WAIT_V(n) asm volatile("s_waitcnt vmcnt(" #n ")" ::: "memory")
; #define PG8_WAIT_L(n) asm volatile("s_waitcnt lgkmcnt(" #n ")" ::: "memory")
; #define PG8_BAR __builtin_amdgcn_s_barrier()
; #define PG8_SCHED __builtin_amdgcn_sched_barrier(0)
; template <class Epi, class Sched, bool ALIGN_EPI = false, bool SP2 = false>
; __device__ __forceinline__ void gemm_phase(PG8_LAS unsigned char* lds, const Gemm g, const Sched& S, const Epi& E, int tid_in) {
;     ...
;         for (int t = 0; t < nt; t += 2) {
;             const bool last = (t == nt - 2);
;             const char* a1 = cA + (size_t)(t + 1) * kstep;
;             const char* a2 = last ? nA : cA + (size_t)(t + 2) * kstep; const char* b2 = last ? nB : cB + (size_t)(t + 2) * kstep;
;             const char* a3 = a2 + kstep; const char* b3 = b2 + kstep;
;             if (last && has_next) S.a_ready(nxt);
;             if constexpr (SP2) {
;             PG8_LDB(B0, 0, 0); PG8_LDB(B1, 0, 1); PG8_SCHED; PG8_LDA(At, 0, 0); PG8_STAGE(PG8_SA(1, 1), a1 + hstepA, voffA);
;             PG8_WAIT_V(8); PG8_WAIT_L(0); PG8_BAR; PG8_MMA(0, 0, At, B0); PG8_MMA(0, 1, At, B1); PG8_BAR; PG8_SCHED;
;             PG8_LDA(At, 0, 1); PG8_STAGE(PG8_SB(0, 0), b2, voffB); PG8_STAGE(PG8_SB(0, 1), b2 + hstep, voffB); PG8_STAGE(PG8_SA(0, 0), a2, voffA);
.LBB0_1507:
	v_add_u32_e32 v158, s4, v152
	v_add_u32_e32 v186, s5, v152
	ds_read_b128 v[142:145], v158
	ds_read_b128 v[146:149], v158 offset:1024
	ds_read_b128 v[154:157], v158 offset:2048
	ds_read_b128 v[158:161], v158 offset:3072
	ds_read_b128 v[162:165], v186
	ds_read_b128 v[166:169], v186 offset:1024
	ds_read_b128 v[182:185], v186 offset:2048
	ds_read_b128 v[186:189], v186 offset:3072
	s_add_u32 s26, s24, 0xfff80080
	s_addc_u32 s27, s25, -1
	s_cmp_eq_u32 s23, 28
	s_cselect_b32 s29, s19, s27
	s_cselect_b32 s28, s18, s26
	s_cselect_b32 s27, s21, s17
	s_cselect_b32 s26, s20, s15
	v_lshl_add_u64 v[222:223], s[24:25], 0, v[138:139]
	s_add_i32 m0, s35, 0xc000
	ds_read_b128 v[190:193], v153
	ds_read_b128 v[194:197], v153 offset:1024
	ds_read_b128 v[198:201], v153 offset:2048
	ds_read_b128 v[202:205], v153 offset:3072
	ds_read_b128 v[206:209], v153 offset:4096
	ds_read_b128 v[210:213], v153 offset:5120
	ds_read_b128 v[214:217], v153 offset:6144
	ds_read_b128 v[218:221], v153 offset:7168
	global_load_lds_dwordx4 v[222:223], off
	v_lshl_add_u64 v[222:223], s[24:25], 0, v[140:141]
	s_add_i32 m0, s35, 0xe000
	s_nop 0
	global_load_lds_dwordx4 v[222:223], off
	s_waitcnt vmcnt(8)
	s_waitcnt lgkmcnt(0)
	s_barrier
	s_setprio 1
	s_waitcnt lgkmcnt(0)
	v_mfma_f32_16x16x32_bf16 v[126:129], v[142:145], v[190:193], v[126:129]
	v_mfma_f32_16x16x32_bf16 v[118:121], v[154:157], v[190:193], v[118:121]
	v_mfma_f32_16x16x32_bf16 v[110:113], v[142:145], v[198:201], v[110:113]
	v_mfma_f32_16x16x32_bf16 v[102:105], v[154:157], v[198:201], v[102:105]
	v_mfma_f32_16x16x32_bf16 v[94:97], v[142:145], v[206:209], v[94:97]
	v_mfma_f32_16x16x32_bf16 v[86:89], v[154:157], v[206:209], v[86:89]
	v_mfma_f32_16x16x32_bf16 v[78:81], v[142:145], v[214:217], v[78:81]
	v_mfma_f32_16x16x32_bf16 v[70:73], v[154:157], v[214:217], v[70:73]
	v_mfma_f32_16x16x32_bf16 v[126:129], v[146:149], v[194:197], v[126:129]
	v_mfma_f32_16x16x32_bf16 v[118:121], v[158:161], v[194:197], v[118:121]
	v_mfma_f32_16x16x32_bf16 v[110:113], v[146:149], v[202:205], v[110:113]
	v_mfma_f32_16x16x32_bf16 v[102:105], v[158:161], v[202:205], v[102:105]
	v_mfma_f32_16x16x32_bf16 v[94:97], v[146:149], v[210:213], v[94:97]
	v_mfma_f32_16x16x32_bf16 v[86:89], v[158:161], v[210:213], v[86:89]
	v_mfma_f32_16x16x32_bf16 v[78:81], v[146:149], v[218:221], v[78:81]
	v_mfma_f32_16x16x32_bf16 v[70:73], v[158:161], v[218:221], v[70:73]
	s_setprio 0
	s_setprio 1
	v_mfma_f32_16x16x32_bf16 v[122:125], v[162:165], v[190:193], v[122:125]
	v_mfma_f32_16x16x32_bf16 v[114:117], v[182:185], v[190:193], v[114:117]
	v_mfma_f32_16x16x32_bf16 v[106:109], v[162:165], v[198:201], v[106:109]
	v_mfma_f32_16x16x32_bf16 v[98:101], v[182:185], v[198:201], v[98:101]
	v_mfma_f32_16x16x32_bf16 v[90:93], v[162:165], v[206:209], v[90:93]
	v_mfma_f32_16x16x32_bf16 v[82:85], v[182:185], v[206:209], v[82:85]
	v_mfma_f32_16x16x32_bf16 v[74:77], v[162:165], v[214:217], v[74:77]
	v_mfma_f32_16x16x32_bf16 v[66:69], v[182:185], v[214:217], v[66:69]
	v_mfma_f32_16x16x32_bf16 v[122:125], v[166:169], v[194:197], v[122:125]
	v_mfma_f32_16x16x32_bf16 v[114:117], v[186:189], v[194:197], v[114:117]
	v_mfma_f32_16x16x32_bf16 v[106:109], v[166:169], v[202:205], v[106:109]
	v_mfma_f32_16x16x32_bf16 v[98:101], v[186:189], v[202:205], v[98:101]
	v_mfma_f32_16x16x32_bf16 v[90:93], v[166:169], v[210:213], v[90:93]
	v_mfma_f32_16x16x32_bf16 v[82:85], v[186:189], v[210:213], v[82:85]
	v_mfma_f32_16x16x32_bf16 v[74:77], v[166:169], v[218:221], v[74:77]
	v_mfma_f32_16x16x32_bf16 v[66:69], v[186:189], v[218:221], v[66:69]
	s_setprio 0
	s_barrier
	s_add_i32 s47, s4, s34
	v_lshl_add_u64 v[222:223], s[26:27], 0, v[0:1]
	s_mov_b32 m0, s47
	ds_read_b128 v[190:193], v153 offset:16384
	ds_read_b128 v[194:197], v153 offset:17408
	ds_read_b128 v[198:201], v153 offset:18432
	ds_read_b128 v[202:205], v153 offset:19456
	ds_read_b128 v[206:209], v153 offset:20480
	ds_read_b128 v[210:213], v153 offset:21504
	ds_read_b128 v[214:217], v153 offset:22528
	ds_read_b128 v[218:221], v153 offset:23552
	global_load_lds_dwordx4 v[222:223], off
	s_add_i32 m0, s47, 0x2000
	s_add_u32 s48, s26, 0x80000
	v_lshl_add_u64 v[224:225], s[26:27], 0, v[130:131]
	s_addc_u32 s49, s27, 0
	s_add_i32 s47, s5, s34
	global_load_lds_dwordx4 v[224:225], off
	v_lshl_add_u64 v[226:227], s[48:49], 0, v[0:1]
	s_mov_b32 m0, s47
	v_lshl_add_u64 v[228:229], s[28:29], 0, v[132:133]
	global_load_lds_dwordx4 v[226:227], off
	v_lshl_add_u64 v[226:227], s[48:49], 0, v[130:131]
	s_add_i32 m0, s47, 0x2000
	s_nop 0
	global_load_lds_dwordx4 v[226:227], off
	s_waitcnt vmcnt(6)
	s_waitcnt lgkmcnt(0)
	s_barrier
; #define PG8_STAGE(bufoff, gbase, voff) do { _Pragma("unroll") for (int _i = 0; _i < 2; ++_i) \
;         __builtin_amdgcn_global_load_lds((const unsigned*)((const char*)(gbase) + (voff)[_i]), (PG8_LAS unsigned*)(lds + (bufoff) + ldsw + _i * 8192), 16, 0, 0); } while (0)
; #define PG8_LDA(dst, b, h) do { _Pragma("unroll") for (int m = 0; m < 4; ++m) _Pragma("unroll") for (int k = 0; k < 2; ++k) dst[m][k] = *(const PG8_LAS bf16x8*)(lds + PG8_SA(b, h) + aoff + m * 2048 + k * 1024); } while (0)
; #define PG8_LDB(dst, b, h) do { _Pragma("unroll") for (int n = 0; n < 2; ++n) _Pragma("unroll") for (int k = 0; k < 2; ++k) dst[n][k] = *(const PG8_LAS bf16x8*)(lds + PG8_SB(b, h) + boff + n * 2048 + k * 1024); } while (0)
; #define PG8_MMA(ai, bj, At, Bt) do { __builtin_amdgcn_s_setprio(1); _Pragma("unroll") for (int m = 0; m < 4; ++m) _Pragma("unroll") for (int n = 0; n < 2; ++n) _Pragma("unroll") for (int k = 0; k < 2; ++k) \
;         acc[ai][bj][m][n] = __builtin_amdgcn_mfma_f32_16x16x32_bf16(Bt[n][k], At[m][k], acc[ai][bj][m][n], 0, 0, 0); __builtin_amdgcn_s_setprio(0); } while (0)
; #define PG8_WAIT_V(n) asm volatile("s_waitcnt vmcnt(" #n ")" ::: "memory")
; #define PG8_WAIT_L(n) asm volatile("s_waitcnt lgkmcnt(" #n ")" ::: "memory")
; #define PG8_BAR __builtin_amdgcn_s_barrier()
; #define PG8_SCHED __builtin_amdgcn_sched_barrier(0)
; template <class Epi, class Sched, bool ALIGN_EPI = false, bool SP2 = false>
; __device__ __forceinline__ void gemm_phase(PG8_LAS unsigned char* lds, const Gemm g, const Sched& S, const Epi& E, int tid_in) {
;     ...
;             PG8_LDA(At, 0, 1); PG8_STAGE(PG8_SB(0, 0), b2, voffB); PG8_STAGE(PG8_SB(0, 1), b2 + hstep, voffB); PG8_STAGE(PG8_SA(0, 0), a2, voffA);
;             PG8_WAIT_V(8); PG8_WAIT_L(0); PG8_BAR; PG8_MMA(1, 0, At, B0); PG8_MMA(1, 1, At, B1); PG8_BAR; PG8_SCHED;
;             PG8_LDB(B0, 1, 0); PG8_LDB(B1, 1, 1); PG8_SCHED; PG8_LDA(At, 1, 0); PG8_STAGE(PG8_SA(0, 1), a2 + hstepA, voffA);
;             PG8_WAIT_V(8); PG8_WAIT_L(0); PG8_BAR; PG8_MMA(0, 0, At, B0); PG8_MMA(0, 1, At, B1); PG8_BAR; PG8_SCHED;
	s_setprio 1
	s_waitcnt lgkmcnt(0)
	v_mfma_f32_16x16x32_bf16 v[62:65], v[142:145], v[190:193], v[62:65]
	v_mfma_f32_16x16x32_bf16 v[54:57], v[154:157], v[190:193], v[54:57]
	v_mfma_f32_16x16x32_bf16 v[46:49], v[142:145], v[198:201], v[46:49]
	v_mfma_f32_16x16x32_bf16 v[38:41], v[154:157], v[198:201], v[38:41]
	v_mfma_f32_16x16x32_bf16 v[30:33], v[142:145], v[206:209], v[30:33]
	v_mfma_f32_16x16x32_bf16 v[22:25], v[154:157], v[206:209], v[22:25]
	v_mfma_f32_16x16x32_bf16 v[14:17], v[142:145], v[214:217], v[14:17]
	v_mfma_f32_16x16x32_bf16 v[6:9], v[154:157], v[214:217], v[6:9]
	v_mfma_f32_16x16x32_bf16 v[62:65], v[146:149], v[194:197], v[62:65]
	v_mfma_f32_16x16x32_bf16 v[54:57], v[158:161], v[194:197], v[54:57]
	v_mfma_f32_16x16x32_bf16 v[46:49], v[146:149], v[202:205], v[46:49]
	v_mfma_f32_16x16x32_bf16 v[38:41], v[158:161], v[202:205], v[38:41]
	v_mfma_f32_16x16x32_bf16 v[30:33], v[146:149], v[210:213], v[30:33]
	v_mfma_f32_16x16x32_bf16 v[22:25], v[158:161], v[210:213], v[22:25]
	v_mfma_f32_16x16x32_bf16 v[14:17], v[146:149], v[218:221], v[14:17]
	v_mfma_f32_16x16x32_bf16 v[6:9], v[158:161], v[218:221], v[6:9]
	s_setprio 0
	s_setprio 1
	v_mfma_f32_16x16x32_bf16 v[58:61], v[162:165], v[190:193], v[58:61]
	v_mfma_f32_16x16x32_bf16 v[50:53], v[182:185], v[190:193], v[50:53]
	v_mfma_f32_16x16x32_bf16 v[42:45], v[162:165], v[198:201], v[42:45]
	v_mfma_f32_16x16x32_bf16 v[34:37], v[182:185], v[198:201], v[34:37]
	v_mfma_f32_16x16x32_bf16 v[26:29], v[162:165], v[206:209], v[26:29]
	v_mfma_f32_16x16x32_bf16 v[18:21], v[182:185], v[206:209], v[18:21]
	v_mfma_f32_16x16x32_bf16 v[10:13], v[162:165], v[214:217], v[10:13]
	v_mfma_f32_16x16x32_bf16 v[2:5], v[182:185], v[214:217], v[2:5]
	v_mfma_f32_16x16x32_bf16 v[58:61], v[166:169], v[194:197], v[58:61]
	v_mfma_f32_16x16x32_bf16 v[50:53], v[186:189], v[194:197], v[50:53]
	v_mfma_f32_16x16x32_bf16 v[42:45], v[166:169], v[202:205], v[42:45]
	v_mfma_f32_16x16x32_bf16 v[34:37], v[186:189], v[202:205], v[34:37]
	v_mfma_f32_16x16x32_bf16 v[26:29], v[166:169], v[210:213], v[26:29]
	v_mfma_f32_16x16x32_bf16 v[18:21], v[186:189], v[210:213], v[18:21]
	v_mfma_f32_16x16x32_bf16 v[10:13], v[166:169], v[218:221], v[10:13]
	v_mfma_f32_16x16x32_bf16 v[2:5], v[186:189], v[218:221], v[2:5]
	s_setprio 0
	s_barrier
	v_lshl_add_u64 v[226:227], s[28:29], 0, v[134:135]
	s_mov_b32 m0, s35
	s_nop 0
	global_load_lds_dwordx4 v[226:227], off
	s_mov_b32 m0, s36
	s_nop 0
	global_load_lds_dwordx4 v[228:229], off
	v_add_u32_e32 v158, s63, v152
	v_add_u32_e32 v186, s55, v152
	ds_read_b128 v[142:145], v158
	ds_read_b128 v[146:149], v158 offset:1024
	ds_read_b128 v[154:157], v158 offset:2048
	ds_read_b128 v[158:161], v158 offset:3072
	ds_read_b128 v[162:165], v186
	ds_read_b128 v[166:169], v186 offset:1024
	ds_read_b128 v[182:185], v186 offset:2048
	ds_read_b128 v[186:189], v186 offset:3072
	s_add_u32 s28, s28, 0x80000
	s_addc_u32 s29, s29, 0
	s_mov_b32 m0, s37
	v_lshl_add_u64 v[240:241], s[28:29], 0, v[134:135]
	ds_read_b128 v[190:193], v153 offset:32768
	ds_read_b128 v[194:197], v153 offset:33792
	ds_read_b128 v[198:201], v153 offset:34816
	ds_read_b128 v[202:205], v153 offset:35840
	ds_read_b128 v[206:209], v153 offset:36864
	ds_read_b128 v[210:213], v153 offset:37888
	ds_read_b128 v[214:217], v153 offset:38912
	ds_read_b128 v[218:221], v153 offset:39936
	global_load_lds_dwordx4 v[240:241], off
	v_lshl_add_u64 v[240:241], s[28:29], 0, v[132:133]
	s_mov_b32 m0, s38
	s_nop 0
	global_load_lds_dwordx4 v[240:241], off
	s_waitcnt vmcnt(8)
	s_waitcnt lgkmcnt(0)
	s_barrier
	s_setprio 1
	s_waitcnt lgkmcnt(0)
	v_mfma_f32_16x16x32_bf16 v[126:129], v[142:145], v[190:193], v[126:129]
	v_mfma_f32_16x16x32_bf16 v[118:121], v[154:157], v[190:193], v[118:121]
	v_mfma_f32_16x16x32_bf16 v[110:113], v[142:145], v[198:201], v[110:113]
	v_mfma_f32_16x16x32_bf16 v[102:105], v[154:157], v[198:201], v[102:105]
	v_mfma_f32_16x16x32_bf16 v[94:97], v[142:145], v[206:209], v[94:97]
	v_mfma_f32_16x16x32_bf16 v[86:89], v[154:157], v[206:209], v[86:89]
	v_mfma_f32_16x16x32_bf16 v[78:81], v[142:145], v[214:217], v[78:81]
	v_mfma_f32_16x16x32_bf16 v[70:73], v[154:157], v[214:217], v[70:73]
	v_mfma_f32_16x16x32_bf16 v[126:129], v[146:149], v[194:197], v[126:129]
	v_mfma_f32_16x16x32_bf16 v[118:121], v[158:161], v[194:197], v[118:121]
	v_mfma_f32_16x16x32_bf16 v[110:113], v[146:149], v[202:205], v[110:113]
	v_mfma_f32_16x16x32_bf16 v[102:105], v[158:161], v[202:205], v[102:105]
	v_mfma_f32_16x16x32_bf16 v[94:97], v[146:149], v[210:213], v[94:97]
	v_mfma_f32_16x16x32_bf16 v[86:89], v[158:161], v[210:213], v[86:89]
	v_mfma_f32_16x16x32_bf16 v[78:81], v[146:149], v[218:221], v[78:81]
	v_mfma_f32_16x16x32_bf16 v[70:73], v[158:161], v[218:221], v[70:73]
	s_setprio 0
	s_setprio 1
	v_mfma_f32_16x16x32_bf16 v[122:125], v[162:165], v[190:193], v[122:125]
	v_mfma_f32_16x16x32_bf16 v[114:117], v[182:185], v[190:193], v[114:117]
	v_mfma_f32_16x16x32_bf16 v[106:109], v[162:165], v[198:201], v[106:109]
	v_mfma_f32_16x16x32_bf16 v[98:101], v[182:185], v[198:201], v[98:101]
	v_mfma_f32_16x16x32_bf16 v[90:93], v[162:165], v[206:209], v[90:93]
	v_mfma_f32_16x16x32_bf16 v[82:85], v[182:185], v[206:209], v[82:85]
	v_mfma_f32_16x16x32_bf16 v[74:77], v[162:165], v[214:217], v[74:77]
	v_mfma_f32_16x16x32_bf16 v[66:69], v[182:185], v[214:217], v[66:69]
	v_mfma_f32_16x16x32_bf16 v[122:125], v[166:169], v[194:197], v[122:125]
	v_mfma_f32_16x16x32_bf16 v[114:117], v[186:189], v[194:197], v[114:117]
	v_mfma_f32_16x16x32_bf16 v[106:109], v[166:169], v[202:205], v[106:109]
	v_mfma_f32_16x16x32_bf16 v[98:101], v[186:189], v[202:205], v[98:101]
	v_mfma_f32_16x16x32_bf16 v[90:93], v[166:169], v[210:213], v[90:93]
	v_mfma_f32_16x16x32_bf16 v[82:85], v[186:189], v[210:213], v[82:85]
	v_mfma_f32_16x16x32_bf16 v[74:77], v[166:169], v[218:221], v[74:77]
	v_mfma_f32_16x16x32_bf16 v[66:69], v[186:189], v[218:221], v[66:69]
	s_setprio 0
	s_barrier
; #define PG8_STAGE(bufoff, gbase, voff) do { _Pragma("unroll") for (int _i = 0; _i < 2; ++_i) \
;         __builtin_amdgcn_global_load_lds((const unsigned*)((const char*)(gbase) + (voff)[_i]), (PG8_LAS unsigned*)(lds + (bufoff) + ldsw + _i * 8192), 16, 0, 0); } while (0)
; #define PG8_LDA(dst, b, h) do { _Pragma("unroll") for (int m = 0; m < 4; ++m) _Pragma("unroll") for (int k = 0; k < 2; ++k) dst[m][k] = *(const PG8_LAS bf16x8*)(lds + PG8_SA(b, h) + aoff + m * 2048 + k * 1024); } while (0)
; #define PG8_MMA(ai, bj, At, Bt) do { __builtin_amdgcn_s_setprio(1); _Pragma("unroll") for (int m = 0; m < 4; ++m) _Pragma("unroll") for (int n = 0; n < 2; ++n) _Pragma("unroll") for (int k = 0; k < 2; ++k) \
;         acc[ai][bj][m][n] = __builtin_amdgcn_mfma_f32_16x16x32_bf16(Bt[n][k], At[m][k], acc[ai][bj][m][n], 0, 0, 0); __builtin_amdgcn_s_setprio(0); } while (0)
; #define PG8_WAIT_V(n) asm volatile("s_waitcnt vmcnt(" #n ")" ::: "memory")
; #define PG8_WAIT_L(n) asm volatile("s_waitcnt lgkmcnt(" #n ")" ::: "memory")
; #define PG8_BAR __builtin_amdgcn_s_barrier()
; #define PG8_SCHED __builtin_amdgcn_sched_barrier(0)
; template <class Epi, class Sched, bool ALIGN_EPI = false, bool SP2 = false>
; __device__ __forceinline__ void gemm_phase(PG8_LAS unsigned char* lds, const Gemm g, const Sched& S, const Epi& E, int tid_in) {
;     ...
;         for (int t = 0; t < nt; t += 2) {
;             const bool last = (t == nt - 2);
;             const char* a1 = cA + (size_t)(t + 1) * kstep;
;             const char* a2 = last ? nA : cA + (size_t)(t + 2) * kstep; const char* b2 = last ? nB : cB + (size_t)(t + 2) * kstep;
;     ...
;             PG8_LDA(At, 1, 1); PG8_STAGE(PG8_SB(1, 0), b3, voffB); PG8_STAGE(PG8_SB(1, 1), b3 + hstep, voffB); PG8_STAGE(PG8_SA(1, 0), a3, voffA);
;             PG8_WAIT_V(8); PG8_WAIT_L(0); PG8_BAR; PG8_MMA(1, 0, At, B0); PG8_MMA(1, 1, At, B1); PG8_BAR; PG8_SCHED;
	s_add_i32 s28, s63, s34
	v_lshl_add_u64 v[222:223], v[222:223], 0, s[90:91]
	s_mov_b32 m0, s28
	ds_read_b128 v[190:193], v153 offset:49152
	ds_read_b128 v[194:197], v153 offset:50176
	ds_read_b128 v[198:201], v153 offset:51200
	ds_read_b128 v[202:205], v153 offset:52224
	ds_read_b128 v[206:209], v153 offset:53248
	ds_read_b128 v[210:213], v153 offset:54272
	ds_read_b128 v[214:217], v153 offset:55296
	ds_read_b128 v[218:221], v153 offset:56320
	global_load_lds_dwordx4 v[222:223], off
	s_add_i32 m0, s28, 0x2000
	s_add_u32 s26, s26, 0x80080
	v_lshl_add_u64 v[222:223], v[224:225], 0, s[90:91]
	s_addc_u32 s27, s27, 0
	s_add_i32 s28, s55, s34
	global_load_lds_dwordx4 v[222:223], off
	v_lshl_add_u64 v[222:223], s[26:27], 0, v[0:1]
	s_mov_b32 m0, s28
	s_nop 0
	global_load_lds_dwordx4 v[222:223], off
	v_lshl_add_u64 v[222:223], s[26:27], 0, v[130:131]
	s_add_i32 m0, s28, 0x2000
	s_nop 0
	global_load_lds_dwordx4 v[222:223], off
	v_lshl_add_u64 v[222:223], v[226:227], 0, s[90:91]
	s_mov_b32 m0, s41
	s_nop 0
	global_load_lds_dwordx4 v[222:223], off
	v_lshl_add_u64 v[222:223], v[228:229], 0, s[90:91]
	s_mov_b32 m0, s42
	s_nop 0
	global_load_lds_dwordx4 v[222:223], off
	s_waitcnt vmcnt(8)
	s_waitcnt lgkmcnt(0)
	s_barrier
	s_setprio 1
	s_waitcnt lgkmcnt(0)
	v_mfma_f32_16x16x32_bf16 v[62:65], v[142:145], v[190:193], v[62:65]
	v_mfma_f32_16x16x32_bf16 v[54:57], v[154:157], v[190:193], v[54:57]
	v_mfma_f32_16x16x32_bf16 v[46:49], v[142:145], v[198:201], v[46:49]
	v_mfma_f32_16x16x32_bf16 v[38:41], v[154:157], v[198:201], v[38:41]
	v_mfma_f32_16x16x32_bf16 v[30:33], v[142:145], v[206:209], v[30:33]
	v_mfma_f32_16x16x32_bf16 v[22:25], v[154:157], v[206:209], v[22:25]
	v_mfma_f32_16x16x32_bf16 v[14:17], v[142:145], v[214:217], v[14:17]
	v_mfma_f32_16x16x32_bf16 v[6:9], v[154:157], v[214:217], v[6:9]
	v_mfma_f32_16x16x32_bf16 v[62:65], v[146:149], v[194:197], v[62:65]
	v_mfma_f32_16x16x32_bf16 v[54:57], v[158:161], v[194:197], v[54:57]
	v_mfma_f32_16x16x32_bf16 v[46:49], v[146:149], v[202:205], v[46:49]
	v_mfma_f32_16x16x32_bf16 v[38:41], v[158:161], v[202:205], v[38:41]
	v_mfma_f32_16x16x32_bf16 v[30:33], v[146:149], v[210:213], v[30:33]
	v_mfma_f32_16x16x32_bf16 v[22:25], v[158:161], v[210:213], v[22:25]
	v_mfma_f32_16x16x32_bf16 v[14:17], v[146:149], v[218:221], v[14:17]
	v_mfma_f32_16x16x32_bf16 v[6:9], v[158:161], v[218:221], v[6:9]
	s_setprio 0
	s_setprio 1
	v_mfma_f32_16x16x32_bf16 v[58:61], v[162:165], v[190:193], v[58:61]
	v_mfma_f32_16x16x32_bf16 v[50:53], v[182:185], v[190:193], v[50:53]
	v_mfma_f32_16x16x32_bf16 v[42:45], v[162:165], v[198:201], v[42:45]
	v_mfma_f32_16x16x32_bf16 v[34:37], v[182:185], v[198:201], v[34:37]
	v_mfma_f32_16x16x32_bf16 v[26:29], v[162:165], v[206:209], v[26:29]
	v_mfma_f32_16x16x32_bf16 v[18:21], v[182:185], v[206:209], v[18:21]
	v_mfma_f32_16x16x32_bf16 v[10:13], v[162:165], v[214:217], v[10:13]
	v_mfma_f32_16x16x32_bf16 v[2:5], v[182:185], v[214:217], v[2:5]
	v_mfma_f32_16x16x32_bf16 v[58:61], v[166:169], v[194:197], v[58:61]
	v_mfma_f32_16x16x32_bf16 v[50:53], v[186:189], v[194:197], v[50:53]
	v_mfma_f32_16x16x32_bf16 v[42:45], v[166:169], v[202:205], v[42:45]
	v_mfma_f32_16x16x32_bf16 v[34:37], v[186:189], v[202:205], v[34:37]
	v_mfma_f32_16x16x32_bf16 v[26:29], v[166:169], v[210:213], v[26:29]
	v_mfma_f32_16x16x32_bf16 v[18:21], v[186:189], v[210:213], v[18:21]
	v_mfma_f32_16x16x32_bf16 v[10:13], v[166:169], v[218:221], v[10:13]
	v_mfma_f32_16x16x32_bf16 v[2:5], v[186:189], v[218:221], v[2:5]
	s_setprio 0
	s_barrier
	s_add_i32 s23, s23, 2
	s_add_u32 s24, s24, 0x100
	s_addc_u32 s25, s25, 0
	s_add_u32 s15, s15, 0x100
	s_addc_u32 s17, s17, 0
	s_cmp_gt_u32 s23, 29
	s_cbranch_scc0 .LBB0_1507
	s_and_b64 vcc, exec, s[12:13]
	s_cbranch_vccz .LBB0_1510
	s_barrier

; #define PG8_STAGE(bufoff, gbase, voff) do { _Pragma("unroll") for (int _i = 0; _i < 2; ++_i) \
;         __builtin_amdgcn_global_load_lds((const unsigned*)((const char*)(gbase) + (voff)[_i]), (PG8_LAS unsigned*)(lds + (bufoff) + ldsw + _i * 8192), 16, 0, 0); } while (0)
; #define PG8_LDA(dst, b, h) do { _Pragma("unroll") for (int m = 0; m < 4; ++m) _Pragma("unroll") for (int k = 0; k < 2; ++k) dst[m][k] = *(const PG8_LAS bf16x8*)(lds + PG8_SA(b, h) + aoff + m * 2048 + k * 1024); } while (0)
; #define PG8_LDB(dst, b, h) do { _Pragma("unroll") for (int n = 0; n < 2; ++n) _Pragma("unroll") for (int k = 0; k < 2; ++k) dst[n][k] = *(const PG8_LAS bf16x8*)(lds + PG8_SB(b, h) + boff + n * 2048 + k * 1024); } while (0)
; #define PG8_MMA(ai, bj, At, Bt) do { __builtin_amdgcn_s_setprio(1); _Pragma("unroll") for (int m = 0; m < 4; ++m) _Pragma("unroll") for (int n = 0; n < 2; ++n) _Pragma("unroll") for (int k = 0; k < 2; ++k) \
;         acc[ai][bj][m][n] = __builtin_amdgcn_mfma_f32_16x16x32_bf16(Bt[n][k], At[m][k], acc[ai][bj][m][n], 0, 0, 0); __builtin_amdgcn_s_setprio(0); } while (0)
; #define PG8_WAIT_V(n) asm volatile("s_waitcnt vmcnt(" #n ")" ::: "memory")
; #define PG8_WAIT_L(n) asm volatile("s_waitcnt lgkmcnt(" #n ")" ::: "memory")
; #define PG8_BAR __builtin_amdgcn_s_barrier()
; #define PG8_SCHED __builtin_amdgcn_sched_barrier(0)
; template <class Epi, class Sched, bool ALIGN_EPI = false, bool SP2 = false>
; __device__ __forceinline__ void gemm_phase(PG8_LAS unsigned char* lds, const Gemm g, const Sched& S, const Epi& E, int tid_in) {
;     ...
;         for (int t = 0; t < nt; t += 2) {
;             const bool last = (t == nt - 2);
;             const char* a1 = cA + (size_t)(t + 1) * kstep;
;             const char* a2 = last ? nA : cA + (size_t)(t + 2) * kstep; const char* b2 = last ? nB : cB + (size_t)(t + 2) * kstep;
;             const char* a3 = a2 + kstep; const char* b3 = b2 + kstep;
;             if (last && has_next) S.a_ready(nxt);
;             if constexpr (SP2) {
;             PG8_LDB(B0, 0, 0); PG8_LDB(B1, 0, 1); PG8_SCHED; PG8_LDA(At, 0, 0); PG8_STAGE(PG8_SA(1, 1), a1 + hstepA, voffA);
;             PG8_WAIT_V(8); PG8_WAIT_L(0); PG8_BAR; PG8_MMA(0, 0, At, B0); PG8_MMA(0, 1, At, B1); PG8_BAR; PG8_SCHED;
;             PG8_LDA(At, 0, 1); PG8_STAGE(PG8_SB(0, 0), b2, voffB); PG8_STAGE(PG8_SB(0, 1), b2 + hstep, voffB); PG8_STAGE(PG8_SA(0, 0), a2, voffA);
.LBB0_1577:
	v_add_u32_e32 v0, s4, v164
	ds_read_b128 v[130:133], v0
	ds_read_b128 v[142:145], v0 offset:1024
	ds_read_b128 v[146:149], v0 offset:2048
	ds_read_b128 v[150:153], v0 offset:3072
	v_add_u32_e32 v0, s5, v164
	ds_read_b128 v[154:157], v0
	ds_read_b128 v[158:161], v0 offset:1024
	ds_read_b128 v[166:169], v0 offset:2048
	ds_read_b128 v[182:185], v0 offset:3072
	s_add_i32 vcc_lo, s10, 2
	s_add_u32 s8, s6, 0x100
	s_addc_u32 s9, s7, 0
	s_cmp_eq_u32 s83, s10
	s_cselect_b32 s10, s82, s84
	s_cselect_b32 s37, s46, s9
	s_cselect_b32 s36, s47, s8
	s_cselect_b32 s11, s76, s85
	v_lshl_add_u64 v[218:219], s[6:7], 0, v[138:139]
	s_add_i32 m0, s38, 0xc000
	ds_read_b128 v[186:189], v165
	ds_read_b128 v[190:193], v165 offset:1024
	ds_read_b128 v[194:197], v165 offset:2048
	ds_read_b128 v[198:201], v165 offset:3072
	ds_read_b128 v[202:205], v165 offset:4096
	ds_read_b128 v[206:209], v165 offset:5120
	ds_read_b128 v[210:213], v165 offset:6144
	ds_read_b128 v[214:217], v165 offset:7168
	global_load_lds_dwordx4 v[218:219], off
	v_lshl_add_u64 v[218:219], s[6:7], 0, v[140:141]
	s_add_i32 m0, s38, 0xe000
	s_nop 0
	global_load_lds_dwordx4 v[218:219], off
	s_waitcnt vmcnt(8)
	s_waitcnt lgkmcnt(0)
	s_barrier
	s_setprio 1
	s_waitcnt lgkmcnt(0)
	v_mfma_f32_16x16x32_bf16 v[126:129], v[130:133], v[186:189], v[126:129]
	v_mfma_f32_16x16x32_bf16 v[122:125], v[146:149], v[186:189], v[122:125]
	v_mfma_f32_16x16x32_bf16 v[118:121], v[130:133], v[194:197], v[118:121]
	v_mfma_f32_16x16x32_bf16 v[114:117], v[146:149], v[194:197], v[114:117]
	v_mfma_f32_16x16x32_bf16 v[110:113], v[130:133], v[202:205], v[110:113]
	v_mfma_f32_16x16x32_bf16 v[106:109], v[146:149], v[202:205], v[106:109]
	v_mfma_f32_16x16x32_bf16 v[102:105], v[130:133], v[210:213], v[102:105]
	v_mfma_f32_16x16x32_bf16 v[98:101], v[146:149], v[210:213], v[98:101]
	v_mfma_f32_16x16x32_bf16 v[126:129], v[142:145], v[190:193], v[126:129]
	v_mfma_f32_16x16x32_bf16 v[122:125], v[150:153], v[190:193], v[122:125]
	v_mfma_f32_16x16x32_bf16 v[118:121], v[142:145], v[198:201], v[118:121]
	v_mfma_f32_16x16x32_bf16 v[114:117], v[150:153], v[198:201], v[114:117]
	v_mfma_f32_16x16x32_bf16 v[110:113], v[142:145], v[206:209], v[110:113]
	v_mfma_f32_16x16x32_bf16 v[106:109], v[150:153], v[206:209], v[106:109]
	v_mfma_f32_16x16x32_bf16 v[102:105], v[142:145], v[214:217], v[102:105]
	v_mfma_f32_16x16x32_bf16 v[98:101], v[150:153], v[214:217], v[98:101]
	s_setprio 0
	s_setprio 1
	v_mfma_f32_16x16x32_bf16 v[94:97], v[154:157], v[186:189], v[94:97]
	v_mfma_f32_16x16x32_bf16 v[90:93], v[166:169], v[186:189], v[90:93]
	v_mfma_f32_16x16x32_bf16 v[86:89], v[154:157], v[194:197], v[86:89]
	v_mfma_f32_16x16x32_bf16 v[82:85], v[166:169], v[194:197], v[82:85]
	v_mfma_f32_16x16x32_bf16 v[78:81], v[154:157], v[202:205], v[78:81]
	v_mfma_f32_16x16x32_bf16 v[74:77], v[166:169], v[202:205], v[74:77]
	v_mfma_f32_16x16x32_bf16 v[70:73], v[154:157], v[210:213], v[70:73]
	v_mfma_f32_16x16x32_bf16 v[66:69], v[166:169], v[210:213], v[66:69]
	v_mfma_f32_16x16x32_bf16 v[94:97], v[158:161], v[190:193], v[94:97]
	v_mfma_f32_16x16x32_bf16 v[90:93], v[182:185], v[190:193], v[90:93]
	v_mfma_f32_16x16x32_bf16 v[86:89], v[158:161], v[198:201], v[86:89]
	v_mfma_f32_16x16x32_bf16 v[82:85], v[182:185], v[198:201], v[82:85]
	v_mfma_f32_16x16x32_bf16 v[78:81], v[158:161], v[206:209], v[78:81]
	v_mfma_f32_16x16x32_bf16 v[74:77], v[182:185], v[206:209], v[74:77]
	v_mfma_f32_16x16x32_bf16 v[70:73], v[158:161], v[214:217], v[70:73]
	v_mfma_f32_16x16x32_bf16 v[66:69], v[182:185], v[214:217], v[66:69]
	s_setprio 0
	s_barrier
	s_add_i32 s6, s4, s33
	v_lshl_add_u64 v[218:219], s[10:11], 0, v[134:135]
	s_mov_b32 m0, s6
	ds_read_b128 v[186:189], v165 offset:16384
	ds_read_b128 v[190:193], v165 offset:17408
	ds_read_b128 v[194:197], v165 offset:18432
	ds_read_b128 v[198:201], v165 offset:19456
	ds_read_b128 v[202:205], v165 offset:20480
	ds_read_b128 v[206:209], v165 offset:21504
	ds_read_b128 v[210:213], v165 offset:22528
	ds_read_b128 v[214:217], v165 offset:23552
	global_load_lds_dwordx4 v[218:219], off
	s_add_i32 m0, s6, 0x2000
	s_add_u32 s6, s10, 0x160000
	v_lshl_add_u64 v[220:221], s[10:11], 0, v[136:137]
	s_addc_u32 s7, s11, 0
	s_add_i32 s64, s5, s33
	global_load_lds_dwordx4 v[220:221], off
	v_lshl_add_u64 v[222:223], s[6:7], 0, v[134:135]
	s_mov_b32 m0, s64
	v_lshl_add_u64 v[224:225], s[36:37], 0, v[136:137]
	global_load_lds_dwordx4 v[222:223], off
	v_lshl_add_u64 v[222:223], s[6:7], 0, v[136:137]
	s_add_i32 m0, s64, 0x2000
	s_nop 0
	global_load_lds_dwordx4 v[222:223], off
	s_waitcnt vmcnt(6)
	s_waitcnt lgkmcnt(0)
	s_barrier
; #define PG8_STAGE(bufoff, gbase, voff) do { _Pragma("unroll") for (int _i = 0; _i < 2; ++_i) \
;         __builtin_amdgcn_global_load_lds((const unsigned*)((const char*)(gbase) + (voff)[_i]), (PG8_LAS unsigned*)(lds + (bufoff) + ldsw + _i * 8192), 16, 0, 0); } while (0)
; #define PG8_LDA(dst, b, h) do { _Pragma("unroll") for (int m = 0; m < 4; ++m) _Pragma("unroll") for (int k = 0; k < 2; ++k) dst[m][k] = *(const PG8_LAS bf16x8*)(lds + PG8_SA(b, h) + aoff + m * 2048 + k * 1024); } while (0)
; #define PG8_LDB(dst, b, h) do { _Pragma("unroll") for (int n = 0; n < 2; ++n) _Pragma("unroll") for (int k = 0; k < 2; ++k) dst[n][k] = *(const PG8_LAS bf16x8*)(lds + PG8_SB(b, h) + boff + n * 2048 + k * 1024); } while (0)
; #define PG8_MMA(ai, bj, At, Bt) do { __builtin_amdgcn_s_setprio(1); _Pragma("unroll") for (int m = 0; m < 4; ++m) _Pragma("unroll") for (int n = 0; n < 2; ++n) _Pragma("unroll") for (int k = 0; k < 2; ++k) \
;         acc[ai][bj][m][n] = __builtin_amdgcn_mfma_f32_16x16x32_bf16(Bt[n][k], At[m][k], acc[ai][bj][m][n], 0, 0, 0); __builtin_amdgcn_s_setprio(0); } while (0)
; #define PG8_WAIT_V(n) asm volatile("s_waitcnt vmcnt(" #n ")" ::: "memory")
; #define PG8_WAIT_L(n) asm volatile("s_waitcnt lgkmcnt(" #n ")" ::: "memory")
; #define PG8_BAR __builtin_amdgcn_s_barrier()
; #define PG8_SCHED __builtin_amdgcn_sched_barrier(0)
; template <class Epi, class Sched, bool ALIGN_EPI = false, bool SP2 = false>
; __device__ __forceinline__ void gemm_phase(PG8_LAS unsigned char* lds, const Gemm g, const Sched& S, const Epi& E, int tid_in) {
;     ...
;             PG8_LDA(At, 0, 1); PG8_STAGE(PG8_SB(0, 0), b2, voffB); PG8_STAGE(PG8_SB(0, 1), b2 + hstep, voffB); PG8_STAGE(PG8_SA(0, 0), a2, voffA);
;             PG8_WAIT_V(8); PG8_WAIT_L(0); PG8_BAR; PG8_MMA(1, 0, At, B0); PG8_MMA(1, 1, At, B1); PG8_BAR; PG8_SCHED;
;             PG8_LDB(B0, 1, 0); PG8_LDB(B1, 1, 1); PG8_SCHED; PG8_LDA(At, 1, 0); PG8_STAGE(PG8_SA(0, 1), a2 + hstepA, voffA);
;             PG8_WAIT_V(8); PG8_WAIT_L(0); PG8_BAR; PG8_MMA(0, 0, At, B0); PG8_MMA(0, 1, At, B1); PG8_BAR; PG8_SCHED;
	s_setprio 1
	s_waitcnt lgkmcnt(0)
	v_mfma_f32_16x16x32_bf16 v[62:65], v[130:133], v[186:189], v[62:65]
	v_mfma_f32_16x16x32_bf16 v[58:61], v[146:149], v[186:189], v[58:61]
	v_mfma_f32_16x16x32_bf16 v[54:57], v[130:133], v[194:197], v[54:57]
	v_mfma_f32_16x16x32_bf16 v[50:53], v[146:149], v[194:197], v[50:53]
	v_mfma_f32_16x16x32_bf16 v[46:49], v[130:133], v[202:205], v[46:49]
	v_mfma_f32_16x16x32_bf16 v[42:45], v[146:149], v[202:205], v[42:45]
	v_mfma_f32_16x16x32_bf16 v[38:41], v[130:133], v[210:213], v[38:41]
	v_mfma_f32_16x16x32_bf16 v[34:37], v[146:149], v[210:213], v[34:37]
	v_mfma_f32_16x16x32_bf16 v[62:65], v[142:145], v[190:193], v[62:65]
	v_mfma_f32_16x16x32_bf16 v[58:61], v[150:153], v[190:193], v[58:61]
	v_mfma_f32_16x16x32_bf16 v[54:57], v[142:145], v[198:201], v[54:57]
	v_mfma_f32_16x16x32_bf16 v[50:53], v[150:153], v[198:201], v[50:53]
	v_mfma_f32_16x16x32_bf16 v[46:49], v[142:145], v[206:209], v[46:49]
	v_mfma_f32_16x16x32_bf16 v[42:45], v[150:153], v[206:209], v[42:45]
	v_mfma_f32_16x16x32_bf16 v[38:41], v[142:145], v[214:217], v[38:41]
	v_mfma_f32_16x16x32_bf16 v[34:37], v[150:153], v[214:217], v[34:37]
	s_setprio 0
	s_setprio 1
	v_mfma_f32_16x16x32_bf16 v[30:33], v[154:157], v[186:189], v[30:33]
	v_mfma_f32_16x16x32_bf16 v[26:29], v[166:169], v[186:189], v[26:29]
	v_mfma_f32_16x16x32_bf16 v[22:25], v[154:157], v[194:197], v[22:25]
	v_mfma_f32_16x16x32_bf16 v[18:21], v[166:169], v[194:197], v[18:21]
	v_mfma_f32_16x16x32_bf16 v[14:17], v[154:157], v[202:205], v[14:17]
	v_mfma_f32_16x16x32_bf16 v[10:13], v[166:169], v[202:205], v[10:13]
	v_mfma_f32_16x16x32_bf16 v[6:9], v[154:157], v[210:213], v[6:9]
	v_mfma_f32_16x16x32_bf16 v[2:5], v[166:169], v[210:213], v[2:5]
	v_mfma_f32_16x16x32_bf16 v[30:33], v[158:161], v[190:193], v[30:33]
	v_mfma_f32_16x16x32_bf16 v[26:29], v[182:185], v[190:193], v[26:29]
	v_mfma_f32_16x16x32_bf16 v[22:25], v[158:161], v[198:201], v[22:25]
	v_mfma_f32_16x16x32_bf16 v[18:21], v[182:185], v[198:201], v[18:21]
	v_mfma_f32_16x16x32_bf16 v[14:17], v[158:161], v[206:209], v[14:17]
	v_mfma_f32_16x16x32_bf16 v[10:13], v[182:185], v[206:209], v[10:13]
	v_mfma_f32_16x16x32_bf16 v[6:9], v[158:161], v[214:217], v[6:9]
	v_mfma_f32_16x16x32_bf16 v[2:5], v[182:185], v[214:217], v[2:5]
	s_setprio 0
	s_barrier
	v_lshl_add_u64 v[222:223], s[36:37], 0, v[134:135]
	s_mov_b32 m0, s38
	s_nop 0
	global_load_lds_dwordx4 v[222:223], off
	s_mov_b32 m0, s39
	s_nop 0
	global_load_lds_dwordx4 v[224:225], off
	v_add_u32_e32 v0, s63, v164
	ds_read_b128 v[130:133], v0
	ds_read_b128 v[142:145], v0 offset:1024
	ds_read_b128 v[146:149], v0 offset:2048
	ds_read_b128 v[150:153], v0 offset:3072
	v_add_u32_e32 v0, s55, v164
	ds_read_b128 v[154:157], v0
	ds_read_b128 v[158:161], v0 offset:1024
	ds_read_b128 v[166:169], v0 offset:2048
	ds_read_b128 v[182:185], v0 offset:3072
	s_add_u32 s6, s36, 0x160000
	s_addc_u32 s7, s37, 0
	s_mov_b32 m0, s40
	v_lshl_add_u64 v[226:227], s[6:7], 0, v[134:135]
	ds_read_b128 v[186:189], v165 offset:32768
	ds_read_b128 v[190:193], v165 offset:33792
	ds_read_b128 v[194:197], v165 offset:34816
	ds_read_b128 v[198:201], v165 offset:35840
	ds_read_b128 v[202:205], v165 offset:36864
	ds_read_b128 v[206:209], v165 offset:37888
	ds_read_b128 v[210:213], v165 offset:38912
	ds_read_b128 v[214:217], v165 offset:39936
	global_load_lds_dwordx4 v[226:227], off
	v_lshl_add_u64 v[226:227], s[6:7], 0, v[136:137]
	s_mov_b32 m0, s41
	s_nop 0
	global_load_lds_dwordx4 v[226:227], off
	s_waitcnt vmcnt(8)
	s_waitcnt lgkmcnt(0)
	s_barrier
	s_setprio 1
	s_waitcnt lgkmcnt(0)
	v_mfma_f32_16x16x32_bf16 v[126:129], v[130:133], v[186:189], v[126:129]
	v_mfma_f32_16x16x32_bf16 v[122:125], v[146:149], v[186:189], v[122:125]
	v_mfma_f32_16x16x32_bf16 v[118:121], v[130:133], v[194:197], v[118:121]
	v_mfma_f32_16x16x32_bf16 v[114:117], v[146:149], v[194:197], v[114:117]
	v_mfma_f32_16x16x32_bf16 v[110:113], v[130:133], v[202:205], v[110:113]
	v_mfma_f32_16x16x32_bf16 v[106:109], v[146:149], v[202:205], v[106:109]
	v_mfma_f32_16x16x32_bf16 v[102:105], v[130:133], v[210:213], v[102:105]
	v_mfma_f32_16x16x32_bf16 v[98:101], v[146:149], v[210:213], v[98:101]
	v_mfma_f32_16x16x32_bf16 v[126:129], v[142:145], v[190:193], v[126:129]
	v_mfma_f32_16x16x32_bf16 v[122:125], v[150:153], v[190:193], v[122:125]
	v_mfma_f32_16x16x32_bf16 v[118:121], v[142:145], v[198:201], v[118:121]
	v_mfma_f32_16x16x32_bf16 v[114:117], v[150:153], v[198:201], v[114:117]
	v_mfma_f32_16x16x32_bf16 v[110:113], v[142:145], v[206:209], v[110:113]
	v_mfma_f32_16x16x32_bf16 v[106:109], v[150:153], v[206:209], v[106:109]
	v_mfma_f32_16x16x32_bf16 v[102:105], v[142:145], v[214:217], v[102:105]
	v_mfma_f32_16x16x32_bf16 v[98:101], v[150:153], v[214:217], v[98:101]
	s_setprio 0
	s_setprio 1
	v_mfma_f32_16x16x32_bf16 v[94:97], v[154:157], v[186:189], v[94:97]
	v_mfma_f32_16x16x32_bf16 v[90:93], v[166:169], v[186:189], v[90:93]
	v_mfma_f32_16x16x32_bf16 v[86:89], v[154:157], v[194:197], v[86:89]
	v_mfma_f32_16x16x32_bf16 v[82:85], v[166:169], v[194:197], v[82:85]
	v_mfma_f32_16x16x32_bf16 v[78:81], v[154:157], v[202:205], v[78:81]
	v_mfma_f32_16x16x32_bf16 v[74:77], v[166:169], v[202:205], v[74:77]
	v_mfma_f32_16x16x32_bf16 v[70:73], v[154:157], v[210:213], v[70:73]
	v_mfma_f32_16x16x32_bf16 v[66:69], v[166:169], v[210:213], v[66:69]
	v_mfma_f32_16x16x32_bf16 v[94:97], v[158:161], v[190:193], v[94:97]
	v_mfma_f32_16x16x32_bf16 v[90:93], v[182:185], v[190:193], v[90:93]
	v_mfma_f32_16x16x32_bf16 v[86:89], v[158:161], v[198:201], v[86:89]
	v_mfma_f32_16x16x32_bf16 v[82:85], v[182:185], v[198:201], v[82:85]
	v_mfma_f32_16x16x32_bf16 v[78:81], v[158:161], v[206:209], v[78:81]
	v_mfma_f32_16x16x32_bf16 v[74:77], v[182:185], v[206:209], v[74:77]
	v_mfma_f32_16x16x32_bf16 v[70:73], v[158:161], v[214:217], v[70:73]
	v_mfma_f32_16x16x32_bf16 v[66:69], v[182:185], v[214:217], v[66:69]
	s_setprio 0
	s_barrier
; #define PG8_STAGE(bufoff, gbase, voff) do { _Pragma("unroll") for (int _i = 0; _i < 2; ++_i) \
;         __builtin_amdgcn_global_load_lds((const unsigned*)((const char*)(gbase) + (voff)[_i]), (PG8_LAS unsigned*)(lds + (bufoff) + ldsw + _i * 8192), 16, 0, 0); } while (0)
; #define PG8_LDA(dst, b, h) do { _Pragma("unroll") for (int m = 0; m < 4; ++m) _Pragma("unroll") for (int k = 0; k < 2; ++k) dst[m][k] = *(const PG8_LAS bf16x8*)(lds + PG8_SA(b, h) + aoff + m * 2048 + k * 1024); } while (0)
; #define PG8_MMA(ai, bj, At, Bt) do { __builtin_amdgcn_s_setprio(1); _Pragma("unroll") for (int m = 0; m < 4; ++m) _Pragma("unroll") for (int n = 0; n < 2; ++n) _Pragma("unroll") for (int k = 0; k < 2; ++k) \
;         acc[ai][bj][m][n] = __builtin_amdgcn_mfma_f32_16x16x32_bf16(Bt[n][k], At[m][k], acc[ai][bj][m][n], 0, 0, 0); __builtin_amdgcn_s_setprio(0); } while (0)
; #define PG8_WAIT_V(n) asm volatile("s_waitcnt vmcnt(" #n ")" ::: "memory")
; #define PG8_WAIT_L(n) asm volatile("s_waitcnt lgkmcnt(" #n ")" ::: "memory")
; #define PG8_BAR __builtin_amdgcn_s_barrier()
; #define PG8_SCHED __builtin_amdgcn_sched_barrier(0)
; template <class Epi, class Sched, bool ALIGN_EPI = false, bool SP2 = false>
; __device__ __forceinline__ void gemm_phase(PG8_LAS unsigned char* lds, const Gemm g, const Sched& S, const Epi& E, int tid_in) {
;     ...
;         for (int t = 0; t < nt; t += 2) {
;             const bool last = (t == nt - 2);
;             const char* a1 = cA + (size_t)(t + 1) * kstep;
;             const char* a2 = last ? nA : cA + (size_t)(t + 2) * kstep; const char* b2 = last ? nB : cB + (size_t)(t + 2) * kstep;
;     ...
;             PG8_LDA(At, 1, 1); PG8_STAGE(PG8_SB(1, 0), b3, voffB); PG8_STAGE(PG8_SB(1, 1), b3 + hstep, voffB); PG8_STAGE(PG8_SA(1, 0), a3, voffA);
;             PG8_WAIT_V(8); PG8_WAIT_L(0); PG8_BAR; PG8_MMA(1, 0, At, B0); PG8_MMA(1, 1, At, B1); PG8_BAR; PG8_SCHED;
	s_add_i32 s6, s63, s33
	v_lshl_add_u64 v[218:219], v[218:219], 0, s[90:91]
	s_mov_b32 m0, s6
	ds_read_b128 v[186:189], v165 offset:49152
	ds_read_b128 v[190:193], v165 offset:50176
	ds_read_b128 v[194:197], v165 offset:51200
	ds_read_b128 v[198:201], v165 offset:52224
	ds_read_b128 v[202:205], v165 offset:53248
	ds_read_b128 v[206:209], v165 offset:54272
	ds_read_b128 v[210:213], v165 offset:55296
	ds_read_b128 v[214:217], v165 offset:56320
	global_load_lds_dwordx4 v[218:219], off
	s_add_i32 m0, s6, 0x2000
	s_add_u32 s6, s10, 0x160080
	v_lshl_add_u64 v[218:219], v[220:221], 0, s[90:91]
	s_addc_u32 s7, s11, 0
	s_add_i32 s10, s55, s33
	global_load_lds_dwordx4 v[218:219], off
	v_lshl_add_u64 v[218:219], s[6:7], 0, v[134:135]
	s_mov_b32 m0, s10
	s_nop 0
	global_load_lds_dwordx4 v[218:219], off
	v_lshl_add_u64 v[218:219], s[6:7], 0, v[136:137]
	s_add_i32 m0, s10, 0x2000
	s_nop 0
	global_load_lds_dwordx4 v[218:219], off
	v_lshl_add_u64 v[218:219], v[222:223], 0, s[90:91]
	s_mov_b32 m0, s49
	s_nop 0
	global_load_lds_dwordx4 v[218:219], off
	v_lshl_add_u64 v[218:219], v[224:225], 0, s[90:91]
	s_mov_b32 m0, s66
	s_nop 0
	global_load_lds_dwordx4 v[218:219], off
	s_waitcnt vmcnt(8)
	s_waitcnt lgkmcnt(0)
	s_barrier
	s_setprio 1
	s_waitcnt lgkmcnt(0)
	v_mfma_f32_16x16x32_bf16 v[62:65], v[130:133], v[186:189], v[62:65]
	v_mfma_f32_16x16x32_bf16 v[58:61], v[146:149], v[186:189], v[58:61]
	v_mfma_f32_16x16x32_bf16 v[54:57], v[130:133], v[194:197], v[54:57]
	v_mfma_f32_16x16x32_bf16 v[50:53], v[146:149], v[194:197], v[50:53]
	v_mfma_f32_16x16x32_bf16 v[46:49], v[130:133], v[202:205], v[46:49]
	v_mfma_f32_16x16x32_bf16 v[42:45], v[146:149], v[202:205], v[42:45]
	v_mfma_f32_16x16x32_bf16 v[38:41], v[130:133], v[210:213], v[38:41]
	v_mfma_f32_16x16x32_bf16 v[34:37], v[146:149], v[210:213], v[34:37]
	v_mfma_f32_16x16x32_bf16 v[62:65], v[142:145], v[190:193], v[62:65]
	v_mfma_f32_16x16x32_bf16 v[58:61], v[150:153], v[190:193], v[58:61]
	v_mfma_f32_16x16x32_bf16 v[54:57], v[142:145], v[198:201], v[54:57]
	v_mfma_f32_16x16x32_bf16 v[50:53], v[150:153], v[198:201], v[50:53]
	v_mfma_f32_16x16x32_bf16 v[46:49], v[142:145], v[206:209], v[46:49]
	v_mfma_f32_16x16x32_bf16 v[42:45], v[150:153], v[206:209], v[42:45]
	v_mfma_f32_16x16x32_bf16 v[38:41], v[142:145], v[214:217], v[38:41]
	v_mfma_f32_16x16x32_bf16 v[34:37], v[150:153], v[214:217], v[34:37]
	s_setprio 0
	s_setprio 1
	v_mfma_f32_16x16x32_bf16 v[30:33], v[154:157], v[186:189], v[30:33]
	v_mfma_f32_16x16x32_bf16 v[26:29], v[166:169], v[186:189], v[26:29]
	v_mfma_f32_16x16x32_bf16 v[22:25], v[154:157], v[194:197], v[22:25]
	v_mfma_f32_16x16x32_bf16 v[18:21], v[166:169], v[194:197], v[18:21]
	v_mfma_f32_16x16x32_bf16 v[14:17], v[154:157], v[202:205], v[14:17]
	v_mfma_f32_16x16x32_bf16 v[10:13], v[166:169], v[202:205], v[10:13]
	v_mfma_f32_16x16x32_bf16 v[6:9], v[154:157], v[210:213], v[6:9]
	v_mfma_f32_16x16x32_bf16 v[2:5], v[166:169], v[210:213], v[2:5]
	v_mfma_f32_16x16x32_bf16 v[30:33], v[158:161], v[190:193], v[30:33]
	v_mfma_f32_16x16x32_bf16 v[26:29], v[182:185], v[190:193], v[26:29]
	v_mfma_f32_16x16x32_bf16 v[22:25], v[158:161], v[198:201], v[22:25]
	v_mfma_f32_16x16x32_bf16 v[18:21], v[182:185], v[198:201], v[18:21]
	v_mfma_f32_16x16x32_bf16 v[14:17], v[158:161], v[206:209], v[14:17]
	v_mfma_f32_16x16x32_bf16 v[10:13], v[182:185], v[206:209], v[10:13]
	v_mfma_f32_16x16x32_bf16 v[6:9], v[158:161], v[214:217], v[6:9]
	v_mfma_f32_16x16x32_bf16 v[2:5], v[182:185], v[214:217], v[2:5]
	s_setprio 0
	s_barrier
	s_add_u32 s84, s84, 0x100
	s_addc_u32 s85, s85, 0
	s_cmp_ge_u32 vcc_lo, s79
	s_mov_b64 s[6:7], s[8:9]
	s_mov_b32 s10, vcc_lo
	s_cbranch_scc0 .LBB0_1577
	s_and_b64 vcc, exec, s[24:25]
	s_cbranch_vccz .LBB0_1580
	s_barrier
